# combined: de-serialized EpiX1/EpiDown epilogues + software-pipelined phase 5 (reversed unit order) + K-loop segment head/tail trims
# speedup vs baseline: 1.0096x; 1.0096x over previous
; #define PG8_STAGE(bufoff, gbase, voff) do { _Pragma("unroll") for (int _i = 0; _i < 2; ++_i) \
;         __builtin_amdgcn_global_load_lds((const unsigned*)((const char*)(gbase) + (voff)[_i]), (PG8_LAS unsigned*)(lds + (bufoff) + ldsw + _i * 8192), 16, 0, 0); } while (0)
; #define PG8_LDA(dst, b, h) do { _Pragma("unroll") for (int m = 0; m < 4; ++m) _Pragma("unroll") for (int k = 0; k < 2; ++k) dst[m][k] = *(const PG8_LAS bf16x8*)(lds + PG8_SA(b, h) + aoff + m * 2048 + k * 1024); } while (0)
; #define PG8_LDB(dst, b, h) do { _Pragma("unroll") for (int n = 0; n < 2; ++n) _Pragma("unroll") for (int k = 0; k < 2; ++k) dst[n][k] = *(const PG8_LAS bf16x8*)(lds + PG8_SB(b, h) + boff + n * 2048 + k * 1024); } while (0)
; #define PG8_WAIT_V(n) asm volatile("s_waitcnt vmcnt(" #n ")" ::: "memory")
; #define PG8_WAIT_L(n) asm volatile("s_waitcnt lgkmcnt(" #n ")" ::: "memory")
; #define PG8_BAR __builtin_amdgcn_s_barrier()
; #define PG8_SCHED __builtin_amdgcn_sched_barrier(0)
; template <class Epi, class Sched, bool ALIGN_EPI = false, bool SP2 = false, bool F8 = false>
; __device__ __forceinline__ void gemm_phase(PG8_LAS unsigned char* lds, const int K, const Sched& S, const Epi& E, const int wave) {
;     ...
;             PG8_LDB(B0, 0, 0); PG8_LDB(B1, 0, 1); PG8_SCHED; PG8_LDA(At, 0, 0); PG8_STAGE(PG8_SA(1, 1), a1 + hstep, voffA);
;             PG8_WAIT_V(8); PG8_WAIT_L(0); PG8_BAR; PG8_MMA(0, 0, At, B0); PG8_MMA(0, 1, At, B1); PG8_BAR; PG8_SCHED;
;             PG8_LDA(At, 0, 1); PG8_STAGE(PG8_SB(0, 0), b2, voffB); PG8_STAGE(PG8_SB(0, 1), b2 + hstep, voffB); PG8_STAGE(PG8_SA(0, 0), a2, voffA);
;             PG8_WAIT_V(8); PG8_WAIT_L(0); PG8_BAR; PG8_MMA(1, 0, At, B0); PG8_MMA(1, 1, At, B1); PG8_BAR; PG8_SCHED;
.LBB0_186:
	s_add_u32 s6, s14, s0
	s_addc_u32 s7, s15, s1
	s_add_u32 s64, s6, 0xffffff80
	s_addc_u32 s65, s7, -1
	s_add_u32 s76, s36, s0
	s_addc_u32 s77, s37, s1
	s_cmp_eq_u32 vcc_lo, 60
	s_cselect_b32 s94, s85, s6
	s_cselect_b32 s95, s83, s7
	s_cselect_b32 s7, s96, s77
	s_cselect_b32 s6, s97, s76
	s_add_u32 s78, s94, 0x80
	s_addc_u32 s79, s95, 0
	s_add_u32 s76, s6, 0x80
	s_addc_u32 s77, s7, 0
	v_add_u32_e32 v140, s47, v245
	v_add_u32_e32 v156, s41, v245
	ds_read_b128 v[128:131], v140
	ds_read_b128 v[132:135], v140 offset:1024
	ds_read_b128 v[136:139], v140 offset:2048
	ds_read_b128 v[140:143], v140 offset:3072
	ds_read_b128 v[144:147], v156
	ds_read_b128 v[148:151], v156 offset:1024
	ds_read_b128 v[152:155], v156 offset:2048
	ds_read_b128 v[156:159], v156 offset:3072
	s_add_u32 s64, s64, 0x100000
	s_addc_u32 s65, s65, 0
	v_lshl_add_u64 v[240:241], s[64:65], 0, v[192:193]
	s_add_i32 m0, s13, 0xc000
	ds_read_b128 v[160:163], v248
	ds_read_b128 v[164:167], v248 offset:1024
	ds_read_b128 v[168:171], v248 offset:2048
	ds_read_b128 v[172:175], v248 offset:3072
	ds_read_b128 v[176:179], v248 offset:4096
	ds_read_b128 v[180:183], v248 offset:5120
	ds_read_b128 v[184:187], v248 offset:6144
	ds_read_b128 v[188:191], v248 offset:7168
	global_load_lds_dwordx4 v[240:241], off
	v_lshl_add_u64 v[240:241], s[64:65], 0, v[196:197]
	s_add_i32 m0, s13, 0xe000
	s_nop 0
	global_load_lds_dwordx4 v[240:241], off
	s_waitcnt vmcnt(8)
	s_waitcnt lgkmcnt(0)
	s_setprio 1
	s_barrier
	v_mfma_f32_16x16x32_bf16 v[124:127], v[128:131], v[160:163], v[124:127]
	v_mfma_f32_16x16x32_bf16 v[120:123], v[136:139], v[160:163], v[120:123]
	v_mfma_f32_16x16x32_bf16 v[116:119], v[128:131], v[168:171], v[116:119]
	v_mfma_f32_16x16x32_bf16 v[112:115], v[136:139], v[168:171], v[112:115]
	v_mfma_f32_16x16x32_bf16 v[108:111], v[128:131], v[176:179], v[108:111]
	v_mfma_f32_16x16x32_bf16 v[104:107], v[136:139], v[176:179], v[104:107]
	v_mfma_f32_16x16x32_bf16 v[100:103], v[128:131], v[184:187], v[100:103]
	v_mfma_f32_16x16x32_bf16 v[96:99], v[136:139], v[184:187], v[96:99]
	v_mfma_f32_16x16x32_bf16 v[124:127], v[132:135], v[164:167], v[124:127]
	v_mfma_f32_16x16x32_bf16 v[120:123], v[140:143], v[164:167], v[120:123]
	v_mfma_f32_16x16x32_bf16 v[116:119], v[132:135], v[172:175], v[116:119]
	v_mfma_f32_16x16x32_bf16 v[112:115], v[140:143], v[172:175], v[112:115]
	v_mfma_f32_16x16x32_bf16 v[108:111], v[132:135], v[180:183], v[108:111]
	v_mfma_f32_16x16x32_bf16 v[104:107], v[140:143], v[180:183], v[104:107]
	v_mfma_f32_16x16x32_bf16 v[100:103], v[132:135], v[188:191], v[100:103]
	v_mfma_f32_16x16x32_bf16 v[96:99], v[140:143], v[188:191], v[96:99]
	v_mfma_f32_16x16x32_bf16 v[92:95], v[144:147], v[160:163], v[92:95]
	v_mfma_f32_16x16x32_bf16 v[88:91], v[152:155], v[160:163], v[88:91]
	v_mfma_f32_16x16x32_bf16 v[84:87], v[144:147], v[168:171], v[84:87]
	v_mfma_f32_16x16x32_bf16 v[80:83], v[152:155], v[168:171], v[80:83]
	v_mfma_f32_16x16x32_bf16 v[76:79], v[144:147], v[176:179], v[76:79]
	v_mfma_f32_16x16x32_bf16 v[72:75], v[152:155], v[176:179], v[72:75]
	v_mfma_f32_16x16x32_bf16 v[68:71], v[144:147], v[184:187], v[68:71]
	v_mfma_f32_16x16x32_bf16 v[64:67], v[152:155], v[184:187], v[64:67]
	v_mfma_f32_16x16x32_bf16 v[92:95], v[148:151], v[164:167], v[92:95]
	v_mfma_f32_16x16x32_bf16 v[88:91], v[156:159], v[164:167], v[88:91]
	v_mfma_f32_16x16x32_bf16 v[84:87], v[148:151], v[172:175], v[84:87]
	v_mfma_f32_16x16x32_bf16 v[80:83], v[156:159], v[172:175], v[80:83]
	v_mfma_f32_16x16x32_bf16 v[76:79], v[148:151], v[180:183], v[76:79]
	v_mfma_f32_16x16x32_bf16 v[72:75], v[156:159], v[180:183], v[72:75]
	v_mfma_f32_16x16x32_bf16 v[68:71], v[148:151], v[188:191], v[68:71]
	v_mfma_f32_16x16x32_bf16 v[64:67], v[156:159], v[188:191], v[64:67]
	s_barrier
	s_setprio 0
	s_add_i32 s64, s47, s74
	v_lshl_add_u64 v[240:241], s[6:7], 0, v[194:195]
	s_mov_b32 m0, s64
	ds_read_b128 v[160:163], v248 offset:16384
	ds_read_b128 v[164:167], v248 offset:17408
	ds_read_b128 v[168:171], v248 offset:18432
	ds_read_b128 v[172:175], v248 offset:19456
	ds_read_b128 v[176:179], v248 offset:20480
	ds_read_b128 v[180:183], v248 offset:21504
	ds_read_b128 v[184:187], v248 offset:22528
	ds_read_b128 v[188:191], v248 offset:23552
	global_load_lds_dwordx4 v[240:241], off
	s_add_i32 m0, s64, 0x2000
	v_lshl_add_u64 v[240:241], s[6:7], 0, v[198:199]
	s_add_u32 s6, s6, 0x100000
	s_addc_u32 s7, s7, 0
	s_add_i32 s64, s41, s74
	global_load_lds_dwordx4 v[240:241], off
	v_lshl_add_u64 v[240:241], s[6:7], 0, v[194:195]
	s_mov_b32 m0, s64
	s_nop 0
	global_load_lds_dwordx4 v[240:241], off
	v_lshl_add_u64 v[240:241], s[6:7], 0, v[198:199]
	s_add_i32 m0, s64, 0x2000
	s_nop 0
	global_load_lds_dwordx4 v[240:241], off
	v_lshl_add_u64 v[240:241], s[94:95], 0, v[192:193]
	s_mov_b32 m0, s13
	s_nop 0
	global_load_lds_dwordx4 v[240:241], off
	v_lshl_add_u64 v[240:241], s[94:95], 0, v[196:197]
	s_mov_b32 m0, s51
	s_nop 0
	global_load_lds_dwordx4 v[240:241], off
	s_waitcnt vmcnt(8)
	s_waitcnt lgkmcnt(0)
	s_setprio 1
	s_barrier
; #define PG8_STAGE(bufoff, gbase, voff) do { _Pragma("unroll") for (int _i = 0; _i < 2; ++_i) \
;         __builtin_amdgcn_global_load_lds((const unsigned*)((const char*)(gbase) + (voff)[_i]), (PG8_LAS unsigned*)(lds + (bufoff) + ldsw + _i * 8192), 16, 0, 0); } while (0)
; #define PG8_LDA(dst, b, h) do { _Pragma("unroll") for (int m = 0; m < 4; ++m) _Pragma("unroll") for (int k = 0; k < 2; ++k) dst[m][k] = *(const PG8_LAS bf16x8*)(lds + PG8_SA(b, h) + aoff + m * 2048 + k * 1024); } while (0)
; #define PG8_LDB(dst, b, h) do { _Pragma("unroll") for (int n = 0; n < 2; ++n) _Pragma("unroll") for (int k = 0; k < 2; ++k) dst[n][k] = *(const PG8_LAS bf16x8*)(lds + PG8_SB(b, h) + boff + n * 2048 + k * 1024); } while (0)
; #define PG8_WAIT_V(n) asm volatile("s_waitcnt vmcnt(" #n ")" ::: "memory")
; #define PG8_WAIT_L(n) asm volatile("s_waitcnt lgkmcnt(" #n ")" ::: "memory")
; #define PG8_BAR __builtin_amdgcn_s_barrier()
; #define PG8_SCHED __builtin_amdgcn_sched_barrier(0)
; template <class Epi, class Sched, bool ALIGN_EPI = false, bool SP2 = false, bool F8 = false>
; __device__ __forceinline__ void gemm_phase(PG8_LAS unsigned char* lds, const int K, const Sched& S, const Epi& E, const int wave) {
;     ...
;             PG8_WAIT_V(8); PG8_WAIT_L(0); PG8_BAR; PG8_MMA(1, 0, At, B0); PG8_MMA(1, 1, At, B1); PG8_BAR; PG8_SCHED;
;             PG8_LDB(B0, 1, 0); PG8_LDB(B1, 1, 1); PG8_SCHED; PG8_LDA(At, 1, 0); PG8_STAGE(PG8_SA(0, 1), a2 + hstep, voffA);
;             PG8_WAIT_V(8); PG8_WAIT_L(0); PG8_BAR; PG8_MMA(0, 0, At, B0); PG8_MMA(0, 1, At, B1); PG8_BAR; PG8_SCHED;
	v_mfma_f32_16x16x32_bf16 v[60:63], v[128:131], v[160:163], v[60:63]
	v_mfma_f32_16x16x32_bf16 v[56:59], v[136:139], v[160:163], v[56:59]
	v_mfma_f32_16x16x32_bf16 v[52:55], v[128:131], v[168:171], v[52:55]
	v_mfma_f32_16x16x32_bf16 v[48:51], v[136:139], v[168:171], v[48:51]
	v_mfma_f32_16x16x32_bf16 v[44:47], v[128:131], v[176:179], v[44:47]
	v_mfma_f32_16x16x32_bf16 v[40:43], v[136:139], v[176:179], v[40:43]
	v_mfma_f32_16x16x32_bf16 v[36:39], v[128:131], v[184:187], v[36:39]
	v_mfma_f32_16x16x32_bf16 v[32:35], v[136:139], v[184:187], v[32:35]
	v_mfma_f32_16x16x32_bf16 v[60:63], v[132:135], v[164:167], v[60:63]
	v_mfma_f32_16x16x32_bf16 v[56:59], v[140:143], v[164:167], v[56:59]
	v_mfma_f32_16x16x32_bf16 v[52:55], v[132:135], v[172:175], v[52:55]
	v_mfma_f32_16x16x32_bf16 v[48:51], v[140:143], v[172:175], v[48:51]
	v_mfma_f32_16x16x32_bf16 v[44:47], v[132:135], v[180:183], v[44:47]
	v_mfma_f32_16x16x32_bf16 v[40:43], v[140:143], v[180:183], v[40:43]
	v_mfma_f32_16x16x32_bf16 v[36:39], v[132:135], v[188:191], v[36:39]
	v_mfma_f32_16x16x32_bf16 v[32:35], v[140:143], v[188:191], v[32:35]
	v_mfma_f32_16x16x32_bf16 v[28:31], v[144:147], v[160:163], v[28:31]
	v_mfma_f32_16x16x32_bf16 v[24:27], v[152:155], v[160:163], v[24:27]
	v_mfma_f32_16x16x32_bf16 v[20:23], v[144:147], v[168:171], v[20:23]
	v_mfma_f32_16x16x32_bf16 v[16:19], v[152:155], v[168:171], v[16:19]
	v_mfma_f32_16x16x32_bf16 v[12:15], v[144:147], v[176:179], v[12:15]
	v_mfma_f32_16x16x32_bf16 v[8:11], v[152:155], v[176:179], v[8:11]
	v_mfma_f32_16x16x32_bf16 v[4:7], v[144:147], v[184:187], v[4:7]
	v_mfma_f32_16x16x32_bf16 v[0:3], v[152:155], v[184:187], v[0:3]
	v_mfma_f32_16x16x32_bf16 v[28:31], v[148:151], v[164:167], v[28:31]
	v_mfma_f32_16x16x32_bf16 v[24:27], v[156:159], v[164:167], v[24:27]
	v_mfma_f32_16x16x32_bf16 v[20:23], v[148:151], v[172:175], v[20:23]
	v_mfma_f32_16x16x32_bf16 v[16:19], v[156:159], v[172:175], v[16:19]
	v_mfma_f32_16x16x32_bf16 v[12:15], v[148:151], v[180:183], v[12:15]
	v_mfma_f32_16x16x32_bf16 v[8:11], v[156:159], v[180:183], v[8:11]
	v_mfma_f32_16x16x32_bf16 v[4:7], v[148:151], v[188:191], v[4:7]
	v_mfma_f32_16x16x32_bf16 v[0:3], v[156:159], v[188:191], v[0:3]
	s_barrier
	s_setprio 0
	s_add_i32 s64, 0, 0x18000
	s_add_i32 s65, 0, 0x1c000
	v_add_u32_e32 v140, s64, v245
	v_add_u32_e32 v156, s65, v245
	ds_read_b128 v[128:131], v140
	ds_read_b128 v[132:135], v140 offset:1024
	ds_read_b128 v[136:139], v140 offset:2048
	ds_read_b128 v[140:143], v140 offset:3072
	ds_read_b128 v[144:147], v156
	ds_read_b128 v[148:151], v156 offset:1024
	ds_read_b128 v[152:155], v156 offset:2048
	ds_read_b128 v[156:159], v156 offset:3072
	s_add_u32 s6, s94, 0x100000
	s_addc_u32 s7, s95, 0
	s_mov_b32 m0, s75
	v_lshl_add_u64 v[240:241], s[6:7], 0, v[192:193]
	ds_read_b128 v[160:163], v248 offset:32768
	ds_read_b128 v[164:167], v248 offset:33792
	ds_read_b128 v[168:171], v248 offset:34816
	ds_read_b128 v[172:175], v248 offset:35840
	ds_read_b128 v[176:179], v248 offset:36864
	ds_read_b128 v[180:183], v248 offset:37888
	ds_read_b128 v[184:187], v248 offset:38912
	ds_read_b128 v[188:191], v248 offset:39936
	global_load_lds_dwordx4 v[240:241], off
	v_lshl_add_u64 v[240:241], s[6:7], 0, v[196:197]
	s_mov_b32 m0, s48
	s_nop 0
	global_load_lds_dwordx4 v[240:241], off
	s_waitcnt vmcnt(8)
	s_waitcnt lgkmcnt(0)
	s_setprio 1
	s_barrier
	v_mfma_f32_16x16x32_bf16 v[124:127], v[128:131], v[160:163], v[124:127]
	v_mfma_f32_16x16x32_bf16 v[120:123], v[136:139], v[160:163], v[120:123]
	v_mfma_f32_16x16x32_bf16 v[116:119], v[128:131], v[168:171], v[116:119]
	v_mfma_f32_16x16x32_bf16 v[112:115], v[136:139], v[168:171], v[112:115]
	v_mfma_f32_16x16x32_bf16 v[108:111], v[128:131], v[176:179], v[108:111]
	v_mfma_f32_16x16x32_bf16 v[104:107], v[136:139], v[176:179], v[104:107]
	v_mfma_f32_16x16x32_bf16 v[100:103], v[128:131], v[184:187], v[100:103]
	v_mfma_f32_16x16x32_bf16 v[96:99], v[136:139], v[184:187], v[96:99]
	v_mfma_f32_16x16x32_bf16 v[124:127], v[132:135], v[164:167], v[124:127]
	v_mfma_f32_16x16x32_bf16 v[120:123], v[140:143], v[164:167], v[120:123]
	v_mfma_f32_16x16x32_bf16 v[116:119], v[132:135], v[172:175], v[116:119]
	v_mfma_f32_16x16x32_bf16 v[112:115], v[140:143], v[172:175], v[112:115]
	v_mfma_f32_16x16x32_bf16 v[108:111], v[132:135], v[180:183], v[108:111]
	v_mfma_f32_16x16x32_bf16 v[104:107], v[140:143], v[180:183], v[104:107]
	v_mfma_f32_16x16x32_bf16 v[100:103], v[132:135], v[188:191], v[100:103]
	v_mfma_f32_16x16x32_bf16 v[96:99], v[140:143], v[188:191], v[96:99]
	v_mfma_f32_16x16x32_bf16 v[92:95], v[144:147], v[160:163], v[92:95]
	v_mfma_f32_16x16x32_bf16 v[88:91], v[152:155], v[160:163], v[88:91]
	v_mfma_f32_16x16x32_bf16 v[84:87], v[144:147], v[168:171], v[84:87]
	v_mfma_f32_16x16x32_bf16 v[80:83], v[152:155], v[168:171], v[80:83]
	v_mfma_f32_16x16x32_bf16 v[76:79], v[144:147], v[176:179], v[76:79]
	v_mfma_f32_16x16x32_bf16 v[72:75], v[152:155], v[176:179], v[72:75]
	v_mfma_f32_16x16x32_bf16 v[68:71], v[144:147], v[184:187], v[68:71]
	v_mfma_f32_16x16x32_bf16 v[64:67], v[152:155], v[184:187], v[64:67]
	v_mfma_f32_16x16x32_bf16 v[92:95], v[148:151], v[164:167], v[92:95]
	v_mfma_f32_16x16x32_bf16 v[88:91], v[156:159], v[164:167], v[88:91]
	v_mfma_f32_16x16x32_bf16 v[84:87], v[148:151], v[172:175], v[84:87]
	v_mfma_f32_16x16x32_bf16 v[80:83], v[156:159], v[172:175], v[80:83]
	v_mfma_f32_16x16x32_bf16 v[76:79], v[148:151], v[180:183], v[76:79]
	v_mfma_f32_16x16x32_bf16 v[72:75], v[156:159], v[180:183], v[72:75]
	v_mfma_f32_16x16x32_bf16 v[68:71], v[148:151], v[188:191], v[68:71]
	v_mfma_f32_16x16x32_bf16 v[64:67], v[156:159], v[188:191], v[64:67]
	s_barrier
; #define PG8_STAGE(bufoff, gbase, voff) do { _Pragma("unroll") for (int _i = 0; _i < 2; ++_i) \
;         __builtin_amdgcn_global_load_lds((const unsigned*)((const char*)(gbase) + (voff)[_i]), (PG8_LAS unsigned*)(lds + (bufoff) + ldsw + _i * 8192), 16, 0, 0); } while (0)
; #define PG8_LDA(dst, b, h) do { _Pragma("unroll") for (int m = 0; m < 4; ++m) _Pragma("unroll") for (int k = 0; k < 2; ++k) dst[m][k] = *(const PG8_LAS bf16x8*)(lds + PG8_SA(b, h) + aoff + m * 2048 + k * 1024); } while (0)
; #define PG8_WAIT_V(n) asm volatile("s_waitcnt vmcnt(" #n ")" ::: "memory")
; #define PG8_WAIT_L(n) asm volatile("s_waitcnt lgkmcnt(" #n ")" ::: "memory")
; #define PG8_BAR __builtin_amdgcn_s_barrier()
; #define PG8_SCHED __builtin_amdgcn_sched_barrier(0)
; template <class Epi, class Sched, bool ALIGN_EPI = false, bool SP2 = false, bool F8 = false>
; __device__ __forceinline__ void gemm_phase(PG8_LAS unsigned char* lds, const int K, const Sched& S, const Epi& E, const int wave) {
;     ...
;         for (int t = 0; t < nt; t += 2) {
;     ...
;             PG8_WAIT_V(8); PG8_WAIT_L(0); PG8_BAR; PG8_MMA(0, 0, At, B0); PG8_MMA(0, 1, At, B1); PG8_BAR; PG8_SCHED;
;             PG8_LDA(At, 1, 1); PG8_STAGE(PG8_SB(1, 0), b3, voffB); PG8_STAGE(PG8_SB(1, 1), b3 + hstep, voffB); PG8_STAGE(PG8_SA(1, 0), a3, voffA);
;             PG8_WAIT_V(8); PG8_WAIT_L(0); PG8_BAR; PG8_MMA(1, 0, At, B0); PG8_MMA(1, 1, At, B1); PG8_BAR; PG8_SCHED;
	s_setprio 0
	s_add_i32 s6, s64, s74
	v_lshl_add_u64 v[240:241], s[76:77], 0, v[194:195]
	s_mov_b32 m0, s6
	ds_read_b128 v[160:163], v248 offset:49152
	ds_read_b128 v[164:167], v248 offset:50176
	ds_read_b128 v[168:171], v248 offset:51200
	ds_read_b128 v[172:175], v248 offset:52224
	ds_read_b128 v[176:179], v248 offset:53248
	ds_read_b128 v[180:183], v248 offset:54272
	ds_read_b128 v[184:187], v248 offset:55296
	ds_read_b128 v[188:191], v248 offset:56320
	global_load_lds_dwordx4 v[240:241], off
	s_add_i32 m0, s6, 0x2000
	s_add_u32 s6, s76, 0x100000
	v_lshl_add_u64 v[240:241], s[76:77], 0, v[198:199]
	s_addc_u32 s7, s77, 0
	s_add_i32 s64, s65, s74
	global_load_lds_dwordx4 v[240:241], off
	v_lshl_add_u64 v[240:241], s[6:7], 0, v[194:195]
	s_mov_b32 m0, s64
	s_nop 0
	global_load_lds_dwordx4 v[240:241], off
	v_lshl_add_u64 v[240:241], s[6:7], 0, v[198:199]
	s_add_i32 m0, s64, 0x2000
	s_nop 0
	global_load_lds_dwordx4 v[240:241], off
	v_lshl_add_u64 v[240:241], s[78:79], 0, v[192:193]
	s_mov_b32 m0, s43
	s_nop 0
	global_load_lds_dwordx4 v[240:241], off
	v_lshl_add_u64 v[240:241], s[78:79], 0, v[196:197]
	s_mov_b32 m0, s44
	s_nop 0
	global_load_lds_dwordx4 v[240:241], off
	s_waitcnt vmcnt(8)
	s_waitcnt lgkmcnt(0)
	s_setprio 1
	s_barrier
	v_mfma_f32_16x16x32_bf16 v[60:63], v[128:131], v[160:163], v[60:63]
	v_mfma_f32_16x16x32_bf16 v[56:59], v[136:139], v[160:163], v[56:59]
	v_mfma_f32_16x16x32_bf16 v[52:55], v[128:131], v[168:171], v[52:55]
	v_mfma_f32_16x16x32_bf16 v[48:51], v[136:139], v[168:171], v[48:51]
	v_mfma_f32_16x16x32_bf16 v[44:47], v[128:131], v[176:179], v[44:47]
	v_mfma_f32_16x16x32_bf16 v[40:43], v[136:139], v[176:179], v[40:43]
	v_mfma_f32_16x16x32_bf16 v[36:39], v[128:131], v[184:187], v[36:39]
	v_mfma_f32_16x16x32_bf16 v[32:35], v[136:139], v[184:187], v[32:35]
	v_mfma_f32_16x16x32_bf16 v[60:63], v[132:135], v[164:167], v[60:63]
	v_mfma_f32_16x16x32_bf16 v[56:59], v[140:143], v[164:167], v[56:59]
	v_mfma_f32_16x16x32_bf16 v[52:55], v[132:135], v[172:175], v[52:55]
	v_mfma_f32_16x16x32_bf16 v[48:51], v[140:143], v[172:175], v[48:51]
	v_mfma_f32_16x16x32_bf16 v[44:47], v[132:135], v[180:183], v[44:47]
	v_mfma_f32_16x16x32_bf16 v[40:43], v[140:143], v[180:183], v[40:43]
	v_mfma_f32_16x16x32_bf16 v[36:39], v[132:135], v[188:191], v[36:39]
	v_mfma_f32_16x16x32_bf16 v[32:35], v[140:143], v[188:191], v[32:35]
	v_mfma_f32_16x16x32_bf16 v[28:31], v[144:147], v[160:163], v[28:31]
	v_mfma_f32_16x16x32_bf16 v[24:27], v[152:155], v[160:163], v[24:27]
	v_mfma_f32_16x16x32_bf16 v[20:23], v[144:147], v[168:171], v[20:23]
	v_mfma_f32_16x16x32_bf16 v[16:19], v[152:155], v[168:171], v[16:19]
	v_mfma_f32_16x16x32_bf16 v[12:15], v[144:147], v[176:179], v[12:15]
	v_mfma_f32_16x16x32_bf16 v[8:11], v[152:155], v[176:179], v[8:11]
	v_mfma_f32_16x16x32_bf16 v[4:7], v[144:147], v[184:187], v[4:7]
	v_mfma_f32_16x16x32_bf16 v[0:3], v[152:155], v[184:187], v[0:3]
	v_mfma_f32_16x16x32_bf16 v[28:31], v[148:151], v[164:167], v[28:31]
	v_mfma_f32_16x16x32_bf16 v[24:27], v[156:159], v[164:167], v[24:27]
	v_mfma_f32_16x16x32_bf16 v[20:23], v[148:151], v[172:175], v[20:23]
	v_mfma_f32_16x16x32_bf16 v[16:19], v[156:159], v[172:175], v[16:19]
	v_mfma_f32_16x16x32_bf16 v[12:15], v[148:151], v[180:183], v[12:15]
	v_mfma_f32_16x16x32_bf16 v[8:11], v[156:159], v[180:183], v[8:11]
	v_mfma_f32_16x16x32_bf16 v[4:7], v[148:151], v[188:191], v[4:7]
	v_mfma_f32_16x16x32_bf16 v[0:3], v[156:159], v[188:191], v[0:3]
	s_barrier
	s_setprio 0
	s_add_i32 vcc_lo, vcc_lo, 2
	s_add_u32 s0, s0, 0x100
	s_addc_u32 s1, s1, 0
	s_cmp_gt_u32 vcc_lo, 61
	s_cbranch_scc0 .LBB0_186
	s_and_b64 vcc, exec, s[80:81]
	s_cbranch_vccz .LBB0_189
	s_barrier

; #define PG8_STAGE(bufoff, gbase, voff) do { _Pragma("unroll") for (int _i = 0; _i < 2; ++_i) \
;         __builtin_amdgcn_global_load_lds((const unsigned*)((const char*)(gbase) + (voff)[_i]), (PG8_LAS unsigned*)(lds + (bufoff) + ldsw + _i * 8192), 16, 0, 0); } while (0)
; #define PG8_LDA(dst, b, h) do { _Pragma("unroll") for (int m = 0; m < 4; ++m) _Pragma("unroll") for (int k = 0; k < 2; ++k) dst[m][k] = *(const PG8_LAS bf16x8*)(lds + PG8_SA(b, h) + aoff + m * 2048 + k * 1024); } while (0)
; #define PG8_LDB(dst, b, h) do { _Pragma("unroll") for (int n = 0; n < 2; ++n) _Pragma("unroll") for (int k = 0; k < 2; ++k) dst[n][k] = *(const PG8_LAS bf16x8*)(lds + PG8_SB(b, h) + boff + n * 2048 + k * 1024); } while (0)
; #define PG8_WAIT_V(n) asm volatile("s_waitcnt vmcnt(" #n ")" ::: "memory")
; #define PG8_WAIT_L(n) asm volatile("s_waitcnt lgkmcnt(" #n ")" ::: "memory")
; #define PG8_BAR __builtin_amdgcn_s_barrier()
; #define PG8_SCHED __builtin_amdgcn_sched_barrier(0)
; template <class Epi, class Sched, bool ALIGN_EPI = false, bool SP2 = false, bool F8 = false>
; __device__ __forceinline__ void gemm_phase(PG8_LAS unsigned char* lds, const int K, const Sched& S, const Epi& E, const int wave) {
;     ...
;             PG8_LDB(B0, 0, 0); PG8_LDB(B1, 0, 1); PG8_SCHED; PG8_LDA(At, 0, 0); PG8_STAGE(PG8_SA(1, 1), a1 + hstep, voffA);
;             PG8_WAIT_V(8); PG8_WAIT_L(0); PG8_BAR; PG8_MMA(0, 0, At, B0); PG8_MMA(0, 1, At, B1); PG8_BAR; PG8_SCHED;
;             PG8_LDA(At, 0, 1); PG8_STAGE(PG8_SB(0, 0), b2, voffB); PG8_STAGE(PG8_SB(0, 1), b2 + hstep, voffB); PG8_STAGE(PG8_SA(0, 0), a2, voffA);
;             PG8_WAIT_V(8); PG8_WAIT_L(0); PG8_BAR; PG8_MMA(1, 0, At, B0); PG8_MMA(1, 1, At, B1); PG8_BAR; PG8_SCHED;
;             PG8_LDB(B0, 1, 0); PG8_LDB(B1, 1, 1); PG8_SCHED; PG8_LDA(At, 1, 0); PG8_STAGE(PG8_SA(0, 1), a2 + hstep, voffA);
;             PG8_WAIT_V(8); PG8_WAIT_L(0); PG8_BAR; PG8_MMA(0, 0, At, B0); PG8_MMA(0, 1, At, B1); PG8_BAR; PG8_SCHED;
;             PG8_LDA(At, 1, 1); PG8_STAGE(PG8_SB(1, 0), b3, voffB); PG8_STAGE(PG8_SB(1, 1), b3 + hstep, voffB); PG8_STAGE(PG8_SA(1, 0), a3, voffA);
;             PG8_WAIT_V(8); PG8_WAIT_L(0); PG8_BAR; PG8_MMA(1, 0, At, B0); PG8_MMA(1, 1, At, B1); PG8_BAR; PG8_SCHED;
.LBB0_248:
	s_add_u32 s6, s10, s94
	s_addc_u32 s7, s11, s95
	s_add_u32 s36, s6, 0xffffff80
	s_addc_u32 s37, s7, -1
	s_add_u32 s78, s12, s94
	s_addc_u32 s79, s13, s95
	s_cmp_eq_u32 s38, 28
	s_cselect_b32 s76, s90, s6
	s_cselect_b32 s77, s91, s7
	s_cselect_b32 s7, s93, s79
	s_cselect_b32 s6, s92, s78
	s_add_u32 s96, s76, 0x80
	s_addc_u32 s97, s77, 0
	s_add_u32 s78, s6, 0x80
	s_addc_u32 s79, s7, 0
	v_add_u32_e32 v128, s49, v163
	ds_read_b128 v[140:143], v128
	ds_read_b128 v[144:147], v128 offset:1024
	ds_read_b128 v[148:151], v128 offset:2048
	ds_read_b128 v[152:155], v128 offset:3072
	v_add_u32_e32 v128, s50, v163
	ds_read_b128 v[168:171], v128
	ds_read_b128 v[172:175], v128 offset:1024
	ds_read_b128 v[176:179], v128 offset:2048
	ds_read_b128 v[180:183], v128 offset:3072
	s_add_u32 s36, s36, 0x100000
	s_addc_u32 s37, s37, 0
	v_lshl_add_u64 v[128:129], s[36:37], 0, v[134:135]
	s_add_i32 m0, s42, 0xc000
	ds_read_b128 v[184:187], v165
	ds_read_b128 v[188:191], v165 offset:1024
	ds_read_b128 v[192:195], v165 offset:2048
	ds_read_b128 v[196:199], v165 offset:3072
	ds_read_b128 v[200:203], v165 offset:4096
	ds_read_b128 v[204:207], v165 offset:5120
	ds_read_b128 v[208:211], v165 offset:6144
	ds_read_b128 v[212:215], v165 offset:7168
	global_load_lds_dwordx4 v[128:129], off
	v_lshl_add_u64 v[128:129], s[36:37], 0, v[160:161]
	s_add_i32 m0, s42, 0xe000
	s_nop 0
	global_load_lds_dwordx4 v[128:129], off
	s_waitcnt vmcnt(8)
	s_waitcnt lgkmcnt(0)
	s_setprio 1
	s_barrier
	v_mfma_scale_f32_16x16x128_f8f6f4 v[124:127], v[140:147], v[184:191], v[124:127], v166, v166 op_sel_hi:[0,0,0]
	v_mfma_scale_f32_16x16x128_f8f6f4 v[120:123], v[148:155], v[184:191], v[120:123], v166, v166 op_sel_hi:[0,0,0]
	v_mfma_scale_f32_16x16x128_f8f6f4 v[116:119], v[140:147], v[192:199], v[116:119], v166, v166 op_sel_hi:[0,0,0]
	v_mfma_scale_f32_16x16x128_f8f6f4 v[112:115], v[148:155], v[192:199], v[112:115], v166, v166 op_sel_hi:[0,0,0]
	v_mfma_scale_f32_16x16x128_f8f6f4 v[108:111], v[140:147], v[200:207], v[108:111], v166, v166 op_sel_hi:[0,0,0]
	v_mfma_scale_f32_16x16x128_f8f6f4 v[104:107], v[148:155], v[200:207], v[104:107], v166, v166 op_sel_hi:[0,0,0]
	v_mfma_scale_f32_16x16x128_f8f6f4 v[100:103], v[140:147], v[208:215], v[100:103], v166, v166 op_sel_hi:[0,0,0]
	v_mfma_scale_f32_16x16x128_f8f6f4 v[96:99], v[148:155], v[208:215], v[96:99], v166, v166 op_sel_hi:[0,0,0]
	v_mfma_scale_f32_16x16x128_f8f6f4 v[156:159], v[168:175], v[184:191], v[92:95], v166, v166 op_sel_hi:[0,0,0]
	v_mfma_scale_f32_16x16x128_f8f6f4 v[184:187], v[176:183], v[184:191], v[88:91], v166, v166 op_sel_hi:[0,0,0]
	v_mfma_scale_f32_16x16x128_f8f6f4 v[188:191], v[168:175], v[192:199], v[84:87], v166, v166 op_sel_hi:[0,0,0]
	v_mfma_scale_f32_16x16x128_f8f6f4 v[192:195], v[176:183], v[192:199], v[80:83], v166, v166 op_sel_hi:[0,0,0]
	v_mfma_scale_f32_16x16x128_f8f6f4 v[196:199], v[168:175], v[200:207], v[76:79], v166, v166 op_sel_hi:[0,0,0]
	v_mfma_scale_f32_16x16x128_f8f6f4 v[200:203], v[176:183], v[200:207], v[72:75], v166, v166 op_sel_hi:[0,0,0]
	v_mfma_scale_f32_16x16x128_f8f6f4 v[204:207], v[168:175], v[208:215], v[68:71], v166, v166 op_sel_hi:[0,0,0]
	v_mfma_scale_f32_16x16x128_f8f6f4 v[208:211], v[176:183], v[208:215], v[64:67], v166, v166 op_sel_hi:[0,0,0]
	s_barrier
	s_setprio 0
	s_add_i32 s36, s49, s74
	v_lshl_add_u64 v[128:129], s[6:7], 0, v[132:133]
	s_mov_b32 m0, s36
	s_nop 1
	ds_read_b128 v[64:67], v165 offset:16384
	ds_read_b128 v[68:71], v165 offset:17408
	ds_read_b128 v[72:75], v165 offset:18432
	ds_read_b128 v[76:79], v165 offset:19456
	ds_read_b128 v[80:83], v165 offset:20480
	ds_read_b128 v[84:87], v165 offset:21504
	ds_read_b128 v[88:91], v165 offset:22528
	ds_read_b128 v[92:95], v165 offset:23552
	global_load_lds_dwordx4 v[128:129], off
	s_add_i32 m0, s36, 0x2000
	v_lshl_add_u64 v[128:129], s[6:7], 0, v[252:253]
	s_add_u32 s6, s6, 0x100000
	s_addc_u32 s7, s7, 0
	s_add_i32 s36, s50, s74
	global_load_lds_dwordx4 v[128:129], off
	v_lshl_add_u64 v[128:129], s[6:7], 0, v[132:133]
	s_mov_b32 m0, s36
	s_nop 0
	global_load_lds_dwordx4 v[128:129], off
	v_lshl_add_u64 v[128:129], s[6:7], 0, v[252:253]
	s_add_i32 m0, s36, 0x2000
	s_nop 0
	global_load_lds_dwordx4 v[128:129], off
	v_lshl_add_u64 v[128:129], s[76:77], 0, v[134:135]
	s_mov_b32 m0, s42
	s_nop 0
	global_load_lds_dwordx4 v[128:129], off
	v_lshl_add_u64 v[128:129], s[76:77], 0, v[160:161]
	s_mov_b32 m0, s43
	s_nop 0
	global_load_lds_dwordx4 v[128:129], off
	s_waitcnt vmcnt(8)
	s_waitcnt lgkmcnt(0)
	s_setprio 1
	s_barrier
	v_mfma_scale_f32_16x16x128_f8f6f4 v[60:63], v[140:147], v[64:71], v[60:63], v166, v166 op_sel_hi:[0,0,0]
	v_mfma_scale_f32_16x16x128_f8f6f4 v[56:59], v[148:155], v[64:71], v[56:59], v166, v166 op_sel_hi:[0,0,0]
	v_mfma_scale_f32_16x16x128_f8f6f4 v[52:55], v[140:147], v[72:79], v[52:55], v166, v166 op_sel_hi:[0,0,0]
	v_mfma_scale_f32_16x16x128_f8f6f4 v[48:51], v[148:155], v[72:79], v[48:51], v166, v166 op_sel_hi:[0,0,0]
	v_mfma_scale_f32_16x16x128_f8f6f4 v[212:215], v[140:147], v[80:87], v[44:47], v166, v166 op_sel_hi:[0,0,0]
	v_mfma_scale_f32_16x16x128_f8f6f4 v[216:219], v[148:155], v[80:87], v[40:43], v166, v166 op_sel_hi:[0,0,0]
	v_mfma_scale_f32_16x16x128_f8f6f4 v[220:223], v[140:147], v[88:95], v[36:39], v166, v166 op_sel_hi:[0,0,0]
	v_mfma_scale_f32_16x16x128_f8f6f4 v[224:227], v[148:155], v[88:95], v[32:35], v166, v166 op_sel_hi:[0,0,0]
	v_mfma_scale_f32_16x16x128_f8f6f4 v[228:231], v[168:175], v[64:71], v[28:31], v166, v166 op_sel_hi:[0,0,0]
	v_mfma_scale_f32_16x16x128_f8f6f4 v[236:239], v[176:183], v[64:71], v[24:27], v166, v166 op_sel_hi:[0,0,0]
	v_mfma_scale_f32_16x16x128_f8f6f4 v[244:247], v[168:175], v[72:79], v[20:23], v166, v166 op_sel_hi:[0,0,0]
	v_mfma_scale_f32_16x16x128_f8f6f4 v[248:251], v[176:183], v[72:79], v[16:19], v166, v166 op_sel_hi:[0,0,0]
	v_mfma_scale_f32_16x16x128_f8f6f4 v[232:235], v[168:175], v[80:87], v[12:15], v166, v166 op_sel_hi:[0,0,0]
	v_mfma_scale_f32_16x16x128_f8f6f4 v[240:243], v[176:183], v[80:87], v[8:11], v166, v166 op_sel_hi:[0,0,0]
	v_mfma_scale_f32_16x16x128_f8f6f4 v[136:139], v[168:175], v[88:95], v[4:7], v166, v166 op_sel_hi:[0,0,0]
	v_mfma_scale_f32_16x16x128_f8f6f4 v[128:131], v[176:183], v[88:95], v[0:3], v166, v166 op_sel_hi:[0,0,0]
	s_barrier
; #define PG8_STAGE(bufoff, gbase, voff) do { _Pragma("unroll") for (int _i = 0; _i < 2; ++_i) \
;         __builtin_amdgcn_global_load_lds((const unsigned*)((const char*)(gbase) + (voff)[_i]), (PG8_LAS unsigned*)(lds + (bufoff) + ldsw + _i * 8192), 16, 0, 0); } while (0)
; #define PG8_LDA(dst, b, h) do { _Pragma("unroll") for (int m = 0; m < 4; ++m) _Pragma("unroll") for (int k = 0; k < 2; ++k) dst[m][k] = *(const PG8_LAS bf16x8*)(lds + PG8_SA(b, h) + aoff + m * 2048 + k * 1024); } while (0)
; #define PG8_LDB(dst, b, h) do { _Pragma("unroll") for (int n = 0; n < 2; ++n) _Pragma("unroll") for (int k = 0; k < 2; ++k) dst[n][k] = *(const PG8_LAS bf16x8*)(lds + PG8_SB(b, h) + boff + n * 2048 + k * 1024); } while (0)
; #define PG8_WAIT_V(n) asm volatile("s_waitcnt vmcnt(" #n ")" ::: "memory")
; #define PG8_WAIT_L(n) asm volatile("s_waitcnt lgkmcnt(" #n ")" ::: "memory")
; #define PG8_BAR __builtin_amdgcn_s_barrier()
; #define PG8_SCHED __builtin_amdgcn_sched_barrier(0)
; template <class Epi, class Sched, bool ALIGN_EPI = false, bool SP2 = false, bool F8 = false>
; __device__ __forceinline__ void gemm_phase(PG8_LAS unsigned char* lds, const int K, const Sched& S, const Epi& E, const int wave) {
;     ...
;             PG8_LDB(B0, 0, 0); PG8_LDB(B1, 0, 1); PG8_SCHED; PG8_LDA(At, 0, 0); PG8_STAGE(PG8_SA(1, 1), a1 + hstep, voffA);
;             PG8_WAIT_V(8); PG8_WAIT_L(0); PG8_BAR; PG8_MMA(0, 0, At, B0); PG8_MMA(0, 1, At, B1); PG8_BAR; PG8_SCHED;
;             PG8_LDA(At, 0, 1); PG8_STAGE(PG8_SB(0, 0), b2, voffB); PG8_STAGE(PG8_SB(0, 1), b2 + hstep, voffB); PG8_STAGE(PG8_SA(0, 0), a2, voffA);
;             PG8_WAIT_V(8); PG8_WAIT_L(0); PG8_BAR; PG8_MMA(1, 0, At, B0); PG8_MMA(1, 1, At, B1); PG8_BAR; PG8_SCHED;
;             PG8_LDB(B0, 1, 0); PG8_LDB(B1, 1, 1); PG8_SCHED; PG8_LDA(At, 1, 0); PG8_STAGE(PG8_SA(0, 1), a2 + hstep, voffA);
;             PG8_WAIT_V(8); PG8_WAIT_L(0); PG8_BAR; PG8_MMA(0, 0, At, B0); PG8_MMA(0, 1, At, B1); PG8_BAR; PG8_SCHED;
;             PG8_LDA(At, 1, 1); PG8_STAGE(PG8_SB(1, 0), b3, voffB); PG8_STAGE(PG8_SB(1, 1), b3 + hstep, voffB); PG8_STAGE(PG8_SA(1, 0), a3, voffA);
;             PG8_WAIT_V(8); PG8_WAIT_L(0); PG8_BAR; PG8_MMA(1, 0, At, B0); PG8_MMA(1, 1, At, B1); PG8_BAR; PG8_SCHED;
	s_setprio 0
	s_add_i32 s36, 0, 0x18000
	s_add_i32 s37, 0, 0x1c000
	v_add_u32_e32 v12, s36, v163
	v_add_u32_e32 v16, s37, v163
	s_nop 0
	ds_read_b128 v[0:3], v12
	ds_read_b128 v[4:7], v12 offset:1024
	ds_read_b128 v[8:11], v12 offset:2048
	ds_read_b128 v[12:15], v12 offset:3072
	ds_read_b128 v[140:143], v16
	ds_read_b128 v[144:147], v16 offset:1024
	ds_read_b128 v[148:151], v16 offset:2048
	ds_read_b128 v[152:155], v16 offset:3072
	s_add_u32 s6, s76, 0x100000
	s_addc_u32 s7, s77, 0
	s_mov_b32 m0, s44
	v_lshl_add_u64 v[64:65], s[6:7], 0, v[134:135]
	ds_read_b128 v[16:19], v165 offset:32768
	ds_read_b128 v[20:23], v165 offset:33792
	ds_read_b128 v[24:27], v165 offset:34816
	ds_read_b128 v[28:31], v165 offset:35840
	ds_read_b128 v[32:35], v165 offset:36864
	ds_read_b128 v[36:39], v165 offset:37888
	ds_read_b128 v[40:43], v165 offset:38912
	ds_read_b128 v[44:47], v165 offset:39936
	global_load_lds_dwordx4 v[64:65], off
	v_lshl_add_u64 v[64:65], s[6:7], 0, v[160:161]
	s_mov_b32 m0, s45
	s_nop 0
	global_load_lds_dwordx4 v[64:65], off
	s_waitcnt vmcnt(8)
	s_waitcnt lgkmcnt(0)
	s_setprio 1
	s_barrier
	v_mfma_scale_f32_16x16x128_f8f6f4 v[124:127], v[0:7], v[16:23], v[124:127], v166, v166 op_sel_hi:[0,0,0]
	v_mfma_scale_f32_16x16x128_f8f6f4 v[120:123], v[8:15], v[16:23], v[120:123], v166, v166 op_sel_hi:[0,0,0]
	v_mfma_scale_f32_16x16x128_f8f6f4 v[116:119], v[0:7], v[24:31], v[116:119], v166, v166 op_sel_hi:[0,0,0]
	v_mfma_scale_f32_16x16x128_f8f6f4 v[112:115], v[8:15], v[24:31], v[112:115], v166, v166 op_sel_hi:[0,0,0]
	v_mfma_scale_f32_16x16x128_f8f6f4 v[108:111], v[0:7], v[32:39], v[108:111], v166, v166 op_sel_hi:[0,0,0]
	v_mfma_scale_f32_16x16x128_f8f6f4 v[104:107], v[8:15], v[32:39], v[104:107], v166, v166 op_sel_hi:[0,0,0]
	v_mfma_scale_f32_16x16x128_f8f6f4 v[100:103], v[0:7], v[40:47], v[100:103], v166, v166 op_sel_hi:[0,0,0]
	v_mfma_scale_f32_16x16x128_f8f6f4 v[96:99], v[8:15], v[40:47], v[96:99], v166, v166 op_sel_hi:[0,0,0]
	v_mfma_scale_f32_16x16x128_f8f6f4 v[92:95], v[140:147], v[16:23], v[156:159], v166, v166 op_sel_hi:[0,0,0]
	v_mfma_scale_f32_16x16x128_f8f6f4 v[88:91], v[148:155], v[16:23], v[184:187], v166, v166 op_sel_hi:[0,0,0]
	v_mfma_scale_f32_16x16x128_f8f6f4 v[84:87], v[140:147], v[24:31], v[188:191], v166, v166 op_sel_hi:[0,0,0]
	v_mfma_scale_f32_16x16x128_f8f6f4 v[80:83], v[148:155], v[24:31], v[192:195], v166, v166 op_sel_hi:[0,0,0]
	v_mfma_scale_f32_16x16x128_f8f6f4 v[76:79], v[140:147], v[32:39], v[196:199], v166, v166 op_sel_hi:[0,0,0]
	v_mfma_scale_f32_16x16x128_f8f6f4 v[72:75], v[148:155], v[32:39], v[200:203], v166, v166 op_sel_hi:[0,0,0]
	v_mfma_scale_f32_16x16x128_f8f6f4 v[68:71], v[140:147], v[40:47], v[204:207], v166, v166 op_sel_hi:[0,0,0]
	v_mfma_scale_f32_16x16x128_f8f6f4 v[64:67], v[148:155], v[40:47], v[208:211], v166, v166 op_sel_hi:[0,0,0]
	s_barrier
	s_setprio 0
	s_add_i32 s6, s36, s74
	v_lshl_add_u64 v[24:25], s[78:79], 0, v[132:133]
	s_mov_b32 m0, s6
	ds_read_b128 v[16:19], v165 offset:49152
	ds_read_b128 v[20:23], v165 offset:50176
	ds_read_b128 v[168:171], v165 offset:51200
	ds_read_b128 v[172:175], v165 offset:52224
	ds_read_b128 v[176:179], v165 offset:53248
	ds_read_b128 v[180:183], v165 offset:54272
	ds_read_b128 v[184:187], v165 offset:55296
	ds_read_b128 v[188:191], v165 offset:56320
	global_load_lds_dwordx4 v[24:25], off
	s_add_i32 m0, s6, 0x2000
	s_add_u32 s6, s78, 0x100000
	v_lshl_add_u64 v[24:25], s[78:79], 0, v[252:253]
	s_addc_u32 s7, s79, 0
	s_add_i32 s36, s37, s74
	global_load_lds_dwordx4 v[24:25], off
	v_lshl_add_u64 v[24:25], s[6:7], 0, v[132:133]
	s_mov_b32 m0, s36
	s_nop 0
	global_load_lds_dwordx4 v[24:25], off
	v_lshl_add_u64 v[24:25], s[6:7], 0, v[252:253]
	s_add_i32 m0, s36, 0x2000
	s_nop 0
	global_load_lds_dwordx4 v[24:25], off
	v_lshl_add_u64 v[24:25], s[96:97], 0, v[134:135]
	s_mov_b32 m0, s46
	s_nop 0
	global_load_lds_dwordx4 v[24:25], off
	v_lshl_add_u64 v[24:25], s[96:97], 0, v[160:161]
	s_mov_b32 m0, s47
	s_nop 0
	global_load_lds_dwordx4 v[24:25], off
	s_waitcnt vmcnt(8)
	s_waitcnt lgkmcnt(0)
	s_setprio 1
	s_barrier
	v_mfma_scale_f32_16x16x128_f8f6f4 v[60:63], v[0:7], v[16:23], v[60:63], v166, v166 op_sel_hi:[0,0,0]
	v_mfma_scale_f32_16x16x128_f8f6f4 v[56:59], v[8:15], v[16:23], v[56:59], v166, v166 op_sel_hi:[0,0,0]
	v_mfma_scale_f32_16x16x128_f8f6f4 v[52:55], v[0:7], v[168:175], v[52:55], v166, v166 op_sel_hi:[0,0,0]
	v_mfma_scale_f32_16x16x128_f8f6f4 v[48:51], v[8:15], v[168:175], v[48:51], v166, v166 op_sel_hi:[0,0,0]
	v_mfma_scale_f32_16x16x128_f8f6f4 v[44:47], v[0:7], v[176:183], v[212:215], v166, v166 op_sel_hi:[0,0,0]
	v_mfma_scale_f32_16x16x128_f8f6f4 v[40:43], v[8:15], v[176:183], v[216:219], v166, v166 op_sel_hi:[0,0,0]
	v_mfma_scale_f32_16x16x128_f8f6f4 v[36:39], v[0:7], v[184:191], v[220:223], v166, v166 op_sel_hi:[0,0,0]
	v_mfma_scale_f32_16x16x128_f8f6f4 v[32:35], v[8:15], v[184:191], v[224:227], v166, v166 op_sel_hi:[0,0,0]
	v_mfma_scale_f32_16x16x128_f8f6f4 v[28:31], v[140:147], v[16:23], v[228:231], v166, v166 op_sel_hi:[0,0,0]
	v_mfma_scale_f32_16x16x128_f8f6f4 v[24:27], v[148:155], v[16:23], v[236:239], v166, v166 op_sel_hi:[0,0,0]
	v_mfma_scale_f32_16x16x128_f8f6f4 v[20:23], v[140:147], v[168:175], v[244:247], v166, v166 op_sel_hi:[0,0,0]
	v_mfma_scale_f32_16x16x128_f8f6f4 v[16:19], v[148:155], v[168:175], v[248:251], v166, v166 op_sel_hi:[0,0,0]
	v_mfma_scale_f32_16x16x128_f8f6f4 v[12:15], v[140:147], v[176:183], v[232:235], v166, v166 op_sel_hi:[0,0,0]
	v_mfma_scale_f32_16x16x128_f8f6f4 v[8:11], v[148:155], v[176:183], v[240:243], v166, v166 op_sel_hi:[0,0,0]
	v_mfma_scale_f32_16x16x128_f8f6f4 v[4:7], v[140:147], v[184:191], v[136:139], v166, v166 op_sel_hi:[0,0,0]
	v_mfma_scale_f32_16x16x128_f8f6f4 v[0:3], v[148:155], v[184:191], v[128:131], v166, v166 op_sel_hi:[0,0,0]
	s_barrier
	s_setprio 0
	s_add_i32 s38, s38, 2
	s_add_u32 s94, s94, 0x100
	s_addc_u32 s95, s95, 0
	s_cmp_gt_u32 s38, 29
	s_cbranch_scc0 .LBB0_248
	s_and_b64 vcc, exec, s[60:61]
	s_cbranch_vccz .LBB0_251
	s_barrier

; __device__ __forceinline__ int tid_of_(int wave) { return wave * 64 + lane_id_(); }
; __device__ __forceinline__ void ph_g3(Frame& F) {
;     int tid_ = tid_of_(F.wave); asm volatile("" : "+v"(tid_)); const int tid = tid_, lane = tid & 63, fr = lane & 15, fq = lane >> 4, w = F.wave;
;     constexpr int PP = 144;
;     LAS unsigned char* P_s = F.lds; LAS float* red = (LAS float*)(F.lds + 64 * PP);
;     const unsigned zrow = (unsigned)(fr * ZS_LD + 8 * fq) * 2u;
;     const unsigned l16 = (unsigned)lane * 16u;
;     for (int unit = F.vcu; unit < NCHK * NH; unit += F.G) {
;         const int ci = unit >> 2, h = unit & 3;
;         const unsigned char* zc = F.ws + WS_ZS + (size_t)ci * 64 * ZS_LD * 2;
;         const unsigned char* qb = zc + (ZQ + h * DK) * 2; const unsigned char* kb = zc + (ZK + h * DK) * 2;
;         __syncthreads();
;         {
;             const int a = w >> 1; f32x4 pc[2] = {(f32x4){0.f, 0.f, 0.f, 0.f}, (f32x4){0.f, 0.f, 0.f, 0.f}};
; #pragma unroll
;             for (int ks = 0; ks < 8; ++ks) { const bf16x8 fqn = ldfrag(qb + (size_t)(16 * a) * ZS_LD * 2 + ks * 64, zrow);
; #pragma unroll
;                 for (int c2 = 0; c2 < 2; ++c2) { const bf16x8 fkn = ldfrag(kb + (size_t)(16 * (2 * (w & 1) + c2)) * ZS_LD * 2 + ks * 64, zrow);
;                     pc[c2] = __builtin_amdgcn_mfma_f32_16x16x32_bf16(fkn, fqn, pc[c2], 0, 0, 0); } }
; #pragma unroll
;             for (int c2 = 0; c2 < 2; ++c2) { const int t = 16 * a + fr, s0 = 16 * (2 * (w & 1) + c2) + 4 * fq; float pv[4];
; #pragma unroll
;                 for (int i = 0; i < 4; ++i) pv[i] = (s0 + i <= t) ? pc[c2][i] : 0.f;
;                 v2u o; o.x = pk2(pv[0], pv[1]); o.y = pk2(pv[2], pv[3]); *(LAS v2u*)(P_s + t * PP + s0 * 2) = o; }
;         }
;         __syncthreads();
;         f32x4 acc[4][4];
; #pragma unroll
;         for (int n = 0; n < 4; ++n)
; #pragma unroll
;             for (int a = 0; a < 4; ++a) acc[n][a] = (f32x4){0.f, 0.f, 0.f, 0.f};
;         const unsigned char* sb = (const unsigned char*)slot_ptr(F, ci, h) + (size_t)(4 * w) * 8 * 1024;
;         {
;             bf16x8 fs[4][8];
; #pragma unroll
;             for (int n = 0; n < 4; ++n)
; #pragma unroll
;                 for (int ks = 0; ks < 8; ++ks) fs[n][ks] = ldfrag(sb + (n * 8 + ks) * 1024, l16);
; #pragma unroll
;             for (int ks = 0; ks < 8; ++ks) { bf16x8 fqn[4];
; #pragma unroll
.LBB0_651:
	v_readlane_b32 s4, v255, 37
	s_cmp_lt_i32 s4, 6
	s_cselect_b64 s[36:37], -1, 0
	s_and_b64 s[0:1], s[36:37], s[0:1]
	s_andn2_b64 vcc, exec, s[0:1]
	v_readlane_b32 s5, v255, 38
	s_cbranch_vccnz .LBB0_670
	v_readlane_b32 s6, v255, 2
	v_readlane_b32 s8, v255, 41
	v_mbcnt_hi_u32_b32 v243, -1, v254
	s_cmpk_gt_i32 s6, 0x47f
	s_cbranch_scc1 .LBB0_670
	v_and_b32_e32 v244, 15, v243
	v_lshrrev_b32_e32 v245, 4, v243
	v_lshlrev_b32_e32 v241, 4, v243
	v_lshlrev_b32_e32 v240, 14, v244
	v_lshl_add_u32 v240, v245, 4, v240
	s_lshr_b32 s26, s8, 1
	s_and_b32 s27, s8, 1
	s_lshl_b32 s9, s26, 18
	s_lshl_b32 s10, s27, 19
	s_mul_i32 s11, s26, 0x900
	s_lshl_b32 s30, s27, 6
	s_add_u32 s11, s11, s30
	s_lshl_b32 s26, s26, 4
	s_lshl_b32 s27, s27, 5
	s_sub_i32 s26, s26, s27
	v_lshlrev_b32_e32 v242, 2, v245
	v_sub_u32_e32 v242, v244, v242
	v_add_u32_e32 v242, s26, v242
	v_readlane_b32 s28, v255, 9
	v_readlane_b32 s29, v255, 10
	s_lshl_b32 s30, s8, 8
	s_add_u32 s28, s28, s30
	s_addc_u32 s29, s29, 0
	v_lshlrev_b32_e32 v246, 4, v245
	global_load_dwordx4 v[224:227], v246, s[28:29]
	global_load_dwordx4 v[228:231], v246, s[28:29] offset:64
	global_load_dwordx4 v[232:235], v246, s[28:29] offset:128
	global_load_dwordx4 v[236:239], v246, s[28:29] offset:192
	s_sub_u32 s28, 0x47f, s6
	s_lshr_b32 s26, s28, 2
	s_and_b32 s27, s28, 3
	s_lshl_b32 s30, s26, 20
	s_lshl_b32 s31, s27, 9
	s_add_u32 s30, s30, s31
	s_add_u32 s30, s30, 0x10400000
	s_add_u32 s12, s34, s30
	s_addc_u32 s13, s35, 0
	s_lshl_b32 s30, s28, 18
	s_mov_b32 s31, 0x100000
	s_mov_b32 s3, 0x35400000
	s_cmp_ge_u32 s28, 0x200
	s_cselect_b32 s31, s3, s31
	s_mov_b32 s3, 0xf8100000
	s_cmp_ge_u32 s28, 0x400
	s_cselect_b32 s31, s3, s31
	s_add_u32 s30, s30, s31
	s_lshl_b32 s31, s8, 15
	s_add_u32 s30, s30, s31
	s_add_u32 s14, s34, s30
	s_addc_u32 s15, s35, 0
	s_lshl_b32 s30, s28, 16
	s_lshl_b32 s31, s8, 13
	s_add_u32 s30, s30, s31
	s_add_u32 s30, s30, 0x4d400000
	s_add_u32 s16, s34, s30
	s_addc_u32 s17, s35, 0
	s_lshl_b32 s30, s27, 9
	s_lshl_b32 s31, s8, 7
	s_add_u32 s30, s30, s31
	s_add_u32 s30, s30, 0x1000
	s_add_u32 s18, s12, s30
	s_addc_u32 s19, s13, 0
	s_lshl_b32 s30, s26, 19
	s_lshl_b32 s3, s27, 10
	s_add_u32 s30, s30, s3
	s_add_u32 s30, s30, s31
	s_add_u32 s30, s30, 0x9000000
	s_add_u32 s20, s70, s30
	s_addc_u32 s21, s71, 0
	s_add_u32 s0, s12, s9
	s_addc_u32 s1, s13, 0
	s_add_u32 s4, s12, s10
	s_addc_u32 s5, s13, 0
	s_add_u32 s4, s4, 0x800
	s_addc_u32 s5, s5, 0
	s_add_u32 s26, s4, 0x40000
	s_addc_u32 s27, s5, 0
	global_load_dwordx4 v[64:67], v240, s[0:1]
	global_load_dwordx4 v[68:71], v240, s[4:5]
	global_load_dwordx4 v[72:75], v240, s[26:27]
	global_load_dwordx4 v[76:79], v240, s[0:1] offset:64
	global_load_dwordx4 v[80:83], v240, s[4:5] offset:64
	global_load_dwordx4 v[84:87], v240, s[26:27] offset:64
	global_load_dwordx4 v[88:91], v240, s[0:1] offset:128
	global_load_dwordx4 v[92:95], v240, s[4:5] offset:128
	s_add_u32 s0, s12, s9
	s_addc_u32 s1, s13, 0
	s_add_u32 s4, s12, s10
	s_addc_u32 s5, s13, 0
	s_add_u32 s4, s4, 0x800
	s_addc_u32 s5, s5, 0
	s_add_u32 s26, s4, 0x40000
	s_addc_u32 s27, s5, 0
	global_load_dwordx4 v[96:99], v240, s[26:27] offset:128
	global_load_dwordx4 v[100:103], v240, s[0:1] offset:192
	global_load_dwordx4 v[104:107], v240, s[4:5] offset:192
	global_load_dwordx4 v[108:111], v240, s[26:27] offset:192
	global_load_dwordx4 v[112:115], v240, s[0:1] offset:256
	global_load_dwordx4 v[116:119], v240, s[4:5] offset:256
	global_load_dwordx4 v[120:123], v240, s[26:27] offset:256
	global_load_dwordx4 v[124:127], v240, s[0:1] offset:320
	s_add_u32 s0, s12, s9
	s_addc_u32 s1, s13, 0
	s_add_u32 s4, s12, s10
	s_addc_u32 s5, s13, 0
	s_add_u32 s4, s4, 0x800
	s_addc_u32 s5, s5, 0
	s_add_u32 s26, s4, 0x40000
	s_addc_u32 s27, s5, 0
	global_load_dwordx4 v[128:131], v240, s[4:5] offset:320
	global_load_dwordx4 v[132:135], v240, s[26:27] offset:320
	global_load_dwordx4 v[136:139], v240, s[0:1] offset:384
	global_load_dwordx4 v[140:143], v240, s[4:5] offset:384
	global_load_dwordx4 v[144:147], v240, s[26:27] offset:384
	global_load_dwordx4 v[148:151], v240, s[0:1] offset:448
	global_load_dwordx4 v[152:155], v240, s[4:5] offset:448
	global_load_dwordx4 v[156:159], v240, s[26:27] offset:448
	global_load_dwordx4 v[160:163], v241, s[14:15]
	s_add_u32 s0, s14, 0x2000
	s_addc_u32 s1, s15, 0
	global_load_dwordx4 v[164:167], v241, s[0:1]
	s_add_u32 s0, s14, 0x4000
	s_addc_u32 s1, s15, 0
	global_load_dwordx4 v[168:171], v241, s[0:1]
	s_add_u32 s0, s14, 0x6000
	s_addc_u32 s1, s15, 0
	global_load_dwordx4 v[172:175], v241, s[0:1]
	global_load_dwordx4 v[176:179], v240, s[12:13]
	s_add_u32 s0, s12, 0x40000
	s_addc_u32 s1, s13, 0
	global_load_dwordx4 v[180:183], v240, s[0:1]
	s_add_u32 s0, s12, 0x80000
	s_addc_u32 s1, s13, 0
	global_load_dwordx4 v[184:187], v240, s[0:1]
	s_add_u32 s0, s12, 0xc0000
	s_addc_u32 s1, s13, 0
	global_load_dwordx4 v[188:191], v240, s[0:1]
	s_add_i32 s7, s6, s33
	s_cmpk_lt_i32 s7, 0x480
	s_cselect_b32 s7, s7, s6
	s_sub_u32 s28, 0x47f, s7
	s_lshr_b32 s26, s28, 2
	s_and_b32 s27, s28, 3
	s_lshl_b32 s30, s26, 20
	s_lshl_b32 s31, s27, 9
	s_add_u32 s30, s30, s31
	s_add_u32 s30, s30, 0x10400000
	s_add_u32 s22, s34, s30
	s_addc_u32 s23, s35, 0
	s_lshl_b32 s30, s28, 18
	s_mov_b32 s31, 0x100000
	s_mov_b32 s3, 0x35400000
	s_cmp_ge_u32 s28, 0x200
	s_cselect_b32 s31, s3, s31
	s_mov_b32 s3, 0xf8100000
	s_cmp_ge_u32 s28, 0x400
	s_cselect_b32 s31, s3, s31
	s_add_u32 s30, s30, s31
	s_lshl_b32 s31, s8, 15
	s_add_u32 s30, s30, s31
	s_add_u32 s24, s34, s30
	s_addc_u32 s25, s35, 0
	s_waitcnt vmcnt(0)
; #define LAS __attribute__((address_space(3)))
; __device__ __forceinline__ unsigned pk2(float lo, float hi) { return pg8::cvt_pk_bf16(lo, hi); }
; __device__ __forceinline__ void ph_g3(Frame& F) {
;     ...
;             const int a = w >> 1; f32x4 pc[2] = {(f32x4){0.f, 0.f, 0.f, 0.f}, (f32x4){0.f, 0.f, 0.f, 0.f}};
; #pragma unroll
;             for (int ks = 0; ks < 8; ++ks) { const bf16x8 fqn = ldfrag(qb + (size_t)(16 * a) * ZS_LD * 2 + ks * 64, zrow);
; #pragma unroll
;                 for (int c2 = 0; c2 < 2; ++c2) { const bf16x8 fkn = ldfrag(kb + (size_t)(16 * (2 * (w & 1) + c2)) * ZS_LD * 2 + ks * 64, zrow);
;                     pc[c2] = __builtin_amdgcn_mfma_f32_16x16x32_bf16(fkn, fqn, pc[c2], 0, 0, 0); } }
; #pragma unroll
;             for (int c2 = 0; c2 < 2; ++c2) { const int t = 16 * a + fr, s0 = 16 * (2 * (w & 1) + c2) + 4 * fq; float pv[4];
; #pragma unroll
;                 for (int i = 0; i < 4; ++i) pv[i] = (s0 + i <= t) ? pc[c2][i] : 0.f;
;                 v2u o; o.x = pk2(pv[0], pv[1]); o.y = pk2(pv[2], pv[3]); *(LAS v2u*)(P_s + t * PP + s0 * 2) = o; }
;         }
.Lg3_unit:
	s_waitcnt vmcnt(24)
	v_mfma_f32_16x16x32_bf16 v[0:3], v[68:71], v[64:67], 0
	v_mfma_f32_16x16x32_bf16 v[4:7], v[72:75], v[64:67], 0
	v_mfma_f32_16x16x32_bf16 v[0:3], v[80:83], v[76:79], v[0:3]
	v_mfma_f32_16x16x32_bf16 v[4:7], v[84:87], v[76:79], v[4:7]
	v_mfma_f32_16x16x32_bf16 v[0:3], v[92:95], v[88:91], v[0:3]
	v_mfma_f32_16x16x32_bf16 v[4:7], v[96:99], v[88:91], v[4:7]
	v_mfma_f32_16x16x32_bf16 v[0:3], v[104:107], v[100:103], v[0:3]
	v_mfma_f32_16x16x32_bf16 v[4:7], v[108:111], v[100:103], v[4:7]
	v_mfma_f32_16x16x32_bf16 v[0:3], v[116:119], v[112:115], v[0:3]
	v_mfma_f32_16x16x32_bf16 v[4:7], v[120:123], v[112:115], v[4:7]
	v_mfma_f32_16x16x32_bf16 v[0:3], v[128:131], v[124:127], v[0:3]
	v_mfma_f32_16x16x32_bf16 v[4:7], v[132:135], v[124:127], v[4:7]
	v_mfma_f32_16x16x32_bf16 v[0:3], v[140:143], v[136:139], v[0:3]
	v_mfma_f32_16x16x32_bf16 v[4:7], v[144:147], v[136:139], v[4:7]
	v_mfma_f32_16x16x32_bf16 v[0:3], v[152:155], v[148:151], v[0:3]
	v_mfma_f32_16x16x32_bf16 v[4:7], v[156:159], v[148:151], v[4:7]
	global_load_dwordx4 v[64:67], v241, s[14:15] offset:1024
	s_add_u32 s0, s14, 0x2000
	s_addc_u32 s1, s15, 0
	global_load_dwordx4 v[68:71], v241, s[0:1] offset:1024
	s_add_u32 s0, s14, 0x4000
	s_addc_u32 s1, s15, 0
	global_load_dwordx4 v[72:75], v241, s[0:1] offset:1024
	s_add_u32 s0, s14, 0x6000
	s_addc_u32 s1, s15, 0
	global_load_dwordx4 v[76:79], v241, s[0:1] offset:1024
	global_load_dwordx4 v[80:83], v240, s[12:13] offset:64
	s_add_u32 s0, s12, 0x40000
	s_addc_u32 s1, s13, 0
	global_load_dwordx4 v[84:87], v240, s[0:1] offset:64
	s_add_u32 s0, s12, 0x80000
	s_addc_u32 s1, s13, 0
	global_load_dwordx4 v[88:91], v240, s[0:1] offset:64
	s_add_u32 s0, s12, 0xc0000
	s_addc_u32 s1, s13, 0
	global_load_dwordx4 v[92:95], v240, s[0:1] offset:64
	global_load_dwordx4 v[96:99], v241, s[14:15] offset:2048
	s_add_u32 s0, s14, 0x2000
	s_addc_u32 s1, s15, 0
	global_load_dwordx4 v[100:103], v241, s[0:1] offset:2048
	s_add_u32 s0, s14, 0x4000
	s_addc_u32 s1, s15, 0
	global_load_dwordx4 v[104:107], v241, s[0:1] offset:2048
	s_add_u32 s0, s14, 0x6000
	s_addc_u32 s1, s15, 0
	global_load_dwordx4 v[108:111], v241, s[0:1] offset:2048
	global_load_dwordx4 v[112:115], v240, s[12:13] offset:128
	s_add_u32 s0, s12, 0x40000
	s_addc_u32 s1, s13, 0
	global_load_dwordx4 v[116:119], v240, s[0:1] offset:128
	s_add_u32 s0, s12, 0x80000
	s_addc_u32 s1, s13, 0
	global_load_dwordx4 v[120:123], v240, s[0:1] offset:128
	s_add_u32 s0, s12, 0xc0000
	s_addc_u32 s1, s13, 0
	global_load_dwordx4 v[124:127], v240, s[0:1] offset:128
	global_load_dwordx4 v[128:131], v241, s[14:15] offset:3072
	s_add_u32 s0, s14, 0x2000
	s_addc_u32 s1, s15, 0
	global_load_dwordx4 v[132:135], v241, s[0:1] offset:3072
	s_add_u32 s0, s14, 0x4000
	s_addc_u32 s1, s15, 0
	global_load_dwordx4 v[136:139], v241, s[0:1] offset:3072
	s_add_u32 s0, s14, 0x6000
	s_addc_u32 s1, s15, 0
	global_load_dwordx4 v[140:143], v241, s[0:1] offset:3072
	global_load_dwordx4 v[144:147], v240, s[12:13] offset:192
	s_add_u32 s0, s12, 0x40000
	s_addc_u32 s1, s13, 0
	global_load_dwordx4 v[148:151], v240, s[0:1] offset:192
	s_add_u32 s0, s12, 0x80000
	s_addc_u32 s1, s13, 0
	global_load_dwordx4 v[152:155], v240, s[0:1] offset:192
	s_add_u32 s0, s12, 0xc0000
	s_addc_u32 s1, s13, 0
	global_load_dwordx4 v[156:159], v240, s[0:1] offset:192
	s_nop 7
	v_cmp_le_i32_e32 vcc, 0, v242
	s_nop 1
	v_cndmask_b32_e32 v0, 0, v0, vcc
	v_cmp_le_i32_e32 vcc, 1, v242
	s_nop 1
	v_cndmask_b32_e32 v1, 0, v1, vcc
	v_cmp_le_i32_e32 vcc, 2, v242
	s_nop 1
	v_cndmask_b32_e32 v2, 0, v2, vcc
	v_cmp_le_i32_e32 vcc, 3, v242
	s_nop 1
	v_cndmask_b32_e32 v3, 0, v3, vcc
	v_cmp_le_i32_e32 vcc, 16, v242
	s_nop 1
	v_cndmask_b32_e32 v4, 0, v4, vcc
	v_cmp_le_i32_e32 vcc, 17, v242
	s_nop 1
	v_cndmask_b32_e32 v5, 0, v5, vcc
	v_cmp_le_i32_e32 vcc, 18, v242
	s_nop 1
	v_cndmask_b32_e32 v6, 0, v6, vcc
	v_cmp_le_i32_e32 vcc, 19, v242
	s_nop 1
	v_cndmask_b32_e32 v7, 0, v7, vcc
	v_cvt_pk_bf16_f32 v244, v0, v1
	v_cvt_pk_bf16_f32 v245, v2, v3
	v_cvt_pk_bf16_f32 v246, v4, v5
	v_cvt_pk_bf16_f32 v247, v6, v7
	v_mbcnt_hi_u32_b32 v248, -1, v254
	v_and_b32_e32 v249, 15, v248
	v_lshrrev_b32_e32 v248, 4, v248
	v_mul_u32_u24_e32 v249, 0x90, v249
	v_lshl_add_u32 v249, v248, 3, v249
	v_add_u32_e32 v249, s11, v249
	ds_write_b64 v249, v[244:245]
	ds_write_b64 v249, v[246:247] offset:32
	s_waitcnt lgkmcnt(0)
	s_barrier
; __device__ __forceinline__ void ph_g3(Frame& F) {
;     ...
;         f32x4 acc[4][4];
; #pragma unroll
;         for (int n = 0; n < 4; ++n)
; #pragma unroll
;             for (int a = 0; a < 4; ++a) acc[n][a] = (f32x4){0.f, 0.f, 0.f, 0.f};
;         const unsigned char* sb = (const unsigned char*)slot_ptr(F, ci, h) + (size_t)(4 * w) * 8 * 1024;
;         {
;             bf16x8 fs[4][8];
; #pragma unroll
;             for (int n = 0; n < 4; ++n)
; #pragma unroll
;                 for (int ks = 0; ks < 8; ++ks) fs[n][ks] = ldfrag(sb + (n * 8 + ks) * 1024, l16);
; #pragma unroll
;             for (int ks = 0; ks < 8; ++ks) { bf16x8 fqn[4];
; #pragma unroll
;                 for (int a = 0; a < 4; ++a) fqn[a] = ldfrag(qb + (size_t)(16 * a) * ZS_LD * 2 + ks * 64, zrow);
; #pragma unroll
;                 for (int n = 0; n < 4; ++n)
; #pragma unroll
;                     for (int a = 0; a < 4; ++a) acc[n][a] = __builtin_amdgcn_mfma_f32_16x16x32_bf16(fs[n][ks], fqn[a], acc[n][a], 0, 0, 0); }
	s_waitcnt vmcnt(40)
	v_mfma_f32_16x16x32_bf16 v[0:3], v[160:163], v[176:179], 0
	v_mfma_f32_16x16x32_bf16 v[4:7], v[160:163], v[180:183], 0
	v_mfma_f32_16x16x32_bf16 v[8:11], v[160:163], v[184:187], 0
	v_mfma_f32_16x16x32_bf16 v[12:15], v[160:163], v[188:191], 0
	v_mfma_f32_16x16x32_bf16 v[16:19], v[164:167], v[176:179], 0
	v_mfma_f32_16x16x32_bf16 v[20:23], v[164:167], v[180:183], 0
	v_mfma_f32_16x16x32_bf16 v[24:27], v[164:167], v[184:187], 0
	v_mfma_f32_16x16x32_bf16 v[28:31], v[164:167], v[188:191], 0
	v_mfma_f32_16x16x32_bf16 v[32:35], v[168:171], v[176:179], 0
	v_mfma_f32_16x16x32_bf16 v[36:39], v[168:171], v[180:183], 0
	v_mfma_f32_16x16x32_bf16 v[40:43], v[168:171], v[184:187], 0
	v_mfma_f32_16x16x32_bf16 v[44:47], v[168:171], v[188:191], 0
	v_mfma_f32_16x16x32_bf16 v[48:51], v[172:175], v[176:179], 0
	v_mfma_f32_16x16x32_bf16 v[52:55], v[172:175], v[180:183], 0
	v_mfma_f32_16x16x32_bf16 v[56:59], v[172:175], v[184:187], 0
	v_mfma_f32_16x16x32_bf16 v[60:63], v[172:175], v[188:191], 0
	s_add_u32 s0, s14, 0x1000
	s_addc_u32 s1, s15, 0
	global_load_dwordx4 v[160:163], v241, s[0:1]
	s_add_u32 s0, s14, 0x3000
	s_addc_u32 s1, s15, 0
	global_load_dwordx4 v[164:167], v241, s[0:1]
	s_add_u32 s0, s14, 0x5000
	s_addc_u32 s1, s15, 0
	global_load_dwordx4 v[168:171], v241, s[0:1]
	s_add_u32 s0, s14, 0x7000
	s_addc_u32 s1, s15, 0
	global_load_dwordx4 v[172:175], v241, s[0:1]
	global_load_dwordx4 v[176:179], v240, s[12:13] offset:256
	s_add_u32 s0, s12, 0x40000
	s_addc_u32 s1, s13, 0
	global_load_dwordx4 v[180:183], v240, s[0:1] offset:256
	s_add_u32 s0, s12, 0x80000
	s_addc_u32 s1, s13, 0
	global_load_dwordx4 v[184:187], v240, s[0:1] offset:256
	s_add_u32 s0, s12, 0xc0000
	s_addc_u32 s1, s13, 0
	global_load_dwordx4 v[188:191], v240, s[0:1] offset:256
	s_waitcnt vmcnt(24)
	v_mfma_f32_16x16x32_bf16 v[0:3], v[64:67], v[80:83], v[0:3]
	v_mfma_f32_16x16x32_bf16 v[4:7], v[64:67], v[84:87], v[4:7]
	v_mfma_f32_16x16x32_bf16 v[8:11], v[64:67], v[88:91], v[8:11]
	v_mfma_f32_16x16x32_bf16 v[12:15], v[64:67], v[92:95], v[12:15]
	v_mfma_f32_16x16x32_bf16 v[16:19], v[68:71], v[80:83], v[16:19]
	v_mfma_f32_16x16x32_bf16 v[20:23], v[68:71], v[84:87], v[20:23]
	v_mfma_f32_16x16x32_bf16 v[24:27], v[68:71], v[88:91], v[24:27]
	v_mfma_f32_16x16x32_bf16 v[28:31], v[68:71], v[92:95], v[28:31]
	v_mfma_f32_16x16x32_bf16 v[32:35], v[72:75], v[80:83], v[32:35]
	v_mfma_f32_16x16x32_bf16 v[36:39], v[72:75], v[84:87], v[36:39]
	v_mfma_f32_16x16x32_bf16 v[40:43], v[72:75], v[88:91], v[40:43]
	v_mfma_f32_16x16x32_bf16 v[44:47], v[72:75], v[92:95], v[44:47]
	v_mfma_f32_16x16x32_bf16 v[48:51], v[76:79], v[80:83], v[48:51]
	v_mfma_f32_16x16x32_bf16 v[52:55], v[76:79], v[84:87], v[52:55]
	v_mfma_f32_16x16x32_bf16 v[56:59], v[76:79], v[88:91], v[56:59]
	v_mfma_f32_16x16x32_bf16 v[60:63], v[76:79], v[92:95], v[60:63]
	s_add_u32 s0, s14, 0x1000
	s_addc_u32 s1, s15, 0
	global_load_dwordx4 v[64:67], v241, s[0:1] offset:1024
	s_add_u32 s0, s14, 0x3000
	s_addc_u32 s1, s15, 0
	global_load_dwordx4 v[68:71], v241, s[0:1] offset:1024
	s_add_u32 s0, s14, 0x5000
	s_addc_u32 s1, s15, 0
	global_load_dwordx4 v[72:75], v241, s[0:1] offset:1024
	s_add_u32 s0, s14, 0x7000
	s_addc_u32 s1, s15, 0
	global_load_dwordx4 v[76:79], v241, s[0:1] offset:1024
	global_load_dwordx4 v[80:83], v240, s[12:13] offset:320
	s_add_u32 s0, s12, 0x40000
	s_addc_u32 s1, s13, 0
	global_load_dwordx4 v[84:87], v240, s[0:1] offset:320
	s_add_u32 s0, s12, 0x80000
	s_addc_u32 s1, s13, 0
	global_load_dwordx4 v[88:91], v240, s[0:1] offset:320
	s_add_u32 s0, s12, 0xc0000
	s_addc_u32 s1, s13, 0
	global_load_dwordx4 v[92:95], v240, s[0:1] offset:320
	s_waitcnt vmcnt(24)
	v_mfma_f32_16x16x32_bf16 v[0:3], v[96:99], v[112:115], v[0:3]
	v_mfma_f32_16x16x32_bf16 v[4:7], v[96:99], v[116:119], v[4:7]
	v_mfma_f32_16x16x32_bf16 v[8:11], v[96:99], v[120:123], v[8:11]
	v_mfma_f32_16x16x32_bf16 v[12:15], v[96:99], v[124:127], v[12:15]
	v_mfma_f32_16x16x32_bf16 v[16:19], v[100:103], v[112:115], v[16:19]
	v_mfma_f32_16x16x32_bf16 v[20:23], v[100:103], v[116:119], v[20:23]
	v_mfma_f32_16x16x32_bf16 v[24:27], v[100:103], v[120:123], v[24:27]
	v_mfma_f32_16x16x32_bf16 v[28:31], v[100:103], v[124:127], v[28:31]
	v_mfma_f32_16x16x32_bf16 v[32:35], v[104:107], v[112:115], v[32:35]
	v_mfma_f32_16x16x32_bf16 v[36:39], v[104:107], v[116:119], v[36:39]
	v_mfma_f32_16x16x32_bf16 v[40:43], v[104:107], v[120:123], v[40:43]
	v_mfma_f32_16x16x32_bf16 v[44:47], v[104:107], v[124:127], v[44:47]
	v_mfma_f32_16x16x32_bf16 v[48:51], v[108:111], v[112:115], v[48:51]
	v_mfma_f32_16x16x32_bf16 v[52:55], v[108:111], v[116:119], v[52:55]
	v_mfma_f32_16x16x32_bf16 v[56:59], v[108:111], v[120:123], v[56:59]
	v_mfma_f32_16x16x32_bf16 v[60:63], v[108:111], v[124:127], v[60:63]
	s_add_u32 s0, s14, 0x1000
	s_addc_u32 s1, s15, 0
	global_load_dwordx4 v[96:99], v241, s[0:1] offset:2048
	s_add_u32 s0, s14, 0x3000
	s_addc_u32 s1, s15, 0
	global_load_dwordx4 v[100:103], v241, s[0:1] offset:2048
	s_add_u32 s0, s14, 0x5000
	s_addc_u32 s1, s15, 0
	global_load_dwordx4 v[104:107], v241, s[0:1] offset:2048
	s_add_u32 s0, s14, 0x7000
	s_addc_u32 s1, s15, 0
	global_load_dwordx4 v[108:111], v241, s[0:1] offset:2048
	global_load_dwordx4 v[112:115], v240, s[12:13] offset:384
	s_add_u32 s0, s12, 0x40000
	s_addc_u32 s1, s13, 0
	global_load_dwordx4 v[116:119], v240, s[0:1] offset:384
	s_add_u32 s0, s12, 0x80000
	s_addc_u32 s1, s13, 0
	global_load_dwordx4 v[120:123], v240, s[0:1] offset:384
	s_add_u32 s0, s12, 0xc0000
	s_addc_u32 s1, s13, 0
	global_load_dwordx4 v[124:127], v240, s[0:1] offset:384
	s_waitcnt vmcnt(24)
; __device__ __forceinline__ float bf_lo(unsigned w) { return __uint_as_float(w << 16); }
; __device__ __forceinline__ float bf_hi(unsigned w) { return __uint_as_float(w & 0xffff0000u); }
; __device__ __forceinline__ void ph_g3(Frame& F) {
;     ...
;             for (int ks = 0; ks < 8; ++ks) { bf16x8 fqn[4];
; #pragma unroll
;                 for (int a = 0; a < 4; ++a) fqn[a] = ldfrag(qb + (size_t)(16 * a) * ZS_LD * 2 + ks * 64, zrow);
; #pragma unroll
;                 for (int n = 0; n < 4; ++n)
; #pragma unroll
;                     for (int a = 0; a < 4; ++a) acc[n][a] = __builtin_amdgcn_mfma_f32_16x16x32_bf16(fs[n][ks], fqn[a], acc[n][a], 0, 0, 0); }
;         }
;         const unsigned char* vb = F.ws + WS_VT + (((size_t)ci * 128 + h * 32 + 4 * w) * 2) * 1024;
; #pragma unroll
;         for (int ks = 0; ks < 2; ++ks) {
;             bf16x8 fv[4], fp[4];
; #pragma unroll
;             for (int n = 0; n < 4; ++n) fv[n] = ldfrag(vb + (n * 2 + ks) * 1024, l16);
;     ...
;                 const v2u rw = *(const v2u*)(rb + (size_t)t * ZS_LD * 2 + dvl * 2); const float rr[4] = {bf_lo(rw.x), bf_hi(rw.x), bf_lo(rw.y), bf_hi(rw.y)}; float o[4];
	v_mfma_f32_16x16x32_bf16 v[0:3], v[128:131], v[144:147], v[0:3]
	v_mfma_f32_16x16x32_bf16 v[4:7], v[128:131], v[148:151], v[4:7]
	v_mfma_f32_16x16x32_bf16 v[8:11], v[128:131], v[152:155], v[8:11]
	v_mfma_f32_16x16x32_bf16 v[12:15], v[128:131], v[156:159], v[12:15]
	v_mfma_f32_16x16x32_bf16 v[16:19], v[132:135], v[144:147], v[16:19]
	v_mfma_f32_16x16x32_bf16 v[20:23], v[132:135], v[148:151], v[20:23]
	v_mfma_f32_16x16x32_bf16 v[24:27], v[132:135], v[152:155], v[24:27]
	v_mfma_f32_16x16x32_bf16 v[28:31], v[132:135], v[156:159], v[28:31]
	v_mfma_f32_16x16x32_bf16 v[32:35], v[136:139], v[144:147], v[32:35]
	v_mfma_f32_16x16x32_bf16 v[36:39], v[136:139], v[148:151], v[36:39]
	v_mfma_f32_16x16x32_bf16 v[40:43], v[136:139], v[152:155], v[40:43]
	v_mfma_f32_16x16x32_bf16 v[44:47], v[136:139], v[156:159], v[44:47]
	v_mfma_f32_16x16x32_bf16 v[48:51], v[140:143], v[144:147], v[48:51]
	v_mfma_f32_16x16x32_bf16 v[52:55], v[140:143], v[148:151], v[52:55]
	v_mfma_f32_16x16x32_bf16 v[56:59], v[140:143], v[152:155], v[56:59]
	v_mfma_f32_16x16x32_bf16 v[60:63], v[140:143], v[156:159], v[60:63]
	s_add_u32 s0, s14, 0x1000
	s_addc_u32 s1, s15, 0
	global_load_dwordx4 v[128:131], v241, s[0:1] offset:3072
	s_add_u32 s0, s14, 0x3000
	s_addc_u32 s1, s15, 0
	global_load_dwordx4 v[132:135], v241, s[0:1] offset:3072
	s_add_u32 s0, s14, 0x5000
	s_addc_u32 s1, s15, 0
	global_load_dwordx4 v[136:139], v241, s[0:1] offset:3072
	s_add_u32 s0, s14, 0x7000
	s_addc_u32 s1, s15, 0
	global_load_dwordx4 v[140:143], v241, s[0:1] offset:3072
	global_load_dwordx4 v[144:147], v240, s[12:13] offset:448
	s_add_u32 s0, s12, 0x40000
	s_addc_u32 s1, s13, 0
	global_load_dwordx4 v[148:151], v240, s[0:1] offset:448
	s_add_u32 s0, s12, 0x80000
	s_addc_u32 s1, s13, 0
	global_load_dwordx4 v[152:155], v240, s[0:1] offset:448
	s_add_u32 s0, s12, 0xc0000
	s_addc_u32 s1, s13, 0
	global_load_dwordx4 v[156:159], v240, s[0:1] offset:448
	v_mbcnt_hi_u32_b32 v252, -1, v254
	v_and_b32_e32 v253, 15, v252
	v_lshrrev_b32_e32 v252, 4, v252
	v_lshlrev_b32_e32 v253, 14, v253
	v_lshl_add_u32 v252, v252, 3, v253
	global_load_dwordx2 v[192:193], v252, s[18:19]
	global_load_dwordx2 v[194:195], v252, s[18:19] offset:32
	global_load_dwordx2 v[196:197], v252, s[18:19] offset:64
	global_load_dwordx2 v[198:199], v252, s[18:19] offset:96
	s_add_u32 s0, s18, 0x40000
	s_addc_u32 s1, s19, 0
	global_load_dwordx2 v[200:201], v252, s[0:1]
	global_load_dwordx2 v[202:203], v252, s[0:1] offset:32
	global_load_dwordx2 v[204:205], v252, s[0:1] offset:64
	global_load_dwordx2 v[206:207], v252, s[0:1] offset:96
	s_add_u32 s0, s18, 0x80000
	s_addc_u32 s1, s19, 0
	global_load_dwordx2 v[208:209], v252, s[0:1]
	global_load_dwordx2 v[210:211], v252, s[0:1] offset:32
	global_load_dwordx2 v[212:213], v252, s[0:1] offset:64
	global_load_dwordx2 v[214:215], v252, s[0:1] offset:96
	s_add_u32 s0, s18, 0xc0000
	s_addc_u32 s1, s19, 0
	global_load_dwordx2 v[216:217], v252, s[0:1]
	global_load_dwordx2 v[218:219], v252, s[0:1] offset:32
	global_load_dwordx2 v[220:221], v252, s[0:1] offset:64
	global_load_dwordx2 v[222:223], v252, s[0:1] offset:96
	s_waitcnt vmcnt(40)
	v_mfma_f32_16x16x32_bf16 v[0:3], v[160:163], v[176:179], v[0:3]
	v_mfma_f32_16x16x32_bf16 v[4:7], v[160:163], v[180:183], v[4:7]
	v_mfma_f32_16x16x32_bf16 v[8:11], v[160:163], v[184:187], v[8:11]
	v_mfma_f32_16x16x32_bf16 v[12:15], v[160:163], v[188:191], v[12:15]
	v_mfma_f32_16x16x32_bf16 v[16:19], v[164:167], v[176:179], v[16:19]
	v_mfma_f32_16x16x32_bf16 v[20:23], v[164:167], v[180:183], v[20:23]
	v_mfma_f32_16x16x32_bf16 v[24:27], v[164:167], v[184:187], v[24:27]
	v_mfma_f32_16x16x32_bf16 v[28:31], v[164:167], v[188:191], v[28:31]
	v_mfma_f32_16x16x32_bf16 v[32:35], v[168:171], v[176:179], v[32:35]
	v_mfma_f32_16x16x32_bf16 v[36:39], v[168:171], v[180:183], v[36:39]
	v_mfma_f32_16x16x32_bf16 v[40:43], v[168:171], v[184:187], v[40:43]
	v_mfma_f32_16x16x32_bf16 v[44:47], v[168:171], v[188:191], v[44:47]
	v_mfma_f32_16x16x32_bf16 v[48:51], v[172:175], v[176:179], v[48:51]
	v_mfma_f32_16x16x32_bf16 v[52:55], v[172:175], v[180:183], v[52:55]
	v_mfma_f32_16x16x32_bf16 v[56:59], v[172:175], v[184:187], v[56:59]
	v_mfma_f32_16x16x32_bf16 v[60:63], v[172:175], v[188:191], v[60:63]
	s_add_u32 s0, s16, 0x1000
	s_addc_u32 s1, s17, 0
	global_load_dwordx4 v[160:163], v241, s[16:17]
	global_load_dwordx4 v[164:167], v241, s[16:17] offset:2048
	global_load_dwordx4 v[168:171], v241, s[0:1]
	global_load_dwordx4 v[172:175], v241, s[0:1] offset:2048
	global_load_dwordx4 v[176:179], v241, s[16:17] offset:1024
	global_load_dwordx4 v[180:183], v241, s[16:17] offset:3072
	global_load_dwordx4 v[184:187], v241, s[0:1] offset:1024
	global_load_dwordx4 v[188:191], v241, s[0:1] offset:3072
	s_waitcnt vmcnt(40)
	v_mfma_f32_16x16x32_bf16 v[0:3], v[64:67], v[80:83], v[0:3]
	v_mfma_f32_16x16x32_bf16 v[4:7], v[64:67], v[84:87], v[4:7]
	v_mfma_f32_16x16x32_bf16 v[8:11], v[64:67], v[88:91], v[8:11]
	v_mfma_f32_16x16x32_bf16 v[12:15], v[64:67], v[92:95], v[12:15]
	v_mfma_f32_16x16x32_bf16 v[16:19], v[68:71], v[80:83], v[16:19]
	v_mfma_f32_16x16x32_bf16 v[20:23], v[68:71], v[84:87], v[20:23]
	v_mfma_f32_16x16x32_bf16 v[24:27], v[68:71], v[88:91], v[24:27]
	v_mfma_f32_16x16x32_bf16 v[28:31], v[68:71], v[92:95], v[28:31]
	v_mfma_f32_16x16x32_bf16 v[32:35], v[72:75], v[80:83], v[32:35]
	v_mfma_f32_16x16x32_bf16 v[36:39], v[72:75], v[84:87], v[36:39]
	v_mfma_f32_16x16x32_bf16 v[40:43], v[72:75], v[88:91], v[40:43]
	v_mfma_f32_16x16x32_bf16 v[44:47], v[72:75], v[92:95], v[44:47]
	v_mfma_f32_16x16x32_bf16 v[48:51], v[76:79], v[80:83], v[48:51]
	v_mfma_f32_16x16x32_bf16 v[52:55], v[76:79], v[84:87], v[52:55]
	v_mfma_f32_16x16x32_bf16 v[56:59], v[76:79], v[88:91], v[56:59]
	v_mfma_f32_16x16x32_bf16 v[60:63], v[76:79], v[92:95], v[60:63]
	s_add_u32 s0, s22, s9
	s_addc_u32 s1, s23, 0
	s_add_u32 s4, s22, s10
	s_addc_u32 s5, s23, 0
	s_add_u32 s4, s4, 0x800
	s_addc_u32 s5, s5, 0
	s_add_u32 s26, s4, 0x40000
	s_addc_u32 s27, s5, 0
	global_load_dwordx4 v[64:67], v240, s[0:1]
	global_load_dwordx4 v[68:71], v240, s[4:5]
	global_load_dwordx4 v[72:75], v240, s[26:27]
	global_load_dwordx4 v[76:79], v240, s[0:1] offset:64
	global_load_dwordx4 v[80:83], v240, s[4:5] offset:64
	global_load_dwordx4 v[84:87], v240, s[26:27] offset:64
	global_load_dwordx4 v[88:91], v240, s[0:1] offset:128
	global_load_dwordx4 v[92:95], v240, s[4:5] offset:128
	s_waitcnt vmcnt(40)
; #define LAS __attribute__((address_space(3)))
; __device__ __forceinline__ void ph_g3(Frame& F) {
;     ...
;             for (int ks = 0; ks < 8; ++ks) { bf16x8 fqn[4];
; #pragma unroll
;                 for (int a = 0; a < 4; ++a) fqn[a] = ldfrag(qb + (size_t)(16 * a) * ZS_LD * 2 + ks * 64, zrow);
; #pragma unroll
;                 for (int n = 0; n < 4; ++n)
; #pragma unroll
;                     for (int a = 0; a < 4; ++a) acc[n][a] = __builtin_amdgcn_mfma_f32_16x16x32_bf16(fs[n][ks], fqn[a], acc[n][a], 0, 0, 0); }
;         }
;         const unsigned char* vb = F.ws + WS_VT + (((size_t)ci * 128 + h * 32 + 4 * w) * 2) * 1024;
; #pragma unroll
;         for (int ks = 0; ks < 2; ++ks) {
;             bf16x8 fv[4], fp[4];
; #pragma unroll
;             for (int n = 0; n < 4; ++n) fv[n] = ldfrag(vb + (n * 2 + ks) * 1024, l16);
; #pragma unroll
;             for (int a = 0; a < 4; ++a) fp[a] = *(const LAS bf16x8*)(P_s + (16 * a + fr) * PP + ks * 64 + fq * 16);
; #pragma unroll
;             for (int n = 0; n < 4; ++n)
; #pragma unroll
;                 for (int a = 0; a < 4; ++a) acc[n][a] = __builtin_amdgcn_mfma_f32_16x16x32_bf16(fv[n], fp[a], acc[n][a], 0, 0, 0);
	v_mfma_f32_16x16x32_bf16 v[0:3], v[96:99], v[112:115], v[0:3]
	v_mfma_f32_16x16x32_bf16 v[4:7], v[96:99], v[116:119], v[4:7]
	v_mfma_f32_16x16x32_bf16 v[8:11], v[96:99], v[120:123], v[8:11]
	v_mfma_f32_16x16x32_bf16 v[12:15], v[96:99], v[124:127], v[12:15]
	v_mfma_f32_16x16x32_bf16 v[16:19], v[100:103], v[112:115], v[16:19]
	v_mfma_f32_16x16x32_bf16 v[20:23], v[100:103], v[116:119], v[20:23]
	v_mfma_f32_16x16x32_bf16 v[24:27], v[100:103], v[120:123], v[24:27]
	v_mfma_f32_16x16x32_bf16 v[28:31], v[100:103], v[124:127], v[28:31]
	v_mfma_f32_16x16x32_bf16 v[32:35], v[104:107], v[112:115], v[32:35]
	v_mfma_f32_16x16x32_bf16 v[36:39], v[104:107], v[116:119], v[36:39]
	v_mfma_f32_16x16x32_bf16 v[40:43], v[104:107], v[120:123], v[40:43]
	v_mfma_f32_16x16x32_bf16 v[44:47], v[104:107], v[124:127], v[44:47]
	v_mfma_f32_16x16x32_bf16 v[48:51], v[108:111], v[112:115], v[48:51]
	v_mfma_f32_16x16x32_bf16 v[52:55], v[108:111], v[116:119], v[52:55]
	v_mfma_f32_16x16x32_bf16 v[56:59], v[108:111], v[120:123], v[56:59]
	v_mfma_f32_16x16x32_bf16 v[60:63], v[108:111], v[124:127], v[60:63]
	s_add_u32 s0, s22, s9
	s_addc_u32 s1, s23, 0
	s_add_u32 s4, s22, s10
	s_addc_u32 s5, s23, 0
	s_add_u32 s4, s4, 0x800
	s_addc_u32 s5, s5, 0
	s_add_u32 s26, s4, 0x40000
	s_addc_u32 s27, s5, 0
	global_load_dwordx4 v[96:99], v240, s[26:27] offset:128
	global_load_dwordx4 v[100:103], v240, s[0:1] offset:192
	global_load_dwordx4 v[104:107], v240, s[4:5] offset:192
	global_load_dwordx4 v[108:111], v240, s[26:27] offset:192
	global_load_dwordx4 v[112:115], v240, s[0:1] offset:256
	global_load_dwordx4 v[116:119], v240, s[4:5] offset:256
	global_load_dwordx4 v[120:123], v240, s[26:27] offset:256
	global_load_dwordx4 v[124:127], v240, s[0:1] offset:320
	s_waitcnt vmcnt(40)
	v_mfma_f32_16x16x32_bf16 v[0:3], v[128:131], v[144:147], v[0:3]
	v_mfma_f32_16x16x32_bf16 v[4:7], v[128:131], v[148:151], v[4:7]
	v_mfma_f32_16x16x32_bf16 v[8:11], v[128:131], v[152:155], v[8:11]
	v_mfma_f32_16x16x32_bf16 v[12:15], v[128:131], v[156:159], v[12:15]
	v_mfma_f32_16x16x32_bf16 v[16:19], v[132:135], v[144:147], v[16:19]
	v_mfma_f32_16x16x32_bf16 v[20:23], v[132:135], v[148:151], v[20:23]
	v_mfma_f32_16x16x32_bf16 v[24:27], v[132:135], v[152:155], v[24:27]
	v_mfma_f32_16x16x32_bf16 v[28:31], v[132:135], v[156:159], v[28:31]
	v_mfma_f32_16x16x32_bf16 v[32:35], v[136:139], v[144:147], v[32:35]
	v_mfma_f32_16x16x32_bf16 v[36:39], v[136:139], v[148:151], v[36:39]
	v_mfma_f32_16x16x32_bf16 v[40:43], v[136:139], v[152:155], v[40:43]
	v_mfma_f32_16x16x32_bf16 v[44:47], v[136:139], v[156:159], v[44:47]
	v_mfma_f32_16x16x32_bf16 v[48:51], v[140:143], v[144:147], v[48:51]
	v_mfma_f32_16x16x32_bf16 v[52:55], v[140:143], v[148:151], v[52:55]
	v_mfma_f32_16x16x32_bf16 v[56:59], v[140:143], v[152:155], v[56:59]
	v_mfma_f32_16x16x32_bf16 v[60:63], v[140:143], v[156:159], v[60:63]
	s_add_u32 s0, s22, s9
	s_addc_u32 s1, s23, 0
	s_add_u32 s4, s22, s10
	s_addc_u32 s5, s23, 0
	s_add_u32 s4, s4, 0x800
	s_addc_u32 s5, s5, 0
	s_add_u32 s26, s4, 0x40000
	s_addc_u32 s27, s5, 0
	global_load_dwordx4 v[128:131], v240, s[4:5] offset:320
	global_load_dwordx4 v[132:135], v240, s[26:27] offset:320
	global_load_dwordx4 v[136:139], v240, s[0:1] offset:384
	global_load_dwordx4 v[140:143], v240, s[4:5] offset:384
	global_load_dwordx4 v[144:147], v240, s[26:27] offset:384
	global_load_dwordx4 v[148:151], v240, s[0:1] offset:448
	global_load_dwordx4 v[152:155], v240, s[4:5] offset:448
	global_load_dwordx4 v[156:159], v240, s[26:27] offset:448
	s_waitcnt vmcnt(24)
	v_mbcnt_hi_u32_b32 v252, -1, v254
	v_and_b32_e32 v253, 15, v252
	v_lshrrev_b32_e32 v252, 4, v252
	v_mul_u32_u24_e32 v253, 0x90, v253
	v_lshl_add_u32 v253, v252, 4, v253
	ds_read_b128 v[244:247], v253 offset:0
	ds_read_b128 v[248:251], v253 offset:2304
	s_waitcnt lgkmcnt(0)
	v_mfma_f32_16x16x32_bf16 v[0:3], v[160:163], v[244:247], v[0:3]
	v_mfma_f32_16x16x32_bf16 v[16:19], v[164:167], v[244:247], v[16:19]
	v_mfma_f32_16x16x32_bf16 v[32:35], v[168:171], v[244:247], v[32:35]
	v_mfma_f32_16x16x32_bf16 v[48:51], v[172:175], v[244:247], v[48:51]
	v_mfma_f32_16x16x32_bf16 v[4:7], v[160:163], v[248:251], v[4:7]
	v_mfma_f32_16x16x32_bf16 v[20:23], v[164:167], v[248:251], v[20:23]
	v_mfma_f32_16x16x32_bf16 v[36:39], v[168:171], v[248:251], v[36:39]
	v_mfma_f32_16x16x32_bf16 v[52:55], v[172:175], v[248:251], v[52:55]
	ds_read_b128 v[244:247], v253 offset:4608
	ds_read_b128 v[248:251], v253 offset:6912
	s_waitcnt lgkmcnt(0)
	v_mfma_f32_16x16x32_bf16 v[8:11], v[160:163], v[244:247], v[8:11]
	v_mfma_f32_16x16x32_bf16 v[24:27], v[164:167], v[244:247], v[24:27]
	v_mfma_f32_16x16x32_bf16 v[40:43], v[168:171], v[244:247], v[40:43]
	v_mfma_f32_16x16x32_bf16 v[56:59], v[172:175], v[244:247], v[56:59]
	v_mfma_f32_16x16x32_bf16 v[12:15], v[160:163], v[248:251], v[12:15]
	v_mfma_f32_16x16x32_bf16 v[28:31], v[164:167], v[248:251], v[28:31]
	v_mfma_f32_16x16x32_bf16 v[44:47], v[168:171], v[248:251], v[44:47]
	v_mfma_f32_16x16x32_bf16 v[60:63], v[172:175], v[248:251], v[60:63]
	ds_read_b128 v[244:247], v253 offset:64
	ds_read_b128 v[248:251], v253 offset:2368
	s_waitcnt lgkmcnt(0)
	v_mfma_f32_16x16x32_bf16 v[0:3], v[176:179], v[244:247], v[0:3]
	v_mfma_f32_16x16x32_bf16 v[16:19], v[180:183], v[244:247], v[16:19]
	v_mfma_f32_16x16x32_bf16 v[32:35], v[184:187], v[244:247], v[32:35]
	v_mfma_f32_16x16x32_bf16 v[48:51], v[188:191], v[244:247], v[48:51]
	v_mfma_f32_16x16x32_bf16 v[4:7], v[176:179], v[248:251], v[4:7]
	v_mfma_f32_16x16x32_bf16 v[20:23], v[180:183], v[248:251], v[20:23]
	v_mfma_f32_16x16x32_bf16 v[36:39], v[184:187], v[248:251], v[36:39]
	v_mfma_f32_16x16x32_bf16 v[52:55], v[188:191], v[248:251], v[52:55]
	ds_read_b128 v[244:247], v253 offset:4672
	ds_read_b128 v[248:251], v253 offset:6976
	s_waitcnt lgkmcnt(0)
; #define LAS __attribute__((address_space(3)))
; __device__ __forceinline__ void ph_g3(Frame& F) {
;     ...
;         const unsigned char* vb = F.ws + WS_VT + (((size_t)ci * 128 + h * 32 + 4 * w) * 2) * 1024;
; #pragma unroll
;         for (int ks = 0; ks < 2; ++ks) {
;             bf16x8 fv[4], fp[4];
; #pragma unroll
;             for (int n = 0; n < 4; ++n) fv[n] = ldfrag(vb + (n * 2 + ks) * 1024, l16);
; #pragma unroll
;             for (int a = 0; a < 4; ++a) fp[a] = *(const LAS bf16x8*)(P_s + (16 * a + fr) * PP + ks * 64 + fq * 16);
; #pragma unroll
;             for (int n = 0; n < 4; ++n)
; #pragma unroll
;                 for (int a = 0; a < 4; ++a) acc[n][a] = __builtin_amdgcn_mfma_f32_16x16x32_bf16(fv[n], fp[a], acc[n][a], 0, 0, 0);
;         }
; #pragma unroll
;         for (int a = 0; a < 4; ++a) { float ss = 0.f;
; #pragma unroll
;             for (int n = 0; n < 4; ++n) ss += (acc[n][a][0] * acc[n][a][0] + acc[n][a][1] * acc[n][a][1]) + (acc[n][a][2] * acc[n][a][2] + acc[n][a][3] * acc[n][a][3]);
;             ss += __shfl_xor(ss, 16); ss += __shfl_xor(ss, 32);
;             if (fq == 0) red[(16 * a + fr) * 8 + w] = ss; }
;         __syncthreads();
	v_mfma_f32_16x16x32_bf16 v[8:11], v[176:179], v[244:247], v[8:11]
	v_mfma_f32_16x16x32_bf16 v[24:27], v[180:183], v[244:247], v[24:27]
	v_mfma_f32_16x16x32_bf16 v[40:43], v[184:187], v[244:247], v[40:43]
	v_mfma_f32_16x16x32_bf16 v[56:59], v[188:191], v[244:247], v[56:59]
	v_mfma_f32_16x16x32_bf16 v[12:15], v[176:179], v[248:251], v[12:15]
	v_mfma_f32_16x16x32_bf16 v[28:31], v[180:183], v[248:251], v[28:31]
	v_mfma_f32_16x16x32_bf16 v[44:47], v[184:187], v[248:251], v[44:47]
	v_mfma_f32_16x16x32_bf16 v[60:63], v[188:191], v[248:251], v[60:63]
	global_load_dwordx4 v[160:163], v241, s[24:25]
	s_add_u32 s0, s24, 0x2000
	s_addc_u32 s1, s25, 0
	global_load_dwordx4 v[164:167], v241, s[0:1]
	s_add_u32 s0, s24, 0x4000
	s_addc_u32 s1, s25, 0
	global_load_dwordx4 v[168:171], v241, s[0:1]
	s_add_u32 s0, s24, 0x6000
	s_addc_u32 s1, s25, 0
	global_load_dwordx4 v[172:175], v241, s[0:1]
	global_load_dwordx4 v[176:179], v240, s[22:23]
	s_add_u32 s0, s22, 0x40000
	s_addc_u32 s1, s23, 0
	global_load_dwordx4 v[180:183], v240, s[0:1]
	s_add_u32 s0, s22, 0x80000
	s_addc_u32 s1, s23, 0
	global_load_dwordx4 v[184:187], v240, s[0:1]
	s_add_u32 s0, s22, 0xc0000
	s_addc_u32 s1, s23, 0
	global_load_dwordx4 v[188:191], v240, s[0:1]
	s_nop 7
	v_mul_f32_e32 v248, v0, v0
	v_fmac_f32_e32 v248, v1, v1
	v_mul_f32_e32 v249, v2, v2
	v_fmac_f32_e32 v249, v3, v3
	v_add_f32_e32 v244, v248, v249
	v_mul_f32_e32 v248, v16, v16
	v_fmac_f32_e32 v248, v17, v17
	v_mul_f32_e32 v249, v18, v18
	v_fmac_f32_e32 v249, v19, v19
	v_add_f32_e32 v248, v248, v249
	v_add_f32_e32 v244, v244, v248
	v_mul_f32_e32 v248, v32, v32
	v_fmac_f32_e32 v248, v33, v33
	v_mul_f32_e32 v249, v34, v34
	v_fmac_f32_e32 v249, v35, v35
	v_add_f32_e32 v248, v248, v249
	v_add_f32_e32 v244, v244, v248
	v_mul_f32_e32 v248, v48, v48
	v_fmac_f32_e32 v248, v49, v49
	v_mul_f32_e32 v249, v50, v50
	v_fmac_f32_e32 v249, v51, v51
	v_add_f32_e32 v248, v248, v249
	v_add_f32_e32 v244, v244, v248
	v_mul_f32_e32 v248, v4, v4
	v_fmac_f32_e32 v248, v5, v5
	v_mul_f32_e32 v249, v6, v6
	v_fmac_f32_e32 v249, v7, v7
	v_add_f32_e32 v245, v248, v249
	v_mul_f32_e32 v248, v20, v20
	v_fmac_f32_e32 v248, v21, v21
	v_mul_f32_e32 v249, v22, v22
	v_fmac_f32_e32 v249, v23, v23
	v_add_f32_e32 v248, v248, v249
	v_add_f32_e32 v245, v245, v248
	v_mul_f32_e32 v248, v36, v36
	v_fmac_f32_e32 v248, v37, v37
	v_mul_f32_e32 v249, v38, v38
	v_fmac_f32_e32 v249, v39, v39
	v_add_f32_e32 v248, v248, v249
	v_add_f32_e32 v245, v245, v248
	v_mul_f32_e32 v248, v52, v52
	v_fmac_f32_e32 v248, v53, v53
	v_mul_f32_e32 v249, v54, v54
	v_fmac_f32_e32 v249, v55, v55
	v_add_f32_e32 v248, v248, v249
	v_add_f32_e32 v245, v245, v248
	v_mul_f32_e32 v248, v8, v8
	v_fmac_f32_e32 v248, v9, v9
	v_mul_f32_e32 v249, v10, v10
	v_fmac_f32_e32 v249, v11, v11
	v_add_f32_e32 v246, v248, v249
	v_mul_f32_e32 v248, v24, v24
	v_fmac_f32_e32 v248, v25, v25
	v_mul_f32_e32 v249, v26, v26
	v_fmac_f32_e32 v249, v27, v27
	v_add_f32_e32 v248, v248, v249
	v_add_f32_e32 v246, v246, v248
	v_mul_f32_e32 v248, v40, v40
	v_fmac_f32_e32 v248, v41, v41
	v_mul_f32_e32 v249, v42, v42
	v_fmac_f32_e32 v249, v43, v43
	v_add_f32_e32 v248, v248, v249
	v_add_f32_e32 v246, v246, v248
	v_mul_f32_e32 v248, v56, v56
	v_fmac_f32_e32 v248, v57, v57
	v_mul_f32_e32 v249, v58, v58
	v_fmac_f32_e32 v249, v59, v59
	v_add_f32_e32 v248, v248, v249
	v_add_f32_e32 v246, v246, v248
	v_mul_f32_e32 v248, v12, v12
	v_fmac_f32_e32 v248, v13, v13
	v_mul_f32_e32 v249, v14, v14
	v_fmac_f32_e32 v249, v15, v15
	v_add_f32_e32 v247, v248, v249
	v_mul_f32_e32 v248, v28, v28
	v_fmac_f32_e32 v248, v29, v29
	v_mul_f32_e32 v249, v30, v30
	v_fmac_f32_e32 v249, v31, v31
	v_add_f32_e32 v248, v248, v249
	v_add_f32_e32 v247, v247, v248
	v_mul_f32_e32 v248, v44, v44
	v_fmac_f32_e32 v248, v45, v45
	v_mul_f32_e32 v249, v46, v46
	v_fmac_f32_e32 v249, v47, v47
	v_add_f32_e32 v248, v248, v249
	v_add_f32_e32 v247, v247, v248
	v_mul_f32_e32 v248, v60, v60
	v_fmac_f32_e32 v248, v61, v61
	v_mul_f32_e32 v249, v62, v62
	v_fmac_f32_e32 v249, v63, v63
	v_add_f32_e32 v248, v248, v249
	v_add_f32_e32 v247, v247, v248
	v_mbcnt_hi_u32_b32 v250, -1, v254
	v_xor_b32_e32 v251, 32, v250
	v_xor_b32_e32 v250, 16, v250
	v_lshlrev_b32_e32 v250, 2, v250
	v_lshlrev_b32_e32 v251, 2, v251
	ds_bpermute_b32 v248, v250, v244
	ds_bpermute_b32 v249, v250, v245
	ds_bpermute_b32 v252, v250, v246
	ds_bpermute_b32 v253, v250, v247
	s_waitcnt lgkmcnt(0)
	v_add_f32_e32 v244, v244, v248
	v_add_f32_e32 v245, v245, v249
	v_add_f32_e32 v246, v246, v252
	v_add_f32_e32 v247, v247, v253
	ds_bpermute_b32 v248, v251, v244
	ds_bpermute_b32 v249, v251, v245
	ds_bpermute_b32 v252, v251, v246
	ds_bpermute_b32 v253, v251, v247
	s_waitcnt lgkmcnt(0)
	v_add_f32_e32 v244, v244, v248
	v_add_f32_e32 v245, v245, v249
	v_add_f32_e32 v246, v246, v252
	v_add_f32_e32 v247, v247, v253
	v_mbcnt_hi_u32_b32 v250, -1, v254
	v_and_b32_e32 v250, 15, v250
	v_lshlrev_b32_e32 v250, 5, v250
	s_lshl_b32 s26, s8, 2
	v_add_u32_e32 v251, s26, v250
	s_mov_b64 exec, 0xffff
	ds_write_b32 v251, v244 offset:9216
	ds_write_b32 v251, v245 offset:9728
	ds_write_b32 v251, v246 offset:10240
	ds_write_b32 v251, v247 offset:10752
	s_mov_b64 exec, -1
	s_waitcnt lgkmcnt(0)
	s_barrier
; #define LAS __attribute__((address_space(3)))
; __device__ __forceinline__ float bf_lo(unsigned w) { return __uint_as_float(w << 16); }
; __device__ __forceinline__ float bf_hi(unsigned w) { return __uint_as_float(w & 0xffff0000u); }
; __device__ __forceinline__ unsigned pk2(float lo, float hi) { return pg8::cvt_pk_bf16(lo, hi); }
; __device__ __forceinline__ float sigmoidf_(float x) { return __builtin_amdgcn_rcpf(1.f + __expf(-x)); }
; __device__ __forceinline__ void ph_g3(Frame& F) {
;     ...
;         const unsigned char* rb = zc + (ZR + h * DV + 64 * w) * 2; unsigned char* bb = (unsigned char*)F.out + OY_BR + ((size_t)ci * 64 * DM + h * DV + 64 * w) * 2;
; #pragma unroll
;         for (int a = 0; a < 4; ++a) { const int t = 16 * a + fr; const LAS f32x4* rp = (const LAS f32x4*)(red + t * 8); const f32x4 r0 = rp[0], r1 = rp[1];
;             const float rstd = rsqrtf(((r0.x + r0.y) + (r0.z + r0.w) + (r1.x + r1.y) + (r1.z + r1.w)) * (1.f / DV) + EPS);
; #pragma unroll
;             for (int n = 0; n < 4; ++n) { const int dvl = 16 * n + 4 * fq; const f32x4 gg = *(const f32x4*)(F.in[I_GGLA] + 64 * w + dvl);
;                 const v2u rw = *(const v2u*)(rb + (size_t)t * ZS_LD * 2 + dvl * 2); const float rr[4] = {bf_lo(rw.x), bf_hi(rw.x), bf_lo(rw.y), bf_hi(rw.y)}; float o[4];
; #pragma unroll
;                 for (int i = 0; i < 4; ++i) o[i] = acc[n][a][i] * rstd * gg[i] * (rr[i] * sigmoidf_(rr[i]));
;                 v2u ow; ow.x = pk2(o[0], o[1]); ow.y = pk2(o[2], o[3]); *(v2u*)(bb + (size_t)t * DM * 2 + dvl * 2) = ow; } }
	v_mbcnt_hi_u32_b32 v252, -1, v254
	v_and_b32_e32 v253, 15, v252
	v_lshrrev_b32_e32 v252, 4, v252
	v_lshlrev_b32_e32 v253, 13, v253
	v_lshl_add_u32 v252, v252, 3, v253
	v_mbcnt_hi_u32_b32 v250, -1, v254
	v_and_b32_e32 v250, 15, v250
	v_lshlrev_b32_e32 v250, 5, v250
	ds_read_b128 v[244:247], v250 offset:9216
	ds_read_b128 v[248:251], v250 offset:9232
	s_waitcnt lgkmcnt(0)
	v_add_f32_e32 v244, v244, v245
	v_add_f32_e32 v246, v246, v247
	v_add_f32_e32 v248, v248, v249
	v_add_f32_e32 v253, v250, v251
	v_add_f32_e32 v244, v244, v246
	v_add_f32_e32 v244, v244, v248
	v_add_f32_e32 v244, v244, v253
	v_mul_f32_e32 v244, 0x3b000000, v244
	v_add_f32_e32 v244, 0x358637bd, v244
	v_rsq_f32_e32 v243, v244
	v_lshlrev_b32_e32 v244, 16, v192
	v_and_b32_e32 v245, 0xffff0000, v192
	v_lshlrev_b32_e32 v246, 16, v193
	v_and_b32_e32 v247, 0xffff0000, v193
	v_mul_f32_e32 v248, 0xbfb8aa3b, v244
	v_mul_f32_e32 v249, 0xbfb8aa3b, v245
	v_mul_f32_e32 v250, 0xbfb8aa3b, v246
	v_mul_f32_e32 v251, 0xbfb8aa3b, v247
	v_exp_f32_e32 v248, v248
	v_exp_f32_e32 v249, v249
	v_exp_f32_e32 v250, v250
	v_exp_f32_e32 v251, v251
	v_mul_f32_e32 v0, v0, v243
	v_mul_f32_e32 v1, v1, v243
	v_mul_f32_e32 v2, v2, v243
	v_mul_f32_e32 v3, v3, v243
	v_add_f32_e32 v248, 1.0, v248
	v_add_f32_e32 v249, 1.0, v249
	v_add_f32_e32 v250, 1.0, v250
	v_add_f32_e32 v251, 1.0, v251
	v_rcp_f32_e32 v248, v248
	v_rcp_f32_e32 v249, v249
	v_rcp_f32_e32 v250, v250
	v_rcp_f32_e32 v251, v251
	v_mul_f32_e32 v0, v224, v0
	v_mul_f32_e32 v1, v225, v1
	v_mul_f32_e32 v2, v226, v2
	v_mul_f32_e32 v3, v227, v3
	v_mul_f32_e32 v248, v248, v244
	v_mul_f32_e32 v249, v249, v245
	v_mul_f32_e32 v250, v250, v246
	v_mul_f32_e32 v251, v251, v247
	v_mul_f32_e32 v0, v248, v0
	v_mul_f32_e32 v1, v249, v1
	v_mul_f32_e32 v2, v250, v2
	v_mul_f32_e32 v3, v251, v3
	v_cvt_pk_bf16_f32 v244, v0, v1
	v_cvt_pk_bf16_f32 v245, v2, v3
	global_store_dwordx2 v252, v[244:245], s[20:21]
	v_lshlrev_b32_e32 v244, 16, v194
	v_and_b32_e32 v245, 0xffff0000, v194
	v_lshlrev_b32_e32 v246, 16, v195
	v_and_b32_e32 v247, 0xffff0000, v195
	v_mul_f32_e32 v248, 0xbfb8aa3b, v244
	v_mul_f32_e32 v249, 0xbfb8aa3b, v245
	v_mul_f32_e32 v250, 0xbfb8aa3b, v246
	v_mul_f32_e32 v251, 0xbfb8aa3b, v247
	v_exp_f32_e32 v248, v248
	v_exp_f32_e32 v249, v249
	v_exp_f32_e32 v250, v250
	v_exp_f32_e32 v251, v251
	v_mul_f32_e32 v16, v16, v243
	v_mul_f32_e32 v17, v17, v243
	v_mul_f32_e32 v18, v18, v243
	v_mul_f32_e32 v19, v19, v243
	v_add_f32_e32 v248, 1.0, v248
	v_add_f32_e32 v249, 1.0, v249
	v_add_f32_e32 v250, 1.0, v250
	v_add_f32_e32 v251, 1.0, v251
	v_rcp_f32_e32 v248, v248
	v_rcp_f32_e32 v249, v249
	v_rcp_f32_e32 v250, v250
	v_rcp_f32_e32 v251, v251
	v_mul_f32_e32 v16, v228, v16
	v_mul_f32_e32 v17, v229, v17
	v_mul_f32_e32 v18, v230, v18
	v_mul_f32_e32 v19, v231, v19
	v_mul_f32_e32 v248, v248, v244
	v_mul_f32_e32 v249, v249, v245
	v_mul_f32_e32 v250, v250, v246
	v_mul_f32_e32 v251, v251, v247
	v_mul_f32_e32 v16, v248, v16
	v_mul_f32_e32 v17, v249, v17
	v_mul_f32_e32 v18, v250, v18
	v_mul_f32_e32 v19, v251, v19
	v_cvt_pk_bf16_f32 v244, v16, v17
	v_cvt_pk_bf16_f32 v245, v18, v19
	global_store_dwordx2 v252, v[244:245], s[20:21] offset:32
	v_lshlrev_b32_e32 v244, 16, v196
	v_and_b32_e32 v245, 0xffff0000, v196
	v_lshlrev_b32_e32 v246, 16, v197
	v_and_b32_e32 v247, 0xffff0000, v197
	v_mul_f32_e32 v248, 0xbfb8aa3b, v244
	v_mul_f32_e32 v249, 0xbfb8aa3b, v245
	v_mul_f32_e32 v250, 0xbfb8aa3b, v246
	v_mul_f32_e32 v251, 0xbfb8aa3b, v247
	v_exp_f32_e32 v248, v248
	v_exp_f32_e32 v249, v249
	v_exp_f32_e32 v250, v250
	v_exp_f32_e32 v251, v251
	v_mul_f32_e32 v32, v32, v243
	v_mul_f32_e32 v33, v33, v243
	v_mul_f32_e32 v34, v34, v243
	v_mul_f32_e32 v35, v35, v243
	v_add_f32_e32 v248, 1.0, v248
	v_add_f32_e32 v249, 1.0, v249
	v_add_f32_e32 v250, 1.0, v250
	v_add_f32_e32 v251, 1.0, v251
	v_rcp_f32_e32 v248, v248
	v_rcp_f32_e32 v249, v249
	v_rcp_f32_e32 v250, v250
	v_rcp_f32_e32 v251, v251
	v_mul_f32_e32 v32, v232, v32
	v_mul_f32_e32 v33, v233, v33
	v_mul_f32_e32 v34, v234, v34
	v_mul_f32_e32 v35, v235, v35
	v_mul_f32_e32 v248, v248, v244
	v_mul_f32_e32 v249, v249, v245
	v_mul_f32_e32 v250, v250, v246
	v_mul_f32_e32 v251, v251, v247
	v_mul_f32_e32 v32, v248, v32
	v_mul_f32_e32 v33, v249, v33
	v_mul_f32_e32 v34, v250, v34
	v_mul_f32_e32 v35, v251, v35
	v_cvt_pk_bf16_f32 v244, v32, v33
	v_cvt_pk_bf16_f32 v245, v34, v35
	global_store_dwordx2 v252, v[244:245], s[20:21] offset:64
	v_lshlrev_b32_e32 v244, 16, v198
	v_and_b32_e32 v245, 0xffff0000, v198
	v_lshlrev_b32_e32 v246, 16, v199
	v_and_b32_e32 v247, 0xffff0000, v199
	v_mul_f32_e32 v248, 0xbfb8aa3b, v244
	v_mul_f32_e32 v249, 0xbfb8aa3b, v245
	v_mul_f32_e32 v250, 0xbfb8aa3b, v246
	v_mul_f32_e32 v251, 0xbfb8aa3b, v247
	v_exp_f32_e32 v248, v248
	v_exp_f32_e32 v249, v249
	v_exp_f32_e32 v250, v250
	v_exp_f32_e32 v251, v251
	v_mul_f32_e32 v48, v48, v243
	v_mul_f32_e32 v49, v49, v243
	v_mul_f32_e32 v50, v50, v243
	v_mul_f32_e32 v51, v51, v243
	v_add_f32_e32 v248, 1.0, v248
	v_add_f32_e32 v249, 1.0, v249
	v_add_f32_e32 v250, 1.0, v250
	v_add_f32_e32 v251, 1.0, v251
	v_rcp_f32_e32 v248, v248
	v_rcp_f32_e32 v249, v249
	v_rcp_f32_e32 v250, v250
	v_rcp_f32_e32 v251, v251
	v_mul_f32_e32 v48, v236, v48
	v_mul_f32_e32 v49, v237, v49
	v_mul_f32_e32 v50, v238, v50
	v_mul_f32_e32 v51, v239, v51
	v_mul_f32_e32 v248, v248, v244
	v_mul_f32_e32 v249, v249, v245
	v_mul_f32_e32 v250, v250, v246
	v_mul_f32_e32 v251, v251, v247
	v_mul_f32_e32 v48, v248, v48
	v_mul_f32_e32 v49, v249, v49
	v_mul_f32_e32 v50, v250, v50
	v_mul_f32_e32 v51, v251, v51
	v_cvt_pk_bf16_f32 v244, v48, v49
	v_cvt_pk_bf16_f32 v245, v50, v51
	global_store_dwordx2 v252, v[244:245], s[20:21] offset:96
	v_mbcnt_hi_u32_b32 v250, -1, v254
	v_and_b32_e32 v250, 15, v250
	v_lshlrev_b32_e32 v250, 5, v250
	ds_read_b128 v[244:247], v250 offset:9728
	ds_read_b128 v[248:251], v250 offset:9744
	s_add_u32 s4, s20, 0x20000
	s_addc_u32 s5, s21, 0
	s_waitcnt lgkmcnt(0)
; #define LAS __attribute__((address_space(3)))
; __device__ __forceinline__ float bf_lo(unsigned w) { return __uint_as_float(w << 16); }
; __device__ __forceinline__ float bf_hi(unsigned w) { return __uint_as_float(w & 0xffff0000u); }
; __device__ __forceinline__ unsigned pk2(float lo, float hi) { return pg8::cvt_pk_bf16(lo, hi); }
; __device__ __forceinline__ float sigmoidf_(float x) { return __builtin_amdgcn_rcpf(1.f + __expf(-x)); }
; __device__ __forceinline__ void ph_g3(Frame& F) {
;     ...
; #pragma unroll
;         for (int a = 0; a < 4; ++a) { const int t = 16 * a + fr; const LAS f32x4* rp = (const LAS f32x4*)(red + t * 8); const f32x4 r0 = rp[0], r1 = rp[1];
;             const float rstd = rsqrtf(((r0.x + r0.y) + (r0.z + r0.w) + (r1.x + r1.y) + (r1.z + r1.w)) * (1.f / DV) + EPS);
; #pragma unroll
;             for (int n = 0; n < 4; ++n) { const int dvl = 16 * n + 4 * fq; const f32x4 gg = *(const f32x4*)(F.in[I_GGLA] + 64 * w + dvl);
;                 const v2u rw = *(const v2u*)(rb + (size_t)t * ZS_LD * 2 + dvl * 2); const float rr[4] = {bf_lo(rw.x), bf_hi(rw.x), bf_lo(rw.y), bf_hi(rw.y)}; float o[4];
; #pragma unroll
;                 for (int i = 0; i < 4; ++i) o[i] = acc[n][a][i] * rstd * gg[i] * (rr[i] * sigmoidf_(rr[i]));
;                 v2u ow; ow.x = pk2(o[0], o[1]); ow.y = pk2(o[2], o[3]); *(v2u*)(bb + (size_t)t * DM * 2 + dvl * 2) = ow; } }
	v_add_f32_e32 v244, v244, v245
	v_add_f32_e32 v246, v246, v247
	v_add_f32_e32 v248, v248, v249
	v_add_f32_e32 v253, v250, v251
	v_add_f32_e32 v244, v244, v246
	v_add_f32_e32 v244, v244, v248
	v_add_f32_e32 v244, v244, v253
	v_mul_f32_e32 v244, 0x3b000000, v244
	v_add_f32_e32 v244, 0x358637bd, v244
	v_rsq_f32_e32 v243, v244
	v_lshlrev_b32_e32 v244, 16, v200
	v_and_b32_e32 v245, 0xffff0000, v200
	v_lshlrev_b32_e32 v246, 16, v201
	v_and_b32_e32 v247, 0xffff0000, v201
	v_mul_f32_e32 v248, 0xbfb8aa3b, v244
	v_mul_f32_e32 v249, 0xbfb8aa3b, v245
	v_mul_f32_e32 v250, 0xbfb8aa3b, v246
	v_mul_f32_e32 v251, 0xbfb8aa3b, v247
	v_exp_f32_e32 v248, v248
	v_exp_f32_e32 v249, v249
	v_exp_f32_e32 v250, v250
	v_exp_f32_e32 v251, v251
	v_mul_f32_e32 v4, v4, v243
	v_mul_f32_e32 v5, v5, v243
	v_mul_f32_e32 v6, v6, v243
	v_mul_f32_e32 v7, v7, v243
	v_add_f32_e32 v248, 1.0, v248
	v_add_f32_e32 v249, 1.0, v249
	v_add_f32_e32 v250, 1.0, v250
	v_add_f32_e32 v251, 1.0, v251
	v_rcp_f32_e32 v248, v248
	v_rcp_f32_e32 v249, v249
	v_rcp_f32_e32 v250, v250
	v_rcp_f32_e32 v251, v251
	v_mul_f32_e32 v4, v224, v4
	v_mul_f32_e32 v5, v225, v5
	v_mul_f32_e32 v6, v226, v6
	v_mul_f32_e32 v7, v227, v7
	v_mul_f32_e32 v248, v248, v244
	v_mul_f32_e32 v249, v249, v245
	v_mul_f32_e32 v250, v250, v246
	v_mul_f32_e32 v251, v251, v247
	v_mul_f32_e32 v4, v248, v4
	v_mul_f32_e32 v5, v249, v5
	v_mul_f32_e32 v6, v250, v6
	v_mul_f32_e32 v7, v251, v7
	v_cvt_pk_bf16_f32 v244, v4, v5
	v_cvt_pk_bf16_f32 v245, v6, v7
	global_store_dwordx2 v252, v[244:245], s[4:5]
	v_lshlrev_b32_e32 v244, 16, v202
	v_and_b32_e32 v245, 0xffff0000, v202
	v_lshlrev_b32_e32 v246, 16, v203
	v_and_b32_e32 v247, 0xffff0000, v203
	v_mul_f32_e32 v248, 0xbfb8aa3b, v244
	v_mul_f32_e32 v249, 0xbfb8aa3b, v245
	v_mul_f32_e32 v250, 0xbfb8aa3b, v246
	v_mul_f32_e32 v251, 0xbfb8aa3b, v247
	v_exp_f32_e32 v248, v248
	v_exp_f32_e32 v249, v249
	v_exp_f32_e32 v250, v250
	v_exp_f32_e32 v251, v251
	v_mul_f32_e32 v20, v20, v243
	v_mul_f32_e32 v21, v21, v243
	v_mul_f32_e32 v22, v22, v243
	v_mul_f32_e32 v23, v23, v243
	v_add_f32_e32 v248, 1.0, v248
	v_add_f32_e32 v249, 1.0, v249
	v_add_f32_e32 v250, 1.0, v250
	v_add_f32_e32 v251, 1.0, v251
	v_rcp_f32_e32 v248, v248
	v_rcp_f32_e32 v249, v249
	v_rcp_f32_e32 v250, v250
	v_rcp_f32_e32 v251, v251
	v_mul_f32_e32 v20, v228, v20
	v_mul_f32_e32 v21, v229, v21
	v_mul_f32_e32 v22, v230, v22
	v_mul_f32_e32 v23, v231, v23
	v_mul_f32_e32 v248, v248, v244
	v_mul_f32_e32 v249, v249, v245
	v_mul_f32_e32 v250, v250, v246
	v_mul_f32_e32 v251, v251, v247
	v_mul_f32_e32 v20, v248, v20
	v_mul_f32_e32 v21, v249, v21
	v_mul_f32_e32 v22, v250, v22
	v_mul_f32_e32 v23, v251, v23
	v_cvt_pk_bf16_f32 v244, v20, v21
	v_cvt_pk_bf16_f32 v245, v22, v23
	global_store_dwordx2 v252, v[244:245], s[4:5] offset:32
	v_lshlrev_b32_e32 v244, 16, v204
	v_and_b32_e32 v245, 0xffff0000, v204
	v_lshlrev_b32_e32 v246, 16, v205
	v_and_b32_e32 v247, 0xffff0000, v205
	v_mul_f32_e32 v248, 0xbfb8aa3b, v244
	v_mul_f32_e32 v249, 0xbfb8aa3b, v245
	v_mul_f32_e32 v250, 0xbfb8aa3b, v246
	v_mul_f32_e32 v251, 0xbfb8aa3b, v247
	v_exp_f32_e32 v248, v248
	v_exp_f32_e32 v249, v249
	v_exp_f32_e32 v250, v250
	v_exp_f32_e32 v251, v251
	v_mul_f32_e32 v36, v36, v243
	v_mul_f32_e32 v37, v37, v243
	v_mul_f32_e32 v38, v38, v243
	v_mul_f32_e32 v39, v39, v243
	v_add_f32_e32 v248, 1.0, v248
	v_add_f32_e32 v249, 1.0, v249
	v_add_f32_e32 v250, 1.0, v250
	v_add_f32_e32 v251, 1.0, v251
	v_rcp_f32_e32 v248, v248
	v_rcp_f32_e32 v249, v249
	v_rcp_f32_e32 v250, v250
	v_rcp_f32_e32 v251, v251
	v_mul_f32_e32 v36, v232, v36
	v_mul_f32_e32 v37, v233, v37
	v_mul_f32_e32 v38, v234, v38
	v_mul_f32_e32 v39, v235, v39
	v_mul_f32_e32 v248, v248, v244
	v_mul_f32_e32 v249, v249, v245
	v_mul_f32_e32 v250, v250, v246
	v_mul_f32_e32 v251, v251, v247
	v_mul_f32_e32 v36, v248, v36
	v_mul_f32_e32 v37, v249, v37
	v_mul_f32_e32 v38, v250, v38
	v_mul_f32_e32 v39, v251, v39
	v_cvt_pk_bf16_f32 v244, v36, v37
	v_cvt_pk_bf16_f32 v245, v38, v39
	global_store_dwordx2 v252, v[244:245], s[4:5] offset:64
	v_lshlrev_b32_e32 v244, 16, v206
	v_and_b32_e32 v245, 0xffff0000, v206
	v_lshlrev_b32_e32 v246, 16, v207
	v_and_b32_e32 v247, 0xffff0000, v207
	v_mul_f32_e32 v248, 0xbfb8aa3b, v244
	v_mul_f32_e32 v249, 0xbfb8aa3b, v245
	v_mul_f32_e32 v250, 0xbfb8aa3b, v246
	v_mul_f32_e32 v251, 0xbfb8aa3b, v247
	v_exp_f32_e32 v248, v248
	v_exp_f32_e32 v249, v249
	v_exp_f32_e32 v250, v250
	v_exp_f32_e32 v251, v251
	v_mul_f32_e32 v52, v52, v243
	v_mul_f32_e32 v53, v53, v243
	v_mul_f32_e32 v54, v54, v243
	v_mul_f32_e32 v55, v55, v243
	v_add_f32_e32 v248, 1.0, v248
	v_add_f32_e32 v249, 1.0, v249
	v_add_f32_e32 v250, 1.0, v250
	v_add_f32_e32 v251, 1.0, v251
	v_rcp_f32_e32 v248, v248
	v_rcp_f32_e32 v249, v249
	v_rcp_f32_e32 v250, v250
	v_rcp_f32_e32 v251, v251
	v_mul_f32_e32 v52, v236, v52
	v_mul_f32_e32 v53, v237, v53
	v_mul_f32_e32 v54, v238, v54
	v_mul_f32_e32 v55, v239, v55
	v_mul_f32_e32 v248, v248, v244
	v_mul_f32_e32 v249, v249, v245
	v_mul_f32_e32 v250, v250, v246
	v_mul_f32_e32 v251, v251, v247
	v_mul_f32_e32 v52, v248, v52
	v_mul_f32_e32 v53, v249, v53
	v_mul_f32_e32 v54, v250, v54
	v_mul_f32_e32 v55, v251, v55
	v_cvt_pk_bf16_f32 v244, v52, v53
	v_cvt_pk_bf16_f32 v245, v54, v55
	global_store_dwordx2 v252, v[244:245], s[4:5] offset:96
	v_mbcnt_hi_u32_b32 v250, -1, v254
	v_and_b32_e32 v250, 15, v250
	v_lshlrev_b32_e32 v250, 5, v250
	ds_read_b128 v[244:247], v250 offset:10240
	ds_read_b128 v[248:251], v250 offset:10256
	s_add_u32 s4, s20, 0x40000
	s_addc_u32 s5, s21, 0
	s_waitcnt lgkmcnt(0)
; #define LAS __attribute__((address_space(3)))
; __device__ __forceinline__ float bf_lo(unsigned w) { return __uint_as_float(w << 16); }
; __device__ __forceinline__ float bf_hi(unsigned w) { return __uint_as_float(w & 0xffff0000u); }
; __device__ __forceinline__ unsigned pk2(float lo, float hi) { return pg8::cvt_pk_bf16(lo, hi); }
; __device__ __forceinline__ float sigmoidf_(float x) { return __builtin_amdgcn_rcpf(1.f + __expf(-x)); }
; __device__ __forceinline__ void ph_g3(Frame& F) {
;     ...
; #pragma unroll
;         for (int a = 0; a < 4; ++a) { const int t = 16 * a + fr; const LAS f32x4* rp = (const LAS f32x4*)(red + t * 8); const f32x4 r0 = rp[0], r1 = rp[1];
;             const float rstd = rsqrtf(((r0.x + r0.y) + (r0.z + r0.w) + (r1.x + r1.y) + (r1.z + r1.w)) * (1.f / DV) + EPS);
; #pragma unroll
;             for (int n = 0; n < 4; ++n) { const int dvl = 16 * n + 4 * fq; const f32x4 gg = *(const f32x4*)(F.in[I_GGLA] + 64 * w + dvl);
;                 const v2u rw = *(const v2u*)(rb + (size_t)t * ZS_LD * 2 + dvl * 2); const float rr[4] = {bf_lo(rw.x), bf_hi(rw.x), bf_lo(rw.y), bf_hi(rw.y)}; float o[4];
; #pragma unroll
;                 for (int i = 0; i < 4; ++i) o[i] = acc[n][a][i] * rstd * gg[i] * (rr[i] * sigmoidf_(rr[i]));
;                 v2u ow; ow.x = pk2(o[0], o[1]); ow.y = pk2(o[2], o[3]); *(v2u*)(bb + (size_t)t * DM * 2 + dvl * 2) = ow; } }
	v_add_f32_e32 v244, v244, v245
	v_add_f32_e32 v246, v246, v247
	v_add_f32_e32 v248, v248, v249
	v_add_f32_e32 v253, v250, v251
	v_add_f32_e32 v244, v244, v246
	v_add_f32_e32 v244, v244, v248
	v_add_f32_e32 v244, v244, v253
	v_mul_f32_e32 v244, 0x3b000000, v244
	v_add_f32_e32 v244, 0x358637bd, v244
	v_rsq_f32_e32 v243, v244
	v_lshlrev_b32_e32 v244, 16, v208
	v_and_b32_e32 v245, 0xffff0000, v208
	v_lshlrev_b32_e32 v246, 16, v209
	v_and_b32_e32 v247, 0xffff0000, v209
	v_mul_f32_e32 v248, 0xbfb8aa3b, v244
	v_mul_f32_e32 v249, 0xbfb8aa3b, v245
	v_mul_f32_e32 v250, 0xbfb8aa3b, v246
	v_mul_f32_e32 v251, 0xbfb8aa3b, v247
	v_exp_f32_e32 v248, v248
	v_exp_f32_e32 v249, v249
	v_exp_f32_e32 v250, v250
	v_exp_f32_e32 v251, v251
	v_mul_f32_e32 v8, v8, v243
	v_mul_f32_e32 v9, v9, v243
	v_mul_f32_e32 v10, v10, v243
	v_mul_f32_e32 v11, v11, v243
	v_add_f32_e32 v248, 1.0, v248
	v_add_f32_e32 v249, 1.0, v249
	v_add_f32_e32 v250, 1.0, v250
	v_add_f32_e32 v251, 1.0, v251
	v_rcp_f32_e32 v248, v248
	v_rcp_f32_e32 v249, v249
	v_rcp_f32_e32 v250, v250
	v_rcp_f32_e32 v251, v251
	v_mul_f32_e32 v8, v224, v8
	v_mul_f32_e32 v9, v225, v9
	v_mul_f32_e32 v10, v226, v10
	v_mul_f32_e32 v11, v227, v11
	v_mul_f32_e32 v248, v248, v244
	v_mul_f32_e32 v249, v249, v245
	v_mul_f32_e32 v250, v250, v246
	v_mul_f32_e32 v251, v251, v247
	v_mul_f32_e32 v8, v248, v8
	v_mul_f32_e32 v9, v249, v9
	v_mul_f32_e32 v10, v250, v10
	v_mul_f32_e32 v11, v251, v11
	v_cvt_pk_bf16_f32 v244, v8, v9
	v_cvt_pk_bf16_f32 v245, v10, v11
	global_store_dwordx2 v252, v[244:245], s[4:5]
	v_lshlrev_b32_e32 v244, 16, v210
	v_and_b32_e32 v245, 0xffff0000, v210
	v_lshlrev_b32_e32 v246, 16, v211
	v_and_b32_e32 v247, 0xffff0000, v211
	v_mul_f32_e32 v248, 0xbfb8aa3b, v244
	v_mul_f32_e32 v249, 0xbfb8aa3b, v245
	v_mul_f32_e32 v250, 0xbfb8aa3b, v246
	v_mul_f32_e32 v251, 0xbfb8aa3b, v247
	v_exp_f32_e32 v248, v248
	v_exp_f32_e32 v249, v249
	v_exp_f32_e32 v250, v250
	v_exp_f32_e32 v251, v251
	v_mul_f32_e32 v24, v24, v243
	v_mul_f32_e32 v25, v25, v243
	v_mul_f32_e32 v26, v26, v243
	v_mul_f32_e32 v27, v27, v243
	v_add_f32_e32 v248, 1.0, v248
	v_add_f32_e32 v249, 1.0, v249
	v_add_f32_e32 v250, 1.0, v250
	v_add_f32_e32 v251, 1.0, v251
	v_rcp_f32_e32 v248, v248
	v_rcp_f32_e32 v249, v249
	v_rcp_f32_e32 v250, v250
	v_rcp_f32_e32 v251, v251
	v_mul_f32_e32 v24, v228, v24
	v_mul_f32_e32 v25, v229, v25
	v_mul_f32_e32 v26, v230, v26
	v_mul_f32_e32 v27, v231, v27
	v_mul_f32_e32 v248, v248, v244
	v_mul_f32_e32 v249, v249, v245
	v_mul_f32_e32 v250, v250, v246
	v_mul_f32_e32 v251, v251, v247
	v_mul_f32_e32 v24, v248, v24
	v_mul_f32_e32 v25, v249, v25
	v_mul_f32_e32 v26, v250, v26
	v_mul_f32_e32 v27, v251, v27
	v_cvt_pk_bf16_f32 v244, v24, v25
	v_cvt_pk_bf16_f32 v245, v26, v27
	global_store_dwordx2 v252, v[244:245], s[4:5] offset:32
	v_lshlrev_b32_e32 v244, 16, v212
	v_and_b32_e32 v245, 0xffff0000, v212
	v_lshlrev_b32_e32 v246, 16, v213
	v_and_b32_e32 v247, 0xffff0000, v213
	v_mul_f32_e32 v248, 0xbfb8aa3b, v244
	v_mul_f32_e32 v249, 0xbfb8aa3b, v245
	v_mul_f32_e32 v250, 0xbfb8aa3b, v246
	v_mul_f32_e32 v251, 0xbfb8aa3b, v247
	v_exp_f32_e32 v248, v248
	v_exp_f32_e32 v249, v249
	v_exp_f32_e32 v250, v250
	v_exp_f32_e32 v251, v251
	v_mul_f32_e32 v40, v40, v243
	v_mul_f32_e32 v41, v41, v243
	v_mul_f32_e32 v42, v42, v243
	v_mul_f32_e32 v43, v43, v243
	v_add_f32_e32 v248, 1.0, v248
	v_add_f32_e32 v249, 1.0, v249
	v_add_f32_e32 v250, 1.0, v250
	v_add_f32_e32 v251, 1.0, v251
	v_rcp_f32_e32 v248, v248
	v_rcp_f32_e32 v249, v249
	v_rcp_f32_e32 v250, v250
	v_rcp_f32_e32 v251, v251
	v_mul_f32_e32 v40, v232, v40
	v_mul_f32_e32 v41, v233, v41
	v_mul_f32_e32 v42, v234, v42
	v_mul_f32_e32 v43, v235, v43
	v_mul_f32_e32 v248, v248, v244
	v_mul_f32_e32 v249, v249, v245
	v_mul_f32_e32 v250, v250, v246
	v_mul_f32_e32 v251, v251, v247
	v_mul_f32_e32 v40, v248, v40
	v_mul_f32_e32 v41, v249, v41
	v_mul_f32_e32 v42, v250, v42
	v_mul_f32_e32 v43, v251, v43
	v_cvt_pk_bf16_f32 v244, v40, v41
	v_cvt_pk_bf16_f32 v245, v42, v43
	global_store_dwordx2 v252, v[244:245], s[4:5] offset:64
	v_lshlrev_b32_e32 v244, 16, v214
	v_and_b32_e32 v245, 0xffff0000, v214
	v_lshlrev_b32_e32 v246, 16, v215
	v_and_b32_e32 v247, 0xffff0000, v215
	v_mul_f32_e32 v248, 0xbfb8aa3b, v244
	v_mul_f32_e32 v249, 0xbfb8aa3b, v245
	v_mul_f32_e32 v250, 0xbfb8aa3b, v246
	v_mul_f32_e32 v251, 0xbfb8aa3b, v247
	v_exp_f32_e32 v248, v248
	v_exp_f32_e32 v249, v249
	v_exp_f32_e32 v250, v250
	v_exp_f32_e32 v251, v251
	v_mul_f32_e32 v56, v56, v243
	v_mul_f32_e32 v57, v57, v243
	v_mul_f32_e32 v58, v58, v243
	v_mul_f32_e32 v59, v59, v243
	v_add_f32_e32 v248, 1.0, v248
	v_add_f32_e32 v249, 1.0, v249
	v_add_f32_e32 v250, 1.0, v250
	v_add_f32_e32 v251, 1.0, v251
	v_rcp_f32_e32 v248, v248
	v_rcp_f32_e32 v249, v249
	v_rcp_f32_e32 v250, v250
	v_rcp_f32_e32 v251, v251
	v_mul_f32_e32 v56, v236, v56
	v_mul_f32_e32 v57, v237, v57
	v_mul_f32_e32 v58, v238, v58
	v_mul_f32_e32 v59, v239, v59
	v_mul_f32_e32 v248, v248, v244
	v_mul_f32_e32 v249, v249, v245
	v_mul_f32_e32 v250, v250, v246
	v_mul_f32_e32 v251, v251, v247
	v_mul_f32_e32 v56, v248, v56
	v_mul_f32_e32 v57, v249, v57
	v_mul_f32_e32 v58, v250, v58
	v_mul_f32_e32 v59, v251, v59
	v_cvt_pk_bf16_f32 v244, v56, v57
	v_cvt_pk_bf16_f32 v245, v58, v59
	global_store_dwordx2 v252, v[244:245], s[4:5] offset:96
	v_mbcnt_hi_u32_b32 v250, -1, v254
	v_and_b32_e32 v250, 15, v250
	v_lshlrev_b32_e32 v250, 5, v250
	ds_read_b128 v[244:247], v250 offset:10752
	ds_read_b128 v[248:251], v250 offset:10768
	s_add_u32 s4, s20, 0x60000
	s_addc_u32 s5, s21, 0
	s_waitcnt lgkmcnt(0)
; #define LAS __attribute__((address_space(3)))
; __device__ __forceinline__ float bf_lo(unsigned w) { return __uint_as_float(w << 16); }
; __device__ __forceinline__ float bf_hi(unsigned w) { return __uint_as_float(w & 0xffff0000u); }
; __device__ __forceinline__ unsigned pk2(float lo, float hi) { return pg8::cvt_pk_bf16(lo, hi); }
; __device__ __forceinline__ float sigmoidf_(float x) { return __builtin_amdgcn_rcpf(1.f + __expf(-x)); }
; __device__ __forceinline__ void ph_g3(Frame& F) {
;     ...
;     for (int unit = F.vcu; unit < NCHK * NH; unit += F.G) {
;         const int ci = unit >> 2, h = unit & 3;
;         const unsigned char* zc = F.ws + WS_ZS + (size_t)ci * 64 * ZS_LD * 2;
;         const unsigned char* qb = zc + (ZQ + h * DK) * 2; const unsigned char* kb = zc + (ZK + h * DK) * 2;
;     ...
; #pragma unroll
;         for (int a = 0; a < 4; ++a) { const int t = 16 * a + fr; const LAS f32x4* rp = (const LAS f32x4*)(red + t * 8); const f32x4 r0 = rp[0], r1 = rp[1];
;             const float rstd = rsqrtf(((r0.x + r0.y) + (r0.z + r0.w) + (r1.x + r1.y) + (r1.z + r1.w)) * (1.f / DV) + EPS);
; #pragma unroll
;             for (int n = 0; n < 4; ++n) { const int dvl = 16 * n + 4 * fq; const f32x4 gg = *(const f32x4*)(F.in[I_GGLA] + 64 * w + dvl);
;                 const v2u rw = *(const v2u*)(rb + (size_t)t * ZS_LD * 2 + dvl * 2); const float rr[4] = {bf_lo(rw.x), bf_hi(rw.x), bf_lo(rw.y), bf_hi(rw.y)}; float o[4];
; #pragma unroll
;                 for (int i = 0; i < 4; ++i) o[i] = acc[n][a][i] * rstd * gg[i] * (rr[i] * sigmoidf_(rr[i]));
;                 v2u ow; ow.x = pk2(o[0], o[1]); ow.y = pk2(o[2], o[3]); *(v2u*)(bb + (size_t)t * DM * 2 + dvl * 2) = ow; } }
	v_add_f32_e32 v244, v244, v245
	v_add_f32_e32 v246, v246, v247
	v_add_f32_e32 v248, v248, v249
	v_add_f32_e32 v253, v250, v251
	v_add_f32_e32 v244, v244, v246
	v_add_f32_e32 v244, v244, v248
	v_add_f32_e32 v244, v244, v253
	v_mul_f32_e32 v244, 0x3b000000, v244
	v_add_f32_e32 v244, 0x358637bd, v244
	v_rsq_f32_e32 v243, v244
	v_lshlrev_b32_e32 v244, 16, v216
	v_and_b32_e32 v245, 0xffff0000, v216
	v_lshlrev_b32_e32 v246, 16, v217
	v_and_b32_e32 v247, 0xffff0000, v217
	v_mul_f32_e32 v248, 0xbfb8aa3b, v244
	v_mul_f32_e32 v249, 0xbfb8aa3b, v245
	v_mul_f32_e32 v250, 0xbfb8aa3b, v246
	v_mul_f32_e32 v251, 0xbfb8aa3b, v247
	v_exp_f32_e32 v248, v248
	v_exp_f32_e32 v249, v249
	v_exp_f32_e32 v250, v250
	v_exp_f32_e32 v251, v251
	v_mul_f32_e32 v12, v12, v243
	v_mul_f32_e32 v13, v13, v243
	v_mul_f32_e32 v14, v14, v243
	v_mul_f32_e32 v15, v15, v243
	v_add_f32_e32 v248, 1.0, v248
	v_add_f32_e32 v249, 1.0, v249
	v_add_f32_e32 v250, 1.0, v250
	v_add_f32_e32 v251, 1.0, v251
	v_rcp_f32_e32 v248, v248
	v_rcp_f32_e32 v249, v249
	v_rcp_f32_e32 v250, v250
	v_rcp_f32_e32 v251, v251
	v_mul_f32_e32 v12, v224, v12
	v_mul_f32_e32 v13, v225, v13
	v_mul_f32_e32 v14, v226, v14
	v_mul_f32_e32 v15, v227, v15
	v_mul_f32_e32 v248, v248, v244
	v_mul_f32_e32 v249, v249, v245
	v_mul_f32_e32 v250, v250, v246
	v_mul_f32_e32 v251, v251, v247
	v_mul_f32_e32 v12, v248, v12
	v_mul_f32_e32 v13, v249, v13
	v_mul_f32_e32 v14, v250, v14
	v_mul_f32_e32 v15, v251, v15
	v_cvt_pk_bf16_f32 v244, v12, v13
	v_cvt_pk_bf16_f32 v245, v14, v15
	global_store_dwordx2 v252, v[244:245], s[4:5]
	v_lshlrev_b32_e32 v244, 16, v218
	v_and_b32_e32 v245, 0xffff0000, v218
	v_lshlrev_b32_e32 v246, 16, v219
	v_and_b32_e32 v247, 0xffff0000, v219
	v_mul_f32_e32 v248, 0xbfb8aa3b, v244
	v_mul_f32_e32 v249, 0xbfb8aa3b, v245
	v_mul_f32_e32 v250, 0xbfb8aa3b, v246
	v_mul_f32_e32 v251, 0xbfb8aa3b, v247
	v_exp_f32_e32 v248, v248
	v_exp_f32_e32 v249, v249
	v_exp_f32_e32 v250, v250
	v_exp_f32_e32 v251, v251
	v_mul_f32_e32 v28, v28, v243
	v_mul_f32_e32 v29, v29, v243
	v_mul_f32_e32 v30, v30, v243
	v_mul_f32_e32 v31, v31, v243
	v_add_f32_e32 v248, 1.0, v248
	v_add_f32_e32 v249, 1.0, v249
	v_add_f32_e32 v250, 1.0, v250
	v_add_f32_e32 v251, 1.0, v251
	v_rcp_f32_e32 v248, v248
	v_rcp_f32_e32 v249, v249
	v_rcp_f32_e32 v250, v250
	v_rcp_f32_e32 v251, v251
	v_mul_f32_e32 v28, v228, v28
	v_mul_f32_e32 v29, v229, v29
	v_mul_f32_e32 v30, v230, v30
	v_mul_f32_e32 v31, v231, v31
	v_mul_f32_e32 v248, v248, v244
	v_mul_f32_e32 v249, v249, v245
	v_mul_f32_e32 v250, v250, v246
	v_mul_f32_e32 v251, v251, v247
	v_mul_f32_e32 v28, v248, v28
	v_mul_f32_e32 v29, v249, v29
	v_mul_f32_e32 v30, v250, v30
	v_mul_f32_e32 v31, v251, v31
	v_cvt_pk_bf16_f32 v244, v28, v29
	v_cvt_pk_bf16_f32 v245, v30, v31
	global_store_dwordx2 v252, v[244:245], s[4:5] offset:32
	v_lshlrev_b32_e32 v244, 16, v220
	v_and_b32_e32 v245, 0xffff0000, v220
	v_lshlrev_b32_e32 v246, 16, v221
	v_and_b32_e32 v247, 0xffff0000, v221
	v_mul_f32_e32 v248, 0xbfb8aa3b, v244
	v_mul_f32_e32 v249, 0xbfb8aa3b, v245
	v_mul_f32_e32 v250, 0xbfb8aa3b, v246
	v_mul_f32_e32 v251, 0xbfb8aa3b, v247
	v_exp_f32_e32 v248, v248
	v_exp_f32_e32 v249, v249
	v_exp_f32_e32 v250, v250
	v_exp_f32_e32 v251, v251
	v_mul_f32_e32 v44, v44, v243
	v_mul_f32_e32 v45, v45, v243
	v_mul_f32_e32 v46, v46, v243
	v_mul_f32_e32 v47, v47, v243
	v_add_f32_e32 v248, 1.0, v248
	v_add_f32_e32 v249, 1.0, v249
	v_add_f32_e32 v250, 1.0, v250
	v_add_f32_e32 v251, 1.0, v251
	v_rcp_f32_e32 v248, v248
	v_rcp_f32_e32 v249, v249
	v_rcp_f32_e32 v250, v250
	v_rcp_f32_e32 v251, v251
	v_mul_f32_e32 v44, v232, v44
	v_mul_f32_e32 v45, v233, v45
	v_mul_f32_e32 v46, v234, v46
	v_mul_f32_e32 v47, v235, v47
	v_mul_f32_e32 v248, v248, v244
	v_mul_f32_e32 v249, v249, v245
	v_mul_f32_e32 v250, v250, v246
	v_mul_f32_e32 v251, v251, v247
	v_mul_f32_e32 v44, v248, v44
	v_mul_f32_e32 v45, v249, v45
	v_mul_f32_e32 v46, v250, v46
	v_mul_f32_e32 v47, v251, v47
	v_cvt_pk_bf16_f32 v244, v44, v45
	v_cvt_pk_bf16_f32 v245, v46, v47
	global_store_dwordx2 v252, v[244:245], s[4:5] offset:64
	v_lshlrev_b32_e32 v244, 16, v222
	v_and_b32_e32 v245, 0xffff0000, v222
	v_lshlrev_b32_e32 v246, 16, v223
	v_and_b32_e32 v247, 0xffff0000, v223
	v_mul_f32_e32 v248, 0xbfb8aa3b, v244
	v_mul_f32_e32 v249, 0xbfb8aa3b, v245
	v_mul_f32_e32 v250, 0xbfb8aa3b, v246
	v_mul_f32_e32 v251, 0xbfb8aa3b, v247
	v_exp_f32_e32 v248, v248
	v_exp_f32_e32 v249, v249
	v_exp_f32_e32 v250, v250
	v_exp_f32_e32 v251, v251
	v_mul_f32_e32 v60, v60, v243
	v_mul_f32_e32 v61, v61, v243
	v_mul_f32_e32 v62, v62, v243
	v_mul_f32_e32 v63, v63, v243
	v_add_f32_e32 v248, 1.0, v248
	v_add_f32_e32 v249, 1.0, v249
	v_add_f32_e32 v250, 1.0, v250
	v_add_f32_e32 v251, 1.0, v251
	v_rcp_f32_e32 v248, v248
	v_rcp_f32_e32 v249, v249
	v_rcp_f32_e32 v250, v250
	v_rcp_f32_e32 v251, v251
	v_mul_f32_e32 v60, v236, v60
	v_mul_f32_e32 v61, v237, v61
	v_mul_f32_e32 v62, v238, v62
	v_mul_f32_e32 v63, v239, v63
	v_mul_f32_e32 v248, v248, v244
	v_mul_f32_e32 v249, v249, v245
	v_mul_f32_e32 v250, v250, v246
	v_mul_f32_e32 v251, v251, v247
	v_mul_f32_e32 v60, v248, v60
	v_mul_f32_e32 v61, v249, v61
	v_mul_f32_e32 v62, v250, v62
	v_mul_f32_e32 v63, v251, v63
	v_cvt_pk_bf16_f32 v244, v60, v61
	v_cvt_pk_bf16_f32 v245, v62, v63
	global_store_dwordx2 v252, v[244:245], s[4:5] offset:96
	s_add_i32 s6, s6, s33
	s_cmpk_lt_i32 s6, 0x480
	s_cbranch_scc0 .Lg3_done
	s_sub_u32 s28, 0x47f, s6
	s_lshr_b32 s26, s28, 2
	s_and_b32 s27, s28, 3
	s_lshl_b32 s30, s26, 20
	s_lshl_b32 s31, s27, 9
	s_add_u32 s30, s30, s31
	s_add_u32 s30, s30, 0x10400000
	s_add_u32 s12, s34, s30
	s_addc_u32 s13, s35, 0
	s_lshl_b32 s30, s28, 18
	s_mov_b32 s31, 0x100000
	s_mov_b32 s3, 0x35400000
	s_cmp_ge_u32 s28, 0x200
	s_cselect_b32 s31, s3, s31
	s_mov_b32 s3, 0xf8100000
	s_cmp_ge_u32 s28, 0x400
	s_cselect_b32 s31, s3, s31
	s_add_u32 s30, s30, s31
	s_lshl_b32 s31, s8, 15
	s_add_u32 s30, s30, s31
	s_add_u32 s14, s34, s30
	s_addc_u32 s15, s35, 0
	s_lshl_b32 s30, s28, 16
	s_lshl_b32 s31, s8, 13
	s_add_u32 s30, s30, s31
	s_add_u32 s30, s30, 0x4d400000
	s_add_u32 s16, s34, s30
	s_addc_u32 s17, s35, 0
	s_lshl_b32 s30, s27, 9
	s_lshl_b32 s31, s8, 7
	s_add_u32 s30, s30, s31
	s_add_u32 s30, s30, 0x1000
	s_add_u32 s18, s12, s30
	s_addc_u32 s19, s13, 0
	s_lshl_b32 s30, s26, 19
	s_lshl_b32 s3, s27, 10
	s_add_u32 s30, s30, s3
	s_add_u32 s30, s30, s31
	s_add_u32 s30, s30, 0x9000000
	s_add_u32 s20, s70, s30
	s_addc_u32 s21, s71, 0
	s_add_i32 s7, s6, s33
	s_cmpk_lt_i32 s7, 0x480
	s_cselect_b32 s7, s7, s6
	s_sub_u32 s28, 0x47f, s7
	s_lshr_b32 s26, s28, 2
	s_and_b32 s27, s28, 3
	s_lshl_b32 s30, s26, 20
	s_lshl_b32 s31, s27, 9
	s_add_u32 s30, s30, s31
	s_add_u32 s30, s30, 0x10400000
	s_add_u32 s22, s34, s30
	s_addc_u32 s23, s35, 0
	s_lshl_b32 s30, s28, 18
	s_mov_b32 s31, 0x100000
	s_mov_b32 s3, 0x35400000
	s_cmp_ge_u32 s28, 0x200
	s_cselect_b32 s31, s3, s31
	s_mov_b32 s3, 0xf8100000
	s_cmp_ge_u32 s28, 0x400
	s_cselect_b32 s31, s3, s31
	s_add_u32 s30, s30, s31
	s_lshl_b32 s31, s8, 15
	s_add_u32 s30, s30, s31
	s_add_u32 s24, s34, s30
	s_addc_u32 s25, s35, 0
	s_branch .Lg3_unit
; __device__ __forceinline__ int lane_id_() { return (int)__builtin_amdgcn_mbcnt_hi(~0u, __builtin_amdgcn_mbcnt_lo(~0u, 0u)); }
; __device__ __forceinline__ unsigned xb_ld(unsigned* p)              { return __hip_atomic_load(p, __ATOMIC_RELAXED, __HIP_MEMORY_SCOPE_AGENT); }
; __device__ __forceinline__ void xcd_barrier_complete(unsigned* bar, unsigned x, unsigned& nloc, unsigned& nx) {
;     const unsigned G = gridDim.x * gridDim.y * gridDim.z;
;     unsigned sum, cnt, mine, sp = 0u;
;     for (;;) {
;         sum = 0u; cnt = 0u; mine = 0u;
; #pragma unroll
;         for (unsigned j = 0; j < 16; ++j) { const unsigned c = xb_ld(&bar[XB_XCNT(j)]); sum += c; cnt += (c > 0u) ? 1u : 0u; mine = (j == x) ? c : mine; }
; __device__ __forceinline__ void xcd_barrier(const XcdBarrier& b, int wave) {
;     asm volatile("s_waitcnt vmcnt(0)" ::: "memory");
;     __syncthreads();
;     if (wave == 0 && lane_id_() == 0) {
;         unsigned* bar = b.bar;
;         __builtin_amdgcn_s_waitcnt(0);
;         unsigned nloc = b.st[0], nx = b.st[1];
;         if (nloc == 0u) { xcd_barrier_complete(bar, b.x, nloc, nx); b.st[0] = nloc; b.st[1] = nx; }
.Lg3_done:
	s_waitcnt vmcnt(0) lgkmcnt(0)
.LBB0_670:
	v_readlane_b32 s0, v255, 37
	v_readlane_b32 s1, v255, 38
	s_cmp_gt_i32 s1, 6
	s_cselect_b64 s[0:1], -1, 0
	s_and_b64 s[4:5], s[36:37], s[0:1]
	s_andn2_b64 vcc, exec, s[4:5]
	s_cbranch_vccnz .LBB0_722
	s_waitcnt vmcnt(0)
	s_cmp_gt_u32 s94, 63
	s_waitcnt vmcnt(0)
	s_barrier
	s_cbranch_scc1 .LBB0_721
	v_mbcnt_hi_u32_b32 v0, -1, v254
	v_cmp_eq_u32_e32 vcc, 0, v0
	s_and_saveexec_b64 s[4:5], vcc
	s_cbranch_execz .LBB0_720
	v_readlane_b32 s3, v255, 40
	s_waitcnt vmcnt(0) expcnt(0) lgkmcnt(0)
	s_nop 0
	v_mov_b32_e32 v0, s3
	ds_read_b32 v2, v0
	ds_read_b32 v0, v0 offset:4
	s_waitcnt lgkmcnt(1)
	v_cmp_ne_u32_e32 vcc, 0, v2
	s_cbranch_vccnz .LBB0_688
	v_readlane_b32 s6, v255, 0
	v_readlane_b32 s7, v255, 1
	s_load_dwordx2 s[10:11], s[6:7], 0x4
	s_add_u32 s6, s34, 0x4200
	s_addc_u32 s7, s35, 0
	s_add_u32 s8, s34, 0x4400
	s_addc_u32 s9, s35, 0
	s_waitcnt lgkmcnt(0)
	s_mul_i32 s3, s10, s33
	s_add_u32 s10, s34, 0x4500
	s_mul_i32 s3, s3, s11
	s_addc_u32 s11, s35, 0
	s_add_u32 s12, s34, 0x4600
	s_addc_u32 s13, s35, 0
	s_add_u32 s14, s34, 0x4700
	s_addc_u32 s15, s35, 0
	s_add_u32 s16, s34, 0x4800
	s_addc_u32 s17, s35, 0
	s_add_u32 s18, s34, 0x4900
	s_addc_u32 s19, s35, 0
	s_add_u32 s20, s34, 0x4a00
	s_addc_u32 s21, s35, 0
	s_add_u32 s22, s34, 0x4b00
	s_addc_u32 s23, s35, 0
	s_add_u32 s24, s34, 0x4c00
	s_addc_u32 s25, s35, 0
	s_add_u32 s26, s34, 0x4d00
	s_addc_u32 s27, s35, 0
	s_add_u32 s28, s34, 0x4e00
	s_addc_u32 s29, s35, 0
	s_add_u32 s30, s34, 0x4f00
	s_addc_u32 s31, s35, 0
	s_add_u32 s36, s34, 0x5000
	s_addc_u32 s37, s35, 0
	s_add_u32 s38, s34, 0x5100
	s_addc_u32 s39, s35, 0
	s_add_u32 s40, s34, 0x5200
	s_addc_u32 s41, s35, 0
	s_add_u32 s42, s34, 0x5300
	s_addc_u32 s43, s35, 0
	s_mov_b32 s44, 1
	v_mov_b32_e32 v16, 0
	s_branch .LBB0_676

; #define PG8_STAGE(bufoff, gbase, voff) do { _Pragma("unroll") for (int _i = 0; _i < 2; ++_i) \
;         __builtin_amdgcn_global_load_lds((const unsigned*)((const char*)(gbase) + (voff)[_i]), (PG8_LAS unsigned*)(lds + (bufoff) + ldsw + _i * 8192), 16, 0, 0); } while (0)
; #define PG8_LDA(dst, b, h) do { _Pragma("unroll") for (int m = 0; m < 4; ++m) _Pragma("unroll") for (int k = 0; k < 2; ++k) dst[m][k] = *(const PG8_LAS bf16x8*)(lds + PG8_SA(b, h) + aoff + m * 2048 + k * 1024); } while (0)
; #define PG8_LDB(dst, b, h) do { _Pragma("unroll") for (int n = 0; n < 2; ++n) _Pragma("unroll") for (int k = 0; k < 2; ++k) dst[n][k] = *(const PG8_LAS bf16x8*)(lds + PG8_SB(b, h) + boff + n * 2048 + k * 1024); } while (0)
; #define PG8_WAIT_V(n) asm volatile("s_waitcnt vmcnt(" #n ")" ::: "memory")
; #define PG8_WAIT_L(n) asm volatile("s_waitcnt lgkmcnt(" #n ")" ::: "memory")
; #define PG8_BAR __builtin_amdgcn_s_barrier()
; #define PG8_SCHED __builtin_amdgcn_sched_barrier(0)
; template <class Epi, class Sched, bool ALIGN_EPI = false, bool SP2 = false, bool F8 = false>
; __device__ __forceinline__ void gemm_phase(PG8_LAS unsigned char* lds, const int K, const Sched& S, const Epi& E, const int wave) {
;     ...
;             PG8_LDB(B0, 0, 0); PG8_LDB(B1, 0, 1); PG8_SCHED; PG8_LDA(At, 0, 0); PG8_STAGE(PG8_SA(1, 1), a1 + hstep, voffA);
;             PG8_WAIT_V(8); PG8_WAIT_L(0); PG8_BAR; PG8_MMA(0, 0, At, B0); PG8_MMA(0, 1, At, B1); PG8_BAR; PG8_SCHED;
;             PG8_LDA(At, 0, 1); PG8_STAGE(PG8_SB(0, 0), b2, voffB); PG8_STAGE(PG8_SB(0, 1), b2 + hstep, voffB); PG8_STAGE(PG8_SA(0, 0), a2, voffA);
;             PG8_WAIT_V(8); PG8_WAIT_L(0); PG8_BAR; PG8_MMA(1, 0, At, B0); PG8_MMA(1, 1, At, B1); PG8_BAR; PG8_SCHED;
.LBB0_763:
	v_add_u32_e32 v1, s82, v220
	ds_read_b128 v[132:135], v1
	ds_read_b128 v[136:139], v1 offset:1024
	ds_read_b128 v[140:143], v1 offset:2048
	ds_read_b128 v[144:147], v1 offset:3072
	v_add_u32_e32 v1, s75, v220
	ds_read_b128 v[148:151], v1
	ds_read_b128 v[152:155], v1 offset:1024
	ds_read_b128 v[156:159], v1 offset:2048
	ds_read_b128 v[160:163], v1 offset:3072
	s_add_i32 s9, s9, 2
	s_add_u32 s64, s64, 0x100000
	s_addc_u32 s65, s65, 0
	v_lshl_add_u64 v[2:3], s[64:65], 0, v[164:165]
	s_add_i32 m0, s87, 0xc000
	ds_read_b128 v[182:185], v222
	ds_read_b128 v[186:189], v222 offset:1024
	ds_read_b128 v[190:193], v222 offset:2048
	ds_read_b128 v[194:197], v222 offset:3072
	ds_read_b128 v[198:201], v222 offset:4096
	ds_read_b128 v[202:205], v222 offset:5120
	ds_read_b128 v[206:209], v222 offset:6144
	ds_read_b128 v[210:213], v222 offset:7168
	global_load_lds_dwordx4 v[2:3], off
	v_lshl_add_u64 v[2:3], s[64:65], 0, v[168:169]
	s_add_i32 m0, s87, 0xe000
	s_nop 0
	global_load_lds_dwordx4 v[2:3], off
	s_waitcnt vmcnt(8)
	s_waitcnt lgkmcnt(0)
	s_setprio 1
	s_barrier
	v_mfma_f32_16x16x32_bf16 v[128:131], v[132:135], v[182:185], v[128:131]
	v_mfma_f32_16x16x32_bf16 v[124:127], v[140:143], v[182:185], v[124:127]
	v_mfma_f32_16x16x32_bf16 v[120:123], v[132:135], v[190:193], v[120:123]
	v_mfma_f32_16x16x32_bf16 v[116:119], v[140:143], v[190:193], v[116:119]
	v_mfma_f32_16x16x32_bf16 v[112:115], v[132:135], v[198:201], v[112:115]
	v_mfma_f32_16x16x32_bf16 v[108:111], v[140:143], v[198:201], v[108:111]
	v_mfma_f32_16x16x32_bf16 v[104:107], v[132:135], v[206:209], v[104:107]
	v_mfma_f32_16x16x32_bf16 v[100:103], v[140:143], v[206:209], v[100:103]
	v_mfma_f32_16x16x32_bf16 v[128:131], v[136:139], v[186:189], v[128:131]
	v_mfma_f32_16x16x32_bf16 v[124:127], v[144:147], v[186:189], v[124:127]
	v_mfma_f32_16x16x32_bf16 v[120:123], v[136:139], v[194:197], v[120:123]
	v_mfma_f32_16x16x32_bf16 v[116:119], v[144:147], v[194:197], v[116:119]
	v_mfma_f32_16x16x32_bf16 v[112:115], v[136:139], v[202:205], v[112:115]
	v_mfma_f32_16x16x32_bf16 v[108:111], v[144:147], v[202:205], v[108:111]
	v_mfma_f32_16x16x32_bf16 v[104:107], v[136:139], v[210:213], v[104:107]
	v_mfma_f32_16x16x32_bf16 v[100:103], v[144:147], v[210:213], v[100:103]
	v_mfma_f32_16x16x32_bf16 v[96:99], v[148:151], v[182:185], v[96:99]
	v_mfma_f32_16x16x32_bf16 v[92:95], v[156:159], v[182:185], v[92:95]
	v_mfma_f32_16x16x32_bf16 v[88:91], v[148:151], v[190:193], v[88:91]
	v_mfma_f32_16x16x32_bf16 v[84:87], v[156:159], v[190:193], v[84:87]
	v_mfma_f32_16x16x32_bf16 v[80:83], v[148:151], v[198:201], v[80:83]
	v_mfma_f32_16x16x32_bf16 v[76:79], v[156:159], v[198:201], v[76:79]
	v_mfma_f32_16x16x32_bf16 v[72:75], v[148:151], v[206:209], v[72:75]
	v_mfma_f32_16x16x32_bf16 v[68:71], v[156:159], v[206:209], v[68:71]
	v_mfma_f32_16x16x32_bf16 v[96:99], v[152:155], v[186:189], v[96:99]
	v_mfma_f32_16x16x32_bf16 v[92:95], v[160:163], v[186:189], v[92:95]
	v_mfma_f32_16x16x32_bf16 v[88:91], v[152:155], v[194:197], v[88:91]
	v_mfma_f32_16x16x32_bf16 v[84:87], v[160:163], v[194:197], v[84:87]
	v_mfma_f32_16x16x32_bf16 v[80:83], v[152:155], v[202:205], v[80:83]
	v_mfma_f32_16x16x32_bf16 v[76:79], v[160:163], v[202:205], v[76:79]
	v_mfma_f32_16x16x32_bf16 v[72:75], v[152:155], v[210:213], v[72:75]
	v_mfma_f32_16x16x32_bf16 v[68:71], v[160:163], v[210:213], v[68:71]
	s_barrier
	s_setprio 0
	s_add_i32 s64, s82, s86
	v_lshl_add_u64 v[2:3], s[62:63], 0, v[166:167]
	s_mov_b32 m0, s64
	ds_read_b128 v[182:185], v222 offset:16384
	ds_read_b128 v[186:189], v222 offset:17408
	ds_read_b128 v[190:193], v222 offset:18432
	ds_read_b128 v[194:197], v222 offset:19456
	ds_read_b128 v[198:201], v222 offset:20480
	ds_read_b128 v[202:205], v222 offset:21504
	ds_read_b128 v[206:209], v222 offset:22528
	ds_read_b128 v[210:213], v222 offset:23552
	global_load_lds_dwordx4 v[2:3], off
	s_add_i32 m0, s64, 0x2000
	v_lshl_add_u64 v[2:3], s[62:63], 0, v[170:171]
	s_add_u32 s62, s62, 0x100000
	s_addc_u32 s63, s63, 0
	s_add_i32 s64, s75, s86
	global_load_lds_dwordx4 v[2:3], off
	v_lshl_add_u64 v[2:3], s[62:63], 0, v[166:167]
	s_mov_b32 m0, s64
	s_nop 0
	global_load_lds_dwordx4 v[2:3], off
	v_lshl_add_u64 v[2:3], s[62:63], 0, v[170:171]
	s_add_i32 m0, s64, 0x2000
	s_nop 0
	global_load_lds_dwordx4 v[2:3], off
	v_lshl_add_u64 v[2:3], s[60:61], 0, v[164:165]
	s_mov_b32 m0, s87
	s_nop 0
	global_load_lds_dwordx4 v[2:3], off
	v_lshl_add_u64 v[2:3], s[60:61], 0, v[168:169]
	s_mov_b32 m0, s88
	s_nop 0
	global_load_lds_dwordx4 v[2:3], off
	s_waitcnt vmcnt(8)
	s_waitcnt lgkmcnt(0)
	s_setprio 1
	s_barrier
; #define PG8_STAGE(bufoff, gbase, voff) do { _Pragma("unroll") for (int _i = 0; _i < 2; ++_i) \
;         __builtin_amdgcn_global_load_lds((const unsigned*)((const char*)(gbase) + (voff)[_i]), (PG8_LAS unsigned*)(lds + (bufoff) + ldsw + _i * 8192), 16, 0, 0); } while (0)
; #define PG8_LDA(dst, b, h) do { _Pragma("unroll") for (int m = 0; m < 4; ++m) _Pragma("unroll") for (int k = 0; k < 2; ++k) dst[m][k] = *(const PG8_LAS bf16x8*)(lds + PG8_SA(b, h) + aoff + m * 2048 + k * 1024); } while (0)
; #define PG8_LDB(dst, b, h) do { _Pragma("unroll") for (int n = 0; n < 2; ++n) _Pragma("unroll") for (int k = 0; k < 2; ++k) dst[n][k] = *(const PG8_LAS bf16x8*)(lds + PG8_SB(b, h) + boff + n * 2048 + k * 1024); } while (0)
; #define PG8_WAIT_V(n) asm volatile("s_waitcnt vmcnt(" #n ")" ::: "memory")
; #define PG8_WAIT_L(n) asm volatile("s_waitcnt lgkmcnt(" #n ")" ::: "memory")
; #define PG8_BAR __builtin_amdgcn_s_barrier()
; #define PG8_SCHED __builtin_amdgcn_sched_barrier(0)
; template <class Epi, class Sched, bool ALIGN_EPI = false, bool SP2 = false, bool F8 = false>
; __device__ __forceinline__ void gemm_phase(PG8_LAS unsigned char* lds, const int K, const Sched& S, const Epi& E, const int wave) {
;     ...
;             PG8_WAIT_V(8); PG8_WAIT_L(0); PG8_BAR; PG8_MMA(1, 0, At, B0); PG8_MMA(1, 1, At, B1); PG8_BAR; PG8_SCHED;
;             PG8_LDB(B0, 1, 0); PG8_LDB(B1, 1, 1); PG8_SCHED; PG8_LDA(At, 1, 0); PG8_STAGE(PG8_SA(0, 1), a2 + hstep, voffA);
;             PG8_WAIT_V(8); PG8_WAIT_L(0); PG8_BAR; PG8_MMA(0, 0, At, B0); PG8_MMA(0, 1, At, B1); PG8_BAR; PG8_SCHED;
	v_mfma_f32_16x16x32_bf16 v[64:67], v[132:135], v[182:185], v[64:67]
	v_mfma_f32_16x16x32_bf16 v[60:63], v[140:143], v[182:185], v[60:63]
	v_mfma_f32_16x16x32_bf16 v[56:59], v[132:135], v[190:193], v[56:59]
	v_mfma_f32_16x16x32_bf16 v[52:55], v[140:143], v[190:193], v[52:55]
	v_mfma_f32_16x16x32_bf16 v[48:51], v[132:135], v[198:201], v[48:51]
	v_mfma_f32_16x16x32_bf16 v[44:47], v[140:143], v[198:201], v[44:47]
	v_mfma_f32_16x16x32_bf16 v[40:43], v[132:135], v[206:209], v[40:43]
	v_mfma_f32_16x16x32_bf16 v[36:39], v[140:143], v[206:209], v[36:39]
	v_mfma_f32_16x16x32_bf16 v[64:67], v[136:139], v[186:189], v[64:67]
	v_mfma_f32_16x16x32_bf16 v[60:63], v[144:147], v[186:189], v[60:63]
	v_mfma_f32_16x16x32_bf16 v[56:59], v[136:139], v[194:197], v[56:59]
	v_mfma_f32_16x16x32_bf16 v[52:55], v[144:147], v[194:197], v[52:55]
	v_mfma_f32_16x16x32_bf16 v[48:51], v[136:139], v[202:205], v[48:51]
	v_mfma_f32_16x16x32_bf16 v[44:47], v[144:147], v[202:205], v[44:47]
	v_mfma_f32_16x16x32_bf16 v[40:43], v[136:139], v[210:213], v[40:43]
	v_mfma_f32_16x16x32_bf16 v[36:39], v[144:147], v[210:213], v[36:39]
	v_mfma_f32_16x16x32_bf16 v[32:35], v[148:151], v[182:185], v[32:35]
	v_mfma_f32_16x16x32_bf16 v[28:31], v[156:159], v[182:185], v[28:31]
	v_mfma_f32_16x16x32_bf16 v[24:27], v[148:151], v[190:193], v[24:27]
	v_mfma_f32_16x16x32_bf16 v[20:23], v[156:159], v[190:193], v[20:23]
	v_mfma_f32_16x16x32_bf16 v[16:19], v[148:151], v[198:201], v[16:19]
	v_mfma_f32_16x16x32_bf16 v[12:15], v[156:159], v[198:201], v[12:15]
	v_mfma_f32_16x16x32_bf16 v[8:11], v[148:151], v[206:209], v[8:11]
	v_mfma_f32_16x16x32_bf16 v[2:5], v[156:159], v[206:209], v[4:7]
	v_mfma_f32_16x16x32_bf16 v[32:35], v[152:155], v[186:189], v[32:35]
	v_mfma_f32_16x16x32_bf16 v[28:31], v[160:163], v[186:189], v[28:31]
	v_mfma_f32_16x16x32_bf16 v[24:27], v[152:155], v[194:197], v[24:27]
	v_mfma_f32_16x16x32_bf16 v[20:23], v[160:163], v[194:197], v[20:23]
	v_mfma_f32_16x16x32_bf16 v[16:19], v[152:155], v[202:205], v[16:19]
	v_mfma_f32_16x16x32_bf16 v[12:15], v[160:163], v[202:205], v[12:15]
	v_mfma_f32_16x16x32_bf16 v[8:11], v[152:155], v[210:213], v[8:11]
	v_mfma_f32_16x16x32_bf16 v[2:5], v[160:163], v[210:213], v[2:5]
	s_barrier
	s_setprio 0
	s_add_i32 s62, 0, 0x18000
	v_add_u32_e32 v1, s62, v220
	s_add_i32 s63, 0, 0x1c000
	ds_read_b128 v[132:135], v1
	ds_read_b128 v[136:139], v1 offset:1024
	ds_read_b128 v[140:143], v1 offset:2048
	ds_read_b128 v[144:147], v1 offset:3072
	v_add_u32_e32 v1, s63, v220
	ds_read_b128 v[148:151], v1
	ds_read_b128 v[152:155], v1 offset:1024
	ds_read_b128 v[156:159], v1 offset:2048
	ds_read_b128 v[160:163], v1 offset:3072
	s_add_u32 s60, s60, 0x100000
	s_addc_u32 s61, s61, 0
	s_mov_b32 m0, s89
	v_lshl_add_u64 v[6:7], s[60:61], 0, v[164:165]
	ds_read_b128 v[182:185], v222 offset:32768
	ds_read_b128 v[186:189], v222 offset:33792
	ds_read_b128 v[190:193], v222 offset:34816
	ds_read_b128 v[194:197], v222 offset:35840
	ds_read_b128 v[198:201], v222 offset:36864
	ds_read_b128 v[202:205], v222 offset:37888
	ds_read_b128 v[206:209], v222 offset:38912
	ds_read_b128 v[210:213], v222 offset:39936
	global_load_lds_dwordx4 v[6:7], off
	v_lshl_add_u64 v[6:7], s[60:61], 0, v[168:169]
	s_mov_b32 m0, s90
	s_nop 0
	global_load_lds_dwordx4 v[6:7], off
	s_waitcnt vmcnt(8)
	s_waitcnt lgkmcnt(0)
	s_setprio 1
	s_barrier
	v_mfma_f32_16x16x32_bf16 v[128:131], v[132:135], v[182:185], v[128:131]
	v_mfma_f32_16x16x32_bf16 v[124:127], v[140:143], v[182:185], v[124:127]
	v_mfma_f32_16x16x32_bf16 v[120:123], v[132:135], v[190:193], v[120:123]
	v_mfma_f32_16x16x32_bf16 v[116:119], v[140:143], v[190:193], v[116:119]
	v_mfma_f32_16x16x32_bf16 v[112:115], v[132:135], v[198:201], v[112:115]
	v_mfma_f32_16x16x32_bf16 v[108:111], v[140:143], v[198:201], v[108:111]
	v_mfma_f32_16x16x32_bf16 v[104:107], v[132:135], v[206:209], v[104:107]
	v_mfma_f32_16x16x32_bf16 v[100:103], v[140:143], v[206:209], v[100:103]
	v_mfma_f32_16x16x32_bf16 v[128:131], v[136:139], v[186:189], v[128:131]
	v_mfma_f32_16x16x32_bf16 v[124:127], v[144:147], v[186:189], v[124:127]
	v_mfma_f32_16x16x32_bf16 v[120:123], v[136:139], v[194:197], v[120:123]
	v_mfma_f32_16x16x32_bf16 v[116:119], v[144:147], v[194:197], v[116:119]
	v_mfma_f32_16x16x32_bf16 v[112:115], v[136:139], v[202:205], v[112:115]
	v_mfma_f32_16x16x32_bf16 v[108:111], v[144:147], v[202:205], v[108:111]
	v_mfma_f32_16x16x32_bf16 v[104:107], v[136:139], v[210:213], v[104:107]
	v_mfma_f32_16x16x32_bf16 v[100:103], v[144:147], v[210:213], v[100:103]
	v_mfma_f32_16x16x32_bf16 v[96:99], v[148:151], v[182:185], v[96:99]
	v_mfma_f32_16x16x32_bf16 v[92:95], v[156:159], v[182:185], v[92:95]
	v_mfma_f32_16x16x32_bf16 v[88:91], v[148:151], v[190:193], v[88:91]
	v_mfma_f32_16x16x32_bf16 v[84:87], v[156:159], v[190:193], v[84:87]
	v_mfma_f32_16x16x32_bf16 v[80:83], v[148:151], v[198:201], v[80:83]
	v_mfma_f32_16x16x32_bf16 v[76:79], v[156:159], v[198:201], v[76:79]
	v_mfma_f32_16x16x32_bf16 v[72:75], v[148:151], v[206:209], v[72:75]
	v_mfma_f32_16x16x32_bf16 v[68:71], v[156:159], v[206:209], v[68:71]
	v_mfma_f32_16x16x32_bf16 v[96:99], v[152:155], v[186:189], v[96:99]
	v_mfma_f32_16x16x32_bf16 v[92:95], v[160:163], v[186:189], v[92:95]
	v_mfma_f32_16x16x32_bf16 v[88:91], v[152:155], v[194:197], v[88:91]
	v_mfma_f32_16x16x32_bf16 v[84:87], v[160:163], v[194:197], v[84:87]
	v_mfma_f32_16x16x32_bf16 v[80:83], v[152:155], v[202:205], v[80:83]
	v_mfma_f32_16x16x32_bf16 v[76:79], v[160:163], v[202:205], v[76:79]
	v_mfma_f32_16x16x32_bf16 v[72:75], v[152:155], v[210:213], v[72:75]
	v_mfma_f32_16x16x32_bf16 v[68:71], v[160:163], v[210:213], v[68:71]
	s_barrier
; #define PG8_STAGE(bufoff, gbase, voff) do { _Pragma("unroll") for (int _i = 0; _i < 2; ++_i) \
;         __builtin_amdgcn_global_load_lds((const unsigned*)((const char*)(gbase) + (voff)[_i]), (PG8_LAS unsigned*)(lds + (bufoff) + ldsw + _i * 8192), 16, 0, 0); } while (0)
; #define PG8_LDA(dst, b, h) do { _Pragma("unroll") for (int m = 0; m < 4; ++m) _Pragma("unroll") for (int k = 0; k < 2; ++k) dst[m][k] = *(const PG8_LAS bf16x8*)(lds + PG8_SA(b, h) + aoff + m * 2048 + k * 1024); } while (0)
; #define PG8_WAIT_V(n) asm volatile("s_waitcnt vmcnt(" #n ")" ::: "memory")
; #define PG8_WAIT_L(n) asm volatile("s_waitcnt lgkmcnt(" #n ")" ::: "memory")
; #define PG8_BAR __builtin_amdgcn_s_barrier()
; #define PG8_SCHED __builtin_amdgcn_sched_barrier(0)
; template <class Epi, class Sched, bool ALIGN_EPI = false, bool SP2 = false, bool F8 = false>
; __device__ __forceinline__ void gemm_phase(PG8_LAS unsigned char* lds, const int K, const Sched& S, const Epi& E, const int wave) {
;     ...
;         for (int t = 0; t < nt; t += 2) {
;     ...
;             PG8_WAIT_V(8); PG8_WAIT_L(0); PG8_BAR; PG8_MMA(0, 0, At, B0); PG8_MMA(0, 1, At, B1); PG8_BAR; PG8_SCHED;
;             PG8_LDA(At, 1, 1); PG8_STAGE(PG8_SB(1, 0), b3, voffB); PG8_STAGE(PG8_SB(1, 1), b3 + hstep, voffB); PG8_STAGE(PG8_SA(1, 0), a3, voffA);
;             PG8_WAIT_V(8); PG8_WAIT_L(0); PG8_BAR; PG8_MMA(1, 0, At, B0); PG8_MMA(1, 1, At, B1); PG8_BAR; PG8_SCHED;
	s_setprio 0
	s_add_i32 s60, s62, s86
	v_lshl_add_u64 v[6:7], s[58:59], 0, v[166:167]
	s_mov_b32 m0, s60
	ds_read_b128 v[182:185], v222 offset:49152
	ds_read_b128 v[186:189], v222 offset:50176
	ds_read_b128 v[190:193], v222 offset:51200
	ds_read_b128 v[194:197], v222 offset:52224
	ds_read_b128 v[198:201], v222 offset:53248
	ds_read_b128 v[202:205], v222 offset:54272
	ds_read_b128 v[206:209], v222 offset:55296
	ds_read_b128 v[210:213], v222 offset:56320
	global_load_lds_dwordx4 v[6:7], off
	s_add_i32 m0, s60, 0x2000
	v_lshl_add_u64 v[6:7], s[58:59], 0, v[170:171]
	s_add_u32 s58, s58, 0x100000
	s_addc_u32 s59, s59, 0
	s_add_i32 s60, s63, s86
	global_load_lds_dwordx4 v[6:7], off
	v_lshl_add_u64 v[6:7], s[58:59], 0, v[166:167]
	s_mov_b32 m0, s60
	s_nop 0
	global_load_lds_dwordx4 v[6:7], off
	v_lshl_add_u64 v[6:7], s[58:59], 0, v[170:171]
	s_add_i32 m0, s60, 0x2000
	s_nop 0
	global_load_lds_dwordx4 v[6:7], off
	v_lshl_add_u64 v[6:7], s[56:57], 0, v[164:165]
	s_mov_b32 m0, s79
	s_nop 0
	global_load_lds_dwordx4 v[6:7], off
	v_lshl_add_u64 v[6:7], s[56:57], 0, v[168:169]
	s_mov_b32 m0, s80
	s_nop 0
	global_load_lds_dwordx4 v[6:7], off
	s_waitcnt vmcnt(8)
	s_waitcnt lgkmcnt(0)
	s_setprio 1
	s_barrier
	v_mfma_f32_16x16x32_bf16 v[64:67], v[132:135], v[182:185], v[64:67]
	v_mfma_f32_16x16x32_bf16 v[60:63], v[140:143], v[182:185], v[60:63]
	v_mfma_f32_16x16x32_bf16 v[56:59], v[132:135], v[190:193], v[56:59]
	v_mfma_f32_16x16x32_bf16 v[52:55], v[140:143], v[190:193], v[52:55]
	v_mfma_f32_16x16x32_bf16 v[48:51], v[132:135], v[198:201], v[48:51]
	v_mfma_f32_16x16x32_bf16 v[44:47], v[140:143], v[198:201], v[44:47]
	v_mfma_f32_16x16x32_bf16 v[40:43], v[132:135], v[206:209], v[40:43]
	v_mfma_f32_16x16x32_bf16 v[36:39], v[140:143], v[206:209], v[36:39]
	v_mfma_f32_16x16x32_bf16 v[64:67], v[136:139], v[186:189], v[64:67]
	v_mfma_f32_16x16x32_bf16 v[60:63], v[144:147], v[186:189], v[60:63]
	v_mfma_f32_16x16x32_bf16 v[56:59], v[136:139], v[194:197], v[56:59]
	v_mfma_f32_16x16x32_bf16 v[52:55], v[144:147], v[194:197], v[52:55]
	v_mfma_f32_16x16x32_bf16 v[48:51], v[136:139], v[202:205], v[48:51]
	v_mfma_f32_16x16x32_bf16 v[44:47], v[144:147], v[202:205], v[44:47]
	v_mfma_f32_16x16x32_bf16 v[40:43], v[136:139], v[210:213], v[40:43]
	v_mfma_f32_16x16x32_bf16 v[36:39], v[144:147], v[210:213], v[36:39]
	v_mfma_f32_16x16x32_bf16 v[32:35], v[148:151], v[182:185], v[32:35]
	v_mfma_f32_16x16x32_bf16 v[28:31], v[156:159], v[182:185], v[28:31]
	v_mfma_f32_16x16x32_bf16 v[24:27], v[148:151], v[190:193], v[24:27]
	v_mfma_f32_16x16x32_bf16 v[20:23], v[156:159], v[190:193], v[20:23]
	v_mfma_f32_16x16x32_bf16 v[16:19], v[148:151], v[198:201], v[16:19]
	v_mfma_f32_16x16x32_bf16 v[12:15], v[156:159], v[198:201], v[12:15]
	v_mfma_f32_16x16x32_bf16 v[6:9], v[148:151], v[206:209], v[8:11]
	v_mfma_f32_16x16x32_bf16 v[2:5], v[156:159], v[206:209], v[2:5]
	v_mfma_f32_16x16x32_bf16 v[32:35], v[152:155], v[186:189], v[32:35]
	v_mfma_f32_16x16x32_bf16 v[28:31], v[160:163], v[186:189], v[28:31]
	v_mfma_f32_16x16x32_bf16 v[24:27], v[152:155], v[194:197], v[24:27]
	v_mfma_f32_16x16x32_bf16 v[20:23], v[160:163], v[194:197], v[20:23]
	v_mfma_f32_16x16x32_bf16 v[16:19], v[152:155], v[202:205], v[16:19]
	v_mfma_f32_16x16x32_bf16 v[12:15], v[160:163], v[202:205], v[12:15]
	v_mfma_f32_16x16x32_bf16 v[8:11], v[152:155], v[210:213], v[6:9]
	v_mfma_f32_16x16x32_bf16 v[4:7], v[160:163], v[210:213], v[2:5]
	s_barrier
	s_setprio 0
	s_add_u32 s78, s78, 0x100
	s_addc_u32 s23, s23, 0
	s_add_u32 s72, s72, 0x100
	s_addc_u32 s8, s8, 0
	s_add_u32 s42, s42, 0x100
	s_addc_u32 s43, s43, 0
	s_cmp_ge_i32 s9, s85
	s_cbranch_scc1 .LBB0_773

; #define PG8_STAGE(bufoff, gbase, voff) do { _Pragma("unroll") for (int _i = 0; _i < 2; ++_i) \
;         __builtin_amdgcn_global_load_lds((const unsigned*)((const char*)(gbase) + (voff)[_i]), (PG8_LAS unsigned*)(lds + (bufoff) + ldsw + _i * 8192), 16, 0, 0); } while (0)
; #define PG8_LDA(dst, b, h) do { _Pragma("unroll") for (int m = 0; m < 4; ++m) _Pragma("unroll") for (int k = 0; k < 2; ++k) dst[m][k] = *(const PG8_LAS bf16x8*)(lds + PG8_SA(b, h) + aoff + m * 2048 + k * 1024); } while (0)
; #define PG8_LDB(dst, b, h) do { _Pragma("unroll") for (int n = 0; n < 2; ++n) _Pragma("unroll") for (int k = 0; k < 2; ++k) dst[n][k] = *(const PG8_LAS bf16x8*)(lds + PG8_SB(b, h) + boff + n * 2048 + k * 1024); } while (0)
; #define PG8_WAIT_V(n) asm volatile("s_waitcnt vmcnt(" #n ")" ::: "memory")
; #define PG8_WAIT_L(n) asm volatile("s_waitcnt lgkmcnt(" #n ")" ::: "memory")
; #define PG8_BAR __builtin_amdgcn_s_barrier()
; #define PG8_SCHED __builtin_amdgcn_sched_barrier(0)
; template <class Epi, class Sched, bool ALIGN_EPI = false, bool SP2 = false, bool F8 = false>
; __device__ __forceinline__ void gemm_phase(PG8_LAS unsigned char* lds, const int K, const Sched& S, const Epi& E, const int wave) {
;     ...
;             PG8_LDB(B0, 0, 0); PG8_LDB(B1, 0, 1); PG8_SCHED; PG8_LDA(At, 0, 0); PG8_STAGE(PG8_SA(1, 1), a1 + hstep, voffA);
;             PG8_WAIT_V(8); PG8_WAIT_L(0); PG8_BAR; PG8_MMA(0, 0, At, B0); PG8_MMA(0, 1, At, B1); PG8_BAR; PG8_SCHED;
;             PG8_LDA(At, 0, 1); PG8_STAGE(PG8_SB(0, 0), b2, voffB); PG8_STAGE(PG8_SB(0, 1), b2 + hstep, voffB); PG8_STAGE(PG8_SA(0, 0), a2, voffA);
;             PG8_WAIT_V(8); PG8_WAIT_L(0); PG8_BAR; PG8_MMA(1, 0, At, B0); PG8_MMA(1, 1, At, B1); PG8_BAR; PG8_SCHED;
.LBB0_966:
	s_add_i32 s90, s8, 2
	s_cmp_eq_u32 s85, s8
	s_cselect_b32 s42, s31, s86
	s_cselect_b32 s43, s25, s87
	s_cselect_b32 s57, s83, s89
	s_cselect_b32 s56, s84, s88
	s_add_u32 s8, s42, 0x80
	s_addc_u32 s9, s43, 0
	s_add_u32 s40, s56, 0x80
	s_addc_u32 s41, s57, 0
	s_mov_b64 s[92:93], s[6:7]
	v_add_u32_e32 v1, s77, v168
	ds_read_b128 v[132:135], v1
	ds_read_b128 v[136:139], v1 offset:1024
	ds_read_b128 v[156:159], v1 offset:2048
	ds_read_b128 v[160:163], v1 offset:3072
	v_add_u32_e32 v1, s78, v168
	ds_read_b128 v[172:175], v1
	ds_read_b128 v[176:179], v1 offset:1024
	ds_read_b128 v[180:183], v1 offset:2048
	ds_read_b128 v[184:187], v1 offset:3072
	s_add_u32 s92, s92, 0x100000
	s_addc_u32 s93, s93, 0
	v_lshl_add_u64 v[2:3], s[92:93], 0, v[140:141]
	s_add_i32 m0, s64, 0xc000
	ds_read_b128 v[188:191], v170
	ds_read_b128 v[192:195], v170 offset:1024
	ds_read_b128 v[196:199], v170 offset:2048
	ds_read_b128 v[200:203], v170 offset:3072
	ds_read_b128 v[204:207], v170 offset:4096
	ds_read_b128 v[208:211], v170 offset:5120
	ds_read_b128 v[212:215], v170 offset:6144
	ds_read_b128 v[216:219], v170 offset:7168
	global_load_lds_dwordx4 v[2:3], off
	v_lshl_add_u64 v[2:3], s[92:93], 0, v[144:145]
	s_add_i32 m0, s64, 0xe000
	s_nop 0
	global_load_lds_dwordx4 v[2:3], off
	s_waitcnt vmcnt(8)
	s_waitcnt lgkmcnt(0)
	s_setprio 1
	s_barrier
	v_mfma_f32_16x16x32_bf16 v[128:131], v[132:135], v[188:191], v[128:131]
	v_mfma_f32_16x16x32_bf16 v[124:127], v[156:159], v[188:191], v[124:127]
	v_mfma_f32_16x16x32_bf16 v[120:123], v[132:135], v[196:199], v[120:123]
	v_mfma_f32_16x16x32_bf16 v[116:119], v[156:159], v[196:199], v[116:119]
	v_mfma_f32_16x16x32_bf16 v[112:115], v[132:135], v[204:207], v[112:115]
	v_mfma_f32_16x16x32_bf16 v[108:111], v[156:159], v[204:207], v[108:111]
	v_mfma_f32_16x16x32_bf16 v[104:107], v[132:135], v[212:215], v[104:107]
	v_mfma_f32_16x16x32_bf16 v[100:103], v[156:159], v[212:215], v[100:103]
	v_mfma_f32_16x16x32_bf16 v[128:131], v[136:139], v[192:195], v[128:131]
	v_mfma_f32_16x16x32_bf16 v[124:127], v[160:163], v[192:195], v[124:127]
	v_mfma_f32_16x16x32_bf16 v[120:123], v[136:139], v[200:203], v[120:123]
	v_mfma_f32_16x16x32_bf16 v[116:119], v[160:163], v[200:203], v[116:119]
	v_mfma_f32_16x16x32_bf16 v[112:115], v[136:139], v[208:211], v[112:115]
	v_mfma_f32_16x16x32_bf16 v[108:111], v[160:163], v[208:211], v[108:111]
	v_mfma_f32_16x16x32_bf16 v[104:107], v[136:139], v[216:219], v[104:107]
	v_mfma_f32_16x16x32_bf16 v[100:103], v[160:163], v[216:219], v[100:103]
	v_mfma_f32_16x16x32_bf16 v[96:99], v[172:175], v[188:191], v[96:99]
	v_mfma_f32_16x16x32_bf16 v[92:95], v[180:183], v[188:191], v[92:95]
	v_mfma_f32_16x16x32_bf16 v[88:91], v[172:175], v[196:199], v[88:91]
	v_mfma_f32_16x16x32_bf16 v[84:87], v[180:183], v[196:199], v[84:87]
	v_mfma_f32_16x16x32_bf16 v[80:83], v[172:175], v[204:207], v[80:83]
	v_mfma_f32_16x16x32_bf16 v[76:79], v[180:183], v[204:207], v[76:79]
	v_mfma_f32_16x16x32_bf16 v[72:75], v[172:175], v[212:215], v[72:75]
	v_mfma_f32_16x16x32_bf16 v[68:71], v[180:183], v[212:215], v[68:71]
	v_mfma_f32_16x16x32_bf16 v[96:99], v[176:179], v[192:195], v[96:99]
	v_mfma_f32_16x16x32_bf16 v[92:95], v[184:187], v[192:195], v[92:95]
	v_mfma_f32_16x16x32_bf16 v[88:91], v[176:179], v[200:203], v[88:91]
	v_mfma_f32_16x16x32_bf16 v[84:87], v[184:187], v[200:203], v[84:87]
	v_mfma_f32_16x16x32_bf16 v[80:83], v[176:179], v[208:211], v[80:83]
	v_mfma_f32_16x16x32_bf16 v[76:79], v[184:187], v[208:211], v[76:79]
	v_mfma_f32_16x16x32_bf16 v[72:75], v[176:179], v[216:219], v[72:75]
	v_mfma_f32_16x16x32_bf16 v[68:71], v[184:187], v[216:219], v[68:71]
	s_barrier
	s_setprio 0
	s_add_i32 s91, s77, s63
	v_lshl_add_u64 v[2:3], s[56:57], 0, v[142:143]
	s_mov_b32 m0, s91
	ds_read_b128 v[188:191], v170 offset:16384
	ds_read_b128 v[192:195], v170 offset:17408
	ds_read_b128 v[196:199], v170 offset:18432
	ds_read_b128 v[200:203], v170 offset:19456
	ds_read_b128 v[204:207], v170 offset:20480
	ds_read_b128 v[208:211], v170 offset:21504
	ds_read_b128 v[212:215], v170 offset:22528
	ds_read_b128 v[216:219], v170 offset:23552
	global_load_lds_dwordx4 v[2:3], off
	s_add_i32 m0, s91, 0x2000
	v_lshl_add_u64 v[2:3], s[56:57], 0, v[146:147]
	s_add_u32 s56, s56, 0x100000
	s_addc_u32 s57, s57, 0
	s_add_i32 s91, s78, s63
	global_load_lds_dwordx4 v[2:3], off
	v_lshl_add_u64 v[2:3], s[56:57], 0, v[142:143]
	s_mov_b32 m0, s91
	s_nop 0
	global_load_lds_dwordx4 v[2:3], off
	v_lshl_add_u64 v[2:3], s[56:57], 0, v[146:147]
	s_add_i32 m0, s91, 0x2000
	s_nop 0
	global_load_lds_dwordx4 v[2:3], off
	v_lshl_add_u64 v[2:3], s[42:43], 0, v[140:141]
	s_mov_b32 m0, s64
	s_nop 0
	global_load_lds_dwordx4 v[2:3], off
	v_lshl_add_u64 v[2:3], s[42:43], 0, v[144:145]
	s_mov_b32 m0, s65
	s_nop 0
	global_load_lds_dwordx4 v[2:3], off
	s_waitcnt vmcnt(8)
	s_waitcnt lgkmcnt(0)
	s_setprio 1
	s_barrier
; #define PG8_STAGE(bufoff, gbase, voff) do { _Pragma("unroll") for (int _i = 0; _i < 2; ++_i) \
;         __builtin_amdgcn_global_load_lds((const unsigned*)((const char*)(gbase) + (voff)[_i]), (PG8_LAS unsigned*)(lds + (bufoff) + ldsw + _i * 8192), 16, 0, 0); } while (0)
; #define PG8_LDA(dst, b, h) do { _Pragma("unroll") for (int m = 0; m < 4; ++m) _Pragma("unroll") for (int k = 0; k < 2; ++k) dst[m][k] = *(const PG8_LAS bf16x8*)(lds + PG8_SA(b, h) + aoff + m * 2048 + k * 1024); } while (0)
; #define PG8_LDB(dst, b, h) do { _Pragma("unroll") for (int n = 0; n < 2; ++n) _Pragma("unroll") for (int k = 0; k < 2; ++k) dst[n][k] = *(const PG8_LAS bf16x8*)(lds + PG8_SB(b, h) + boff + n * 2048 + k * 1024); } while (0)
; #define PG8_WAIT_V(n) asm volatile("s_waitcnt vmcnt(" #n ")" ::: "memory")
; #define PG8_WAIT_L(n) asm volatile("s_waitcnt lgkmcnt(" #n ")" ::: "memory")
; #define PG8_BAR __builtin_amdgcn_s_barrier()
; #define PG8_SCHED __builtin_amdgcn_sched_barrier(0)
; template <class Epi, class Sched, bool ALIGN_EPI = false, bool SP2 = false, bool F8 = false>
; __device__ __forceinline__ void gemm_phase(PG8_LAS unsigned char* lds, const int K, const Sched& S, const Epi& E, const int wave) {
;     ...
;             PG8_WAIT_V(8); PG8_WAIT_L(0); PG8_BAR; PG8_MMA(1, 0, At, B0); PG8_MMA(1, 1, At, B1); PG8_BAR; PG8_SCHED;
;             PG8_LDB(B0, 1, 0); PG8_LDB(B1, 1, 1); PG8_SCHED; PG8_LDA(At, 1, 0); PG8_STAGE(PG8_SA(0, 1), a2 + hstep, voffA);
;             PG8_WAIT_V(8); PG8_WAIT_L(0); PG8_BAR; PG8_MMA(0, 0, At, B0); PG8_MMA(0, 1, At, B1); PG8_BAR; PG8_SCHED;
	v_mfma_f32_16x16x32_bf16 v[64:67], v[132:135], v[188:191], v[64:67]
	v_mfma_f32_16x16x32_bf16 v[60:63], v[156:159], v[188:191], v[60:63]
	v_mfma_f32_16x16x32_bf16 v[56:59], v[132:135], v[196:199], v[56:59]
	v_mfma_f32_16x16x32_bf16 v[52:55], v[156:159], v[196:199], v[52:55]
	v_mfma_f32_16x16x32_bf16 v[48:51], v[132:135], v[204:207], v[48:51]
	v_mfma_f32_16x16x32_bf16 v[44:47], v[156:159], v[204:207], v[44:47]
	v_mfma_f32_16x16x32_bf16 v[40:43], v[132:135], v[212:215], v[40:43]
	v_mfma_f32_16x16x32_bf16 v[36:39], v[156:159], v[212:215], v[36:39]
	v_mfma_f32_16x16x32_bf16 v[64:67], v[136:139], v[192:195], v[64:67]
	v_mfma_f32_16x16x32_bf16 v[60:63], v[160:163], v[192:195], v[60:63]
	v_mfma_f32_16x16x32_bf16 v[56:59], v[136:139], v[200:203], v[56:59]
	v_mfma_f32_16x16x32_bf16 v[52:55], v[160:163], v[200:203], v[52:55]
	v_mfma_f32_16x16x32_bf16 v[48:51], v[136:139], v[208:211], v[48:51]
	v_mfma_f32_16x16x32_bf16 v[44:47], v[160:163], v[208:211], v[44:47]
	v_mfma_f32_16x16x32_bf16 v[40:43], v[136:139], v[216:219], v[40:43]
	v_mfma_f32_16x16x32_bf16 v[36:39], v[160:163], v[216:219], v[36:39]
	v_mfma_f32_16x16x32_bf16 v[32:35], v[172:175], v[188:191], v[32:35]
	v_mfma_f32_16x16x32_bf16 v[28:31], v[180:183], v[188:191], v[28:31]
	v_mfma_f32_16x16x32_bf16 v[24:27], v[172:175], v[196:199], v[24:27]
	v_mfma_f32_16x16x32_bf16 v[20:23], v[180:183], v[196:199], v[20:23]
	v_mfma_f32_16x16x32_bf16 v[16:19], v[172:175], v[204:207], v[16:19]
	v_mfma_f32_16x16x32_bf16 v[12:15], v[180:183], v[204:207], v[12:15]
	v_mfma_f32_16x16x32_bf16 v[8:11], v[172:175], v[212:215], v[8:11]
	v_mfma_f32_16x16x32_bf16 v[2:5], v[180:183], v[212:215], v[4:7]
	v_mfma_f32_16x16x32_bf16 v[32:35], v[176:179], v[192:195], v[32:35]
	v_mfma_f32_16x16x32_bf16 v[28:31], v[184:187], v[192:195], v[28:31]
	v_mfma_f32_16x16x32_bf16 v[24:27], v[176:179], v[200:203], v[24:27]
	v_mfma_f32_16x16x32_bf16 v[20:23], v[184:187], v[200:203], v[20:23]
	v_mfma_f32_16x16x32_bf16 v[16:19], v[176:179], v[208:211], v[16:19]
	v_mfma_f32_16x16x32_bf16 v[12:15], v[184:187], v[208:211], v[12:15]
	v_mfma_f32_16x16x32_bf16 v[8:11], v[176:179], v[216:219], v[8:11]
	v_mfma_f32_16x16x32_bf16 v[2:5], v[184:187], v[216:219], v[2:5]
	s_barrier
	s_setprio 0
	s_add_i32 s56, 0, 0x18000
	v_add_u32_e32 v1, s56, v168
	s_add_i32 s57, 0, 0x1c000
	ds_read_b128 v[132:135], v1
	ds_read_b128 v[136:139], v1 offset:1024
	ds_read_b128 v[156:159], v1 offset:2048
	ds_read_b128 v[160:163], v1 offset:3072
	v_add_u32_e32 v1, s57, v168
	ds_read_b128 v[172:175], v1
	ds_read_b128 v[176:179], v1 offset:1024
	ds_read_b128 v[180:183], v1 offset:2048
	ds_read_b128 v[184:187], v1 offset:3072
	s_add_u32 s42, s42, 0x100000
	s_addc_u32 s43, s43, 0
	s_mov_b32 m0, s66
	v_lshl_add_u64 v[6:7], s[42:43], 0, v[140:141]
	ds_read_b128 v[188:191], v170 offset:32768
	ds_read_b128 v[192:195], v170 offset:33792
	ds_read_b128 v[196:199], v170 offset:34816
	ds_read_b128 v[200:203], v170 offset:35840
	ds_read_b128 v[204:207], v170 offset:36864
	ds_read_b128 v[208:211], v170 offset:37888
	ds_read_b128 v[212:215], v170 offset:38912
	ds_read_b128 v[216:219], v170 offset:39936
	global_load_lds_dwordx4 v[6:7], off
	v_lshl_add_u64 v[6:7], s[42:43], 0, v[144:145]
	s_mov_b32 m0, s67
	s_nop 0
	global_load_lds_dwordx4 v[6:7], off
	s_waitcnt vmcnt(8)
	s_waitcnt lgkmcnt(0)
	s_setprio 1
	s_barrier
	v_mfma_f32_16x16x32_bf16 v[128:131], v[132:135], v[188:191], v[128:131]
	v_mfma_f32_16x16x32_bf16 v[124:127], v[156:159], v[188:191], v[124:127]
	v_mfma_f32_16x16x32_bf16 v[120:123], v[132:135], v[196:199], v[120:123]
	v_mfma_f32_16x16x32_bf16 v[116:119], v[156:159], v[196:199], v[116:119]
	v_mfma_f32_16x16x32_bf16 v[112:115], v[132:135], v[204:207], v[112:115]
	v_mfma_f32_16x16x32_bf16 v[108:111], v[156:159], v[204:207], v[108:111]
	v_mfma_f32_16x16x32_bf16 v[104:107], v[132:135], v[212:215], v[104:107]
	v_mfma_f32_16x16x32_bf16 v[100:103], v[156:159], v[212:215], v[100:103]
	v_mfma_f32_16x16x32_bf16 v[128:131], v[136:139], v[192:195], v[128:131]
	v_mfma_f32_16x16x32_bf16 v[124:127], v[160:163], v[192:195], v[124:127]
	v_mfma_f32_16x16x32_bf16 v[120:123], v[136:139], v[200:203], v[120:123]
	v_mfma_f32_16x16x32_bf16 v[116:119], v[160:163], v[200:203], v[116:119]
	v_mfma_f32_16x16x32_bf16 v[112:115], v[136:139], v[208:211], v[112:115]
	v_mfma_f32_16x16x32_bf16 v[108:111], v[160:163], v[208:211], v[108:111]
	v_mfma_f32_16x16x32_bf16 v[104:107], v[136:139], v[216:219], v[104:107]
	v_mfma_f32_16x16x32_bf16 v[100:103], v[160:163], v[216:219], v[100:103]
	v_mfma_f32_16x16x32_bf16 v[96:99], v[172:175], v[188:191], v[96:99]
	v_mfma_f32_16x16x32_bf16 v[92:95], v[180:183], v[188:191], v[92:95]
	v_mfma_f32_16x16x32_bf16 v[88:91], v[172:175], v[196:199], v[88:91]
	v_mfma_f32_16x16x32_bf16 v[84:87], v[180:183], v[196:199], v[84:87]
	v_mfma_f32_16x16x32_bf16 v[80:83], v[172:175], v[204:207], v[80:83]
	v_mfma_f32_16x16x32_bf16 v[76:79], v[180:183], v[204:207], v[76:79]
	v_mfma_f32_16x16x32_bf16 v[72:75], v[172:175], v[212:215], v[72:75]
	v_mfma_f32_16x16x32_bf16 v[68:71], v[180:183], v[212:215], v[68:71]
	v_mfma_f32_16x16x32_bf16 v[96:99], v[176:179], v[192:195], v[96:99]
	v_mfma_f32_16x16x32_bf16 v[92:95], v[184:187], v[192:195], v[92:95]
	v_mfma_f32_16x16x32_bf16 v[88:91], v[176:179], v[200:203], v[88:91]
	v_mfma_f32_16x16x32_bf16 v[84:87], v[184:187], v[200:203], v[84:87]
	v_mfma_f32_16x16x32_bf16 v[80:83], v[176:179], v[208:211], v[80:83]
	v_mfma_f32_16x16x32_bf16 v[76:79], v[184:187], v[208:211], v[76:79]
	v_mfma_f32_16x16x32_bf16 v[72:75], v[176:179], v[216:219], v[72:75]
	v_mfma_f32_16x16x32_bf16 v[68:71], v[184:187], v[216:219], v[68:71]
	s_barrier
; #define PG8_STAGE(bufoff, gbase, voff) do { _Pragma("unroll") for (int _i = 0; _i < 2; ++_i) \
;         __builtin_amdgcn_global_load_lds((const unsigned*)((const char*)(gbase) + (voff)[_i]), (PG8_LAS unsigned*)(lds + (bufoff) + ldsw + _i * 8192), 16, 0, 0); } while (0)
; #define PG8_LDA(dst, b, h) do { _Pragma("unroll") for (int m = 0; m < 4; ++m) _Pragma("unroll") for (int k = 0; k < 2; ++k) dst[m][k] = *(const PG8_LAS bf16x8*)(lds + PG8_SA(b, h) + aoff + m * 2048 + k * 1024); } while (0)
; #define PG8_WAIT_V(n) asm volatile("s_waitcnt vmcnt(" #n ")" ::: "memory")
; #define PG8_WAIT_L(n) asm volatile("s_waitcnt lgkmcnt(" #n ")" ::: "memory")
; #define PG8_BAR __builtin_amdgcn_s_barrier()
; #define PG8_SCHED __builtin_amdgcn_sched_barrier(0)
; template <class Epi, class Sched, bool ALIGN_EPI = false, bool SP2 = false, bool F8 = false>
; __device__ __forceinline__ void gemm_phase(PG8_LAS unsigned char* lds, const int K, const Sched& S, const Epi& E, const int wave) {
;     ...
;         for (int t = 0; t < nt; t += 2) {
;     ...
;             PG8_WAIT_V(8); PG8_WAIT_L(0); PG8_BAR; PG8_MMA(0, 0, At, B0); PG8_MMA(0, 1, At, B1); PG8_BAR; PG8_SCHED;
;             PG8_LDA(At, 1, 1); PG8_STAGE(PG8_SB(1, 0), b3, voffB); PG8_STAGE(PG8_SB(1, 1), b3 + hstep, voffB); PG8_STAGE(PG8_SA(1, 0), a3, voffA);
;             PG8_WAIT_V(8); PG8_WAIT_L(0); PG8_BAR; PG8_MMA(1, 0, At, B0); PG8_MMA(1, 1, At, B1); PG8_BAR; PG8_SCHED;
	s_setprio 0
	s_add_i32 s42, s56, s63
	v_lshl_add_u64 v[6:7], s[40:41], 0, v[142:143]
	s_mov_b32 m0, s42
	ds_read_b128 v[188:191], v170 offset:49152
	ds_read_b128 v[192:195], v170 offset:50176
	ds_read_b128 v[196:199], v170 offset:51200
	ds_read_b128 v[200:203], v170 offset:52224
	ds_read_b128 v[204:207], v170 offset:53248
	ds_read_b128 v[208:211], v170 offset:54272
	ds_read_b128 v[212:215], v170 offset:55296
	ds_read_b128 v[216:219], v170 offset:56320
	global_load_lds_dwordx4 v[6:7], off
	s_add_i32 m0, s42, 0x2000
	v_lshl_add_u64 v[6:7], s[40:41], 0, v[146:147]
	s_add_u32 s40, s40, 0x100000
	s_addc_u32 s41, s41, 0
	s_add_i32 s42, s57, s63
	global_load_lds_dwordx4 v[6:7], off
	v_lshl_add_u64 v[6:7], s[40:41], 0, v[142:143]
	s_mov_b32 m0, s42
	s_nop 0
	global_load_lds_dwordx4 v[6:7], off
	v_lshl_add_u64 v[6:7], s[40:41], 0, v[146:147]
	s_add_i32 m0, s42, 0x2000
	s_nop 0
	global_load_lds_dwordx4 v[6:7], off
	v_lshl_add_u64 v[6:7], s[8:9], 0, v[140:141]
	s_mov_b32 m0, s74
	s_nop 0
	global_load_lds_dwordx4 v[6:7], off
	v_lshl_add_u64 v[6:7], s[8:9], 0, v[144:145]
	s_mov_b32 m0, s76
	s_nop 0
	global_load_lds_dwordx4 v[6:7], off
	s_waitcnt vmcnt(8)
	s_waitcnt lgkmcnt(0)
	s_setprio 1
	s_barrier
	v_mfma_f32_16x16x32_bf16 v[64:67], v[132:135], v[188:191], v[64:67]
	v_mfma_f32_16x16x32_bf16 v[60:63], v[156:159], v[188:191], v[60:63]
	v_mfma_f32_16x16x32_bf16 v[56:59], v[132:135], v[196:199], v[56:59]
	v_mfma_f32_16x16x32_bf16 v[52:55], v[156:159], v[196:199], v[52:55]
	v_mfma_f32_16x16x32_bf16 v[48:51], v[132:135], v[204:207], v[48:51]
	v_mfma_f32_16x16x32_bf16 v[44:47], v[156:159], v[204:207], v[44:47]
	v_mfma_f32_16x16x32_bf16 v[40:43], v[132:135], v[212:215], v[40:43]
	v_mfma_f32_16x16x32_bf16 v[36:39], v[156:159], v[212:215], v[36:39]
	v_mfma_f32_16x16x32_bf16 v[64:67], v[136:139], v[192:195], v[64:67]
	v_mfma_f32_16x16x32_bf16 v[60:63], v[160:163], v[192:195], v[60:63]
	v_mfma_f32_16x16x32_bf16 v[56:59], v[136:139], v[200:203], v[56:59]
	v_mfma_f32_16x16x32_bf16 v[52:55], v[160:163], v[200:203], v[52:55]
	v_mfma_f32_16x16x32_bf16 v[48:51], v[136:139], v[208:211], v[48:51]
	v_mfma_f32_16x16x32_bf16 v[44:47], v[160:163], v[208:211], v[44:47]
	v_mfma_f32_16x16x32_bf16 v[40:43], v[136:139], v[216:219], v[40:43]
	v_mfma_f32_16x16x32_bf16 v[36:39], v[160:163], v[216:219], v[36:39]
	v_mfma_f32_16x16x32_bf16 v[32:35], v[172:175], v[188:191], v[32:35]
	v_mfma_f32_16x16x32_bf16 v[28:31], v[180:183], v[188:191], v[28:31]
	v_mfma_f32_16x16x32_bf16 v[24:27], v[172:175], v[196:199], v[24:27]
	v_mfma_f32_16x16x32_bf16 v[20:23], v[180:183], v[196:199], v[20:23]
	v_mfma_f32_16x16x32_bf16 v[16:19], v[172:175], v[204:207], v[16:19]
	v_mfma_f32_16x16x32_bf16 v[12:15], v[180:183], v[204:207], v[12:15]
	v_mfma_f32_16x16x32_bf16 v[6:9], v[172:175], v[212:215], v[8:11]
	v_mfma_f32_16x16x32_bf16 v[2:5], v[180:183], v[212:215], v[2:5]
	v_mfma_f32_16x16x32_bf16 v[32:35], v[176:179], v[192:195], v[32:35]
	v_mfma_f32_16x16x32_bf16 v[28:31], v[184:187], v[192:195], v[28:31]
	v_mfma_f32_16x16x32_bf16 v[24:27], v[176:179], v[200:203], v[24:27]
	v_mfma_f32_16x16x32_bf16 v[20:23], v[184:187], v[200:203], v[20:23]
	v_mfma_f32_16x16x32_bf16 v[16:19], v[176:179], v[208:211], v[16:19]
	v_mfma_f32_16x16x32_bf16 v[12:15], v[184:187], v[208:211], v[12:15]
	v_mfma_f32_16x16x32_bf16 v[8:11], v[176:179], v[216:219], v[6:9]
	v_mfma_f32_16x16x32_bf16 v[4:7], v[184:187], v[216:219], v[2:5]
	s_barrier
	s_setprio 0
	s_add_u32 s86, s86, 0x100
	s_addc_u32 s87, s87, 0
	s_add_u32 s88, s88, 0x100
	s_addc_u32 s89, s89, 0
	s_add_u32 s6, s6, 0x100
	s_addc_u32 s7, s7, 0
	s_cmp_ge_i32 s90, s62
	s_mov_b32 s8, s90
	s_cbranch_scc0 .LBB0_966

; #define PG8_STAGE(bufoff, gbase, voff) do { _Pragma("unroll") for (int _i = 0; _i < 2; ++_i) \
;         __builtin_amdgcn_global_load_lds((const unsigned*)((const char*)(gbase) + (voff)[_i]), (PG8_LAS unsigned*)(lds + (bufoff) + ldsw + _i * 8192), 16, 0, 0); } while (0)
; #define PG8_LDA(dst, b, h) do { _Pragma("unroll") for (int m = 0; m < 4; ++m) _Pragma("unroll") for (int k = 0; k < 2; ++k) dst[m][k] = *(const PG8_LAS bf16x8*)(lds + PG8_SA(b, h) + aoff + m * 2048 + k * 1024); } while (0)
; #define PG8_LDB(dst, b, h) do { _Pragma("unroll") for (int n = 0; n < 2; ++n) _Pragma("unroll") for (int k = 0; k < 2; ++k) dst[n][k] = *(const PG8_LAS bf16x8*)(lds + PG8_SB(b, h) + boff + n * 2048 + k * 1024); } while (0)
; #define PG8_WAIT_V(n) asm volatile("s_waitcnt vmcnt(" #n ")" ::: "memory")
; #define PG8_WAIT_L(n) asm volatile("s_waitcnt lgkmcnt(" #n ")" ::: "memory")
; #define PG8_BAR __builtin_amdgcn_s_barrier()
; #define PG8_SCHED __builtin_amdgcn_sched_barrier(0)
; template <class Epi, class Sched, bool ALIGN_EPI = false, bool SP2 = false, bool F8 = false>
; __device__ __forceinline__ void gemm_phase(PG8_LAS unsigned char* lds, const int K, const Sched& S, const Epi& E, const int wave) {
;     ...
;             PG8_LDB(B0, 0, 0); PG8_LDB(B1, 0, 1); PG8_SCHED; PG8_LDA(At, 0, 0); PG8_STAGE(PG8_SA(1, 1), a1 + hstep, voffA);
;             PG8_WAIT_V(8); PG8_WAIT_L(0); PG8_BAR; PG8_MMA(0, 0, At, B0); PG8_MMA(0, 1, At, B1); PG8_BAR; PG8_SCHED;
;             PG8_LDA(At, 0, 1); PG8_STAGE(PG8_SB(0, 0), b2, voffB); PG8_STAGE(PG8_SB(0, 1), b2 + hstep, voffB); PG8_STAGE(PG8_SA(0, 0), a2, voffA);
;             PG8_WAIT_V(8); PG8_WAIT_L(0); PG8_BAR; PG8_MMA(1, 0, At, B0); PG8_MMA(1, 1, At, B1); PG8_BAR; PG8_SCHED;
.LBB0_1240:
	s_add_u32 s25, s10, s38
	s_addc_u32 s40, s11, s39
	s_add_u32 s64, s25, 0xffffff80
	s_addc_u32 s65, s40, -1
	s_add_u32 s41, s12, s38
	s_addc_u32 s42, s13, s39
	s_cmp_eq_u32 s23, 60
	s_cselect_b32 s44, s30, s25
	s_cselect_b32 s45, s31, s40
	s_cselect_b32 s53, s37, s42
	s_cselect_b32 s52, s36, s41
	s_add_u32 s40, s44, 0x80
	s_addc_u32 s41, s45, 0
	s_add_u32 s42, s52, 0x80
	s_addc_u32 s43, s53, 0
	v_add_u32_e32 v149, s59, v146
	ds_read_b128 v[140:143], v149
	ds_read_b128 v[150:153], v149 offset:1024
	ds_read_b128 v[154:157], v149 offset:2048
	ds_read_b128 v[158:161], v149 offset:3072
	v_add_u32_e32 v149, s60, v146
	ds_read_b128 v[162:165], v149
	ds_read_b128 v[166:169], v149 offset:1024
	ds_read_b128 v[170:173], v149 offset:2048
	ds_read_b128 v[174:177], v149 offset:3072
	s_add_u32 s64, s64, 0x100000
	s_addc_u32 s65, s65, 0
	v_lshl_add_u64 v[210:211], s[64:65], 0, v[134:135]
	s_add_i32 m0, s9, 0xc000
	ds_read_b128 v[178:181], v148
	ds_read_b128 v[182:185], v148 offset:1024
	ds_read_b128 v[186:189], v148 offset:2048
	ds_read_b128 v[190:193], v148 offset:3072
	ds_read_b128 v[194:197], v148 offset:4096
	ds_read_b128 v[198:201], v148 offset:5120
	ds_read_b128 v[202:205], v148 offset:6144
	ds_read_b128 v[206:209], v148 offset:7168
	global_load_lds_dwordx4 v[210:211], off
	v_lshl_add_u64 v[210:211], s[64:65], 0, v[130:131]
	s_add_i32 m0, s9, 0xe000
	s_nop 0
	global_load_lds_dwordx4 v[210:211], off
	s_waitcnt vmcnt(8)
	s_waitcnt lgkmcnt(0)
	s_setprio 1
	s_barrier
	v_mfma_f32_16x16x32_bf16 v[124:127], v[140:143], v[178:181], v[124:127]
	v_mfma_f32_16x16x32_bf16 v[120:123], v[154:157], v[178:181], v[120:123]
	v_mfma_f32_16x16x32_bf16 v[116:119], v[140:143], v[186:189], v[116:119]
	v_mfma_f32_16x16x32_bf16 v[112:115], v[154:157], v[186:189], v[112:115]
	v_mfma_f32_16x16x32_bf16 v[108:111], v[140:143], v[194:197], v[108:111]
	v_mfma_f32_16x16x32_bf16 v[104:107], v[154:157], v[194:197], v[104:107]
	v_mfma_f32_16x16x32_bf16 v[100:103], v[140:143], v[202:205], v[100:103]
	v_mfma_f32_16x16x32_bf16 v[96:99], v[154:157], v[202:205], v[96:99]
	v_mfma_f32_16x16x32_bf16 v[124:127], v[150:153], v[182:185], v[124:127]
	v_mfma_f32_16x16x32_bf16 v[120:123], v[158:161], v[182:185], v[120:123]
	v_mfma_f32_16x16x32_bf16 v[116:119], v[150:153], v[190:193], v[116:119]
	v_mfma_f32_16x16x32_bf16 v[112:115], v[158:161], v[190:193], v[112:115]
	v_mfma_f32_16x16x32_bf16 v[108:111], v[150:153], v[198:201], v[108:111]
	v_mfma_f32_16x16x32_bf16 v[104:107], v[158:161], v[198:201], v[104:107]
	v_mfma_f32_16x16x32_bf16 v[100:103], v[150:153], v[206:209], v[100:103]
	v_mfma_f32_16x16x32_bf16 v[96:99], v[158:161], v[206:209], v[96:99]
	v_mfma_f32_16x16x32_bf16 v[92:95], v[162:165], v[178:181], v[92:95]
	v_mfma_f32_16x16x32_bf16 v[88:91], v[170:173], v[178:181], v[88:91]
	v_mfma_f32_16x16x32_bf16 v[84:87], v[162:165], v[186:189], v[84:87]
	v_mfma_f32_16x16x32_bf16 v[80:83], v[170:173], v[186:189], v[80:83]
	v_mfma_f32_16x16x32_bf16 v[76:79], v[162:165], v[194:197], v[76:79]
	v_mfma_f32_16x16x32_bf16 v[72:75], v[170:173], v[194:197], v[72:75]
	v_mfma_f32_16x16x32_bf16 v[68:71], v[162:165], v[202:205], v[68:71]
	v_mfma_f32_16x16x32_bf16 v[64:67], v[170:173], v[202:205], v[64:67]
	v_mfma_f32_16x16x32_bf16 v[92:95], v[166:169], v[182:185], v[92:95]
	v_mfma_f32_16x16x32_bf16 v[88:91], v[174:177], v[182:185], v[88:91]
	v_mfma_f32_16x16x32_bf16 v[84:87], v[166:169], v[190:193], v[84:87]
	v_mfma_f32_16x16x32_bf16 v[80:83], v[174:177], v[190:193], v[80:83]
	v_mfma_f32_16x16x32_bf16 v[76:79], v[166:169], v[198:201], v[76:79]
	v_mfma_f32_16x16x32_bf16 v[72:75], v[174:177], v[198:201], v[72:75]
	v_mfma_f32_16x16x32_bf16 v[68:71], v[166:169], v[206:209], v[68:71]
	v_mfma_f32_16x16x32_bf16 v[64:67], v[174:177], v[206:209], v[64:67]
	s_barrier
	s_setprio 0
	s_add_i32 s25, s59, s48
	v_lshl_add_u64 v[210:211], s[52:53], 0, v[132:133]
	s_mov_b32 m0, s25
	ds_read_b128 v[178:181], v148 offset:16384
	ds_read_b128 v[182:185], v148 offset:17408
	ds_read_b128 v[186:189], v148 offset:18432
	ds_read_b128 v[190:193], v148 offset:19456
	ds_read_b128 v[194:197], v148 offset:20480
	ds_read_b128 v[198:201], v148 offset:21504
	ds_read_b128 v[202:205], v148 offset:22528
	ds_read_b128 v[206:209], v148 offset:23552
	global_load_lds_dwordx4 v[210:211], off
	s_add_i32 m0, s25, 0x2000
	v_lshl_add_u64 v[210:211], s[52:53], 0, v[128:129]
	s_add_u32 s52, s52, 0x100000
	s_addc_u32 s53, s53, 0
	s_add_i32 s25, s60, s48
	global_load_lds_dwordx4 v[210:211], off
	v_lshl_add_u64 v[210:211], s[52:53], 0, v[132:133]
	s_mov_b32 m0, s25
	s_nop 0
	global_load_lds_dwordx4 v[210:211], off
	v_lshl_add_u64 v[210:211], s[52:53], 0, v[128:129]
	s_add_i32 m0, s25, 0x2000
	s_nop 0
	global_load_lds_dwordx4 v[210:211], off
	v_lshl_add_u64 v[210:211], s[44:45], 0, v[134:135]
	s_mov_b32 m0, s9
	s_nop 0
	global_load_lds_dwordx4 v[210:211], off
	v_lshl_add_u64 v[210:211], s[44:45], 0, v[130:131]
	s_mov_b32 m0, s50
	s_nop 0
	global_load_lds_dwordx4 v[210:211], off
	s_waitcnt vmcnt(8)
	s_waitcnt lgkmcnt(0)
	s_setprio 1
	s_barrier
; #define PG8_STAGE(bufoff, gbase, voff) do { _Pragma("unroll") for (int _i = 0; _i < 2; ++_i) \
;         __builtin_amdgcn_global_load_lds((const unsigned*)((const char*)(gbase) + (voff)[_i]), (PG8_LAS unsigned*)(lds + (bufoff) + ldsw + _i * 8192), 16, 0, 0); } while (0)
; #define PG8_LDA(dst, b, h) do { _Pragma("unroll") for (int m = 0; m < 4; ++m) _Pragma("unroll") for (int k = 0; k < 2; ++k) dst[m][k] = *(const PG8_LAS bf16x8*)(lds + PG8_SA(b, h) + aoff + m * 2048 + k * 1024); } while (0)
; #define PG8_LDB(dst, b, h) do { _Pragma("unroll") for (int n = 0; n < 2; ++n) _Pragma("unroll") for (int k = 0; k < 2; ++k) dst[n][k] = *(const PG8_LAS bf16x8*)(lds + PG8_SB(b, h) + boff + n * 2048 + k * 1024); } while (0)
; #define PG8_WAIT_V(n) asm volatile("s_waitcnt vmcnt(" #n ")" ::: "memory")
; #define PG8_WAIT_L(n) asm volatile("s_waitcnt lgkmcnt(" #n ")" ::: "memory")
; #define PG8_BAR __builtin_amdgcn_s_barrier()
; #define PG8_SCHED __builtin_amdgcn_sched_barrier(0)
; template <class Epi, class Sched, bool ALIGN_EPI = false, bool SP2 = false, bool F8 = false>
; __device__ __forceinline__ void gemm_phase(PG8_LAS unsigned char* lds, const int K, const Sched& S, const Epi& E, const int wave) {
;     ...
;             PG8_WAIT_V(8); PG8_WAIT_L(0); PG8_BAR; PG8_MMA(1, 0, At, B0); PG8_MMA(1, 1, At, B1); PG8_BAR; PG8_SCHED;
;             PG8_LDB(B0, 1, 0); PG8_LDB(B1, 1, 1); PG8_SCHED; PG8_LDA(At, 1, 0); PG8_STAGE(PG8_SA(0, 1), a2 + hstep, voffA);
;             PG8_WAIT_V(8); PG8_WAIT_L(0); PG8_BAR; PG8_MMA(0, 0, At, B0); PG8_MMA(0, 1, At, B1); PG8_BAR; PG8_SCHED;
	v_mfma_f32_16x16x32_bf16 v[60:63], v[140:143], v[178:181], v[60:63]
	v_mfma_f32_16x16x32_bf16 v[56:59], v[154:157], v[178:181], v[56:59]
	v_mfma_f32_16x16x32_bf16 v[52:55], v[140:143], v[186:189], v[52:55]
	v_mfma_f32_16x16x32_bf16 v[48:51], v[154:157], v[186:189], v[48:51]
	v_mfma_f32_16x16x32_bf16 v[44:47], v[140:143], v[194:197], v[44:47]
	v_mfma_f32_16x16x32_bf16 v[40:43], v[154:157], v[194:197], v[40:43]
	v_mfma_f32_16x16x32_bf16 v[36:39], v[140:143], v[202:205], v[36:39]
	v_mfma_f32_16x16x32_bf16 v[32:35], v[154:157], v[202:205], v[32:35]
	v_mfma_f32_16x16x32_bf16 v[60:63], v[150:153], v[182:185], v[60:63]
	v_mfma_f32_16x16x32_bf16 v[56:59], v[158:161], v[182:185], v[56:59]
	v_mfma_f32_16x16x32_bf16 v[52:55], v[150:153], v[190:193], v[52:55]
	v_mfma_f32_16x16x32_bf16 v[48:51], v[158:161], v[190:193], v[48:51]
	v_mfma_f32_16x16x32_bf16 v[44:47], v[150:153], v[198:201], v[44:47]
	v_mfma_f32_16x16x32_bf16 v[40:43], v[158:161], v[198:201], v[40:43]
	v_mfma_f32_16x16x32_bf16 v[36:39], v[150:153], v[206:209], v[36:39]
	v_mfma_f32_16x16x32_bf16 v[32:35], v[158:161], v[206:209], v[32:35]
	v_mfma_f32_16x16x32_bf16 v[28:31], v[162:165], v[178:181], v[28:31]
	v_mfma_f32_16x16x32_bf16 v[24:27], v[170:173], v[178:181], v[24:27]
	v_mfma_f32_16x16x32_bf16 v[20:23], v[162:165], v[186:189], v[20:23]
	v_mfma_f32_16x16x32_bf16 v[16:19], v[170:173], v[186:189], v[16:19]
	v_mfma_f32_16x16x32_bf16 v[12:15], v[162:165], v[194:197], v[12:15]
	v_mfma_f32_16x16x32_bf16 v[8:11], v[170:173], v[194:197], v[8:11]
	v_mfma_f32_16x16x32_bf16 v[4:7], v[162:165], v[202:205], v[4:7]
	v_mfma_f32_16x16x32_bf16 v[0:3], v[170:173], v[202:205], v[0:3]
	v_mfma_f32_16x16x32_bf16 v[28:31], v[166:169], v[182:185], v[28:31]
	v_mfma_f32_16x16x32_bf16 v[24:27], v[174:177], v[182:185], v[24:27]
	v_mfma_f32_16x16x32_bf16 v[20:23], v[166:169], v[190:193], v[20:23]
	v_mfma_f32_16x16x32_bf16 v[16:19], v[174:177], v[190:193], v[16:19]
	v_mfma_f32_16x16x32_bf16 v[12:15], v[166:169], v[198:201], v[12:15]
	v_mfma_f32_16x16x32_bf16 v[8:11], v[174:177], v[198:201], v[8:11]
	v_mfma_f32_16x16x32_bf16 v[4:7], v[166:169], v[206:209], v[4:7]
	v_mfma_f32_16x16x32_bf16 v[0:3], v[174:177], v[206:209], v[0:3]
	s_barrier
	s_setprio 0
	s_add_i32 s25, 0, 0x18000
	v_add_u32_e32 v149, s25, v146
	s_add_i32 s52, 0, 0x1c000
	ds_read_b128 v[140:143], v149
	ds_read_b128 v[150:153], v149 offset:1024
	ds_read_b128 v[154:157], v149 offset:2048
	ds_read_b128 v[158:161], v149 offset:3072
	v_add_u32_e32 v149, s52, v146
	ds_read_b128 v[162:165], v149
	ds_read_b128 v[166:169], v149 offset:1024
	ds_read_b128 v[170:173], v149 offset:2048
	ds_read_b128 v[174:177], v149 offset:3072
	s_add_u32 s44, s44, 0x100000
	s_addc_u32 s45, s45, 0
	s_mov_b32 m0, s51
	v_lshl_add_u64 v[210:211], s[44:45], 0, v[134:135]
	ds_read_b128 v[178:181], v148 offset:32768
	ds_read_b128 v[182:185], v148 offset:33792
	ds_read_b128 v[186:189], v148 offset:34816
	ds_read_b128 v[190:193], v148 offset:35840
	ds_read_b128 v[194:197], v148 offset:36864
	ds_read_b128 v[198:201], v148 offset:37888
	ds_read_b128 v[202:205], v148 offset:38912
	ds_read_b128 v[206:209], v148 offset:39936
	global_load_lds_dwordx4 v[210:211], off
	v_lshl_add_u64 v[210:211], s[44:45], 0, v[130:131]
	s_mov_b32 m0, s54
	s_nop 0
	global_load_lds_dwordx4 v[210:211], off
	s_waitcnt vmcnt(8)
	s_waitcnt lgkmcnt(0)
	s_setprio 1
	s_barrier
	v_mfma_f32_16x16x32_bf16 v[124:127], v[140:143], v[178:181], v[124:127]
	v_mfma_f32_16x16x32_bf16 v[120:123], v[154:157], v[178:181], v[120:123]
	v_mfma_f32_16x16x32_bf16 v[116:119], v[140:143], v[186:189], v[116:119]
	v_mfma_f32_16x16x32_bf16 v[112:115], v[154:157], v[186:189], v[112:115]
	v_mfma_f32_16x16x32_bf16 v[108:111], v[140:143], v[194:197], v[108:111]
	v_mfma_f32_16x16x32_bf16 v[104:107], v[154:157], v[194:197], v[104:107]
	v_mfma_f32_16x16x32_bf16 v[100:103], v[140:143], v[202:205], v[100:103]
	v_mfma_f32_16x16x32_bf16 v[96:99], v[154:157], v[202:205], v[96:99]
	v_mfma_f32_16x16x32_bf16 v[124:127], v[150:153], v[182:185], v[124:127]
	v_mfma_f32_16x16x32_bf16 v[120:123], v[158:161], v[182:185], v[120:123]
	v_mfma_f32_16x16x32_bf16 v[116:119], v[150:153], v[190:193], v[116:119]
	v_mfma_f32_16x16x32_bf16 v[112:115], v[158:161], v[190:193], v[112:115]
	v_mfma_f32_16x16x32_bf16 v[108:111], v[150:153], v[198:201], v[108:111]
	v_mfma_f32_16x16x32_bf16 v[104:107], v[158:161], v[198:201], v[104:107]
	v_mfma_f32_16x16x32_bf16 v[100:103], v[150:153], v[206:209], v[100:103]
	v_mfma_f32_16x16x32_bf16 v[96:99], v[158:161], v[206:209], v[96:99]
	v_mfma_f32_16x16x32_bf16 v[92:95], v[162:165], v[178:181], v[92:95]
	v_mfma_f32_16x16x32_bf16 v[88:91], v[170:173], v[178:181], v[88:91]
	v_mfma_f32_16x16x32_bf16 v[84:87], v[162:165], v[186:189], v[84:87]
	v_mfma_f32_16x16x32_bf16 v[80:83], v[170:173], v[186:189], v[80:83]
	v_mfma_f32_16x16x32_bf16 v[76:79], v[162:165], v[194:197], v[76:79]
	v_mfma_f32_16x16x32_bf16 v[72:75], v[170:173], v[194:197], v[72:75]
	v_mfma_f32_16x16x32_bf16 v[68:71], v[162:165], v[202:205], v[68:71]
	v_mfma_f32_16x16x32_bf16 v[64:67], v[170:173], v[202:205], v[64:67]
	v_mfma_f32_16x16x32_bf16 v[92:95], v[166:169], v[182:185], v[92:95]
	v_mfma_f32_16x16x32_bf16 v[88:91], v[174:177], v[182:185], v[88:91]
	v_mfma_f32_16x16x32_bf16 v[84:87], v[166:169], v[190:193], v[84:87]
	v_mfma_f32_16x16x32_bf16 v[80:83], v[174:177], v[190:193], v[80:83]
	v_mfma_f32_16x16x32_bf16 v[76:79], v[166:169], v[198:201], v[76:79]
	v_mfma_f32_16x16x32_bf16 v[72:75], v[174:177], v[198:201], v[72:75]
	v_mfma_f32_16x16x32_bf16 v[68:71], v[166:169], v[206:209], v[68:71]
	v_mfma_f32_16x16x32_bf16 v[64:67], v[174:177], v[206:209], v[64:67]
	s_barrier
; #define PG8_STAGE(bufoff, gbase, voff) do { _Pragma("unroll") for (int _i = 0; _i < 2; ++_i) \
;         __builtin_amdgcn_global_load_lds((const unsigned*)((const char*)(gbase) + (voff)[_i]), (PG8_LAS unsigned*)(lds + (bufoff) + ldsw + _i * 8192), 16, 0, 0); } while (0)
; #define PG8_LDA(dst, b, h) do { _Pragma("unroll") for (int m = 0; m < 4; ++m) _Pragma("unroll") for (int k = 0; k < 2; ++k) dst[m][k] = *(const PG8_LAS bf16x8*)(lds + PG8_SA(b, h) + aoff + m * 2048 + k * 1024); } while (0)
; #define PG8_WAIT_V(n) asm volatile("s_waitcnt vmcnt(" #n ")" ::: "memory")
; #define PG8_WAIT_L(n) asm volatile("s_waitcnt lgkmcnt(" #n ")" ::: "memory")
; #define PG8_BAR __builtin_amdgcn_s_barrier()
; #define PG8_SCHED __builtin_amdgcn_sched_barrier(0)
; template <class Epi, class Sched, bool ALIGN_EPI = false, bool SP2 = false, bool F8 = false>
; __device__ __forceinline__ void gemm_phase(PG8_LAS unsigned char* lds, const int K, const Sched& S, const Epi& E, const int wave) {
;     ...
;             PG8_LDA(At, 1, 1); PG8_STAGE(PG8_SB(1, 0), b3, voffB); PG8_STAGE(PG8_SB(1, 1), b3 + hstep, voffB); PG8_STAGE(PG8_SA(1, 0), a3, voffA);
;             PG8_WAIT_V(8); PG8_WAIT_L(0); PG8_BAR; PG8_MMA(1, 0, At, B0); PG8_MMA(1, 1, At, B1); PG8_BAR; PG8_SCHED;
	s_setprio 0
	s_add_i32 s25, s25, s48
	v_lshl_add_u64 v[210:211], s[42:43], 0, v[132:133]
	s_mov_b32 m0, s25
	ds_read_b128 v[178:181], v148 offset:49152
	ds_read_b128 v[182:185], v148 offset:50176
	ds_read_b128 v[186:189], v148 offset:51200
	ds_read_b128 v[190:193], v148 offset:52224
	ds_read_b128 v[194:197], v148 offset:53248
	ds_read_b128 v[198:201], v148 offset:54272
	ds_read_b128 v[202:205], v148 offset:55296
	ds_read_b128 v[206:209], v148 offset:56320
	global_load_lds_dwordx4 v[210:211], off
	s_add_i32 m0, s25, 0x2000
	v_lshl_add_u64 v[210:211], s[42:43], 0, v[128:129]
	s_add_u32 s42, s42, 0x100000
	s_addc_u32 s43, s43, 0
	s_add_i32 s25, s52, s48
	global_load_lds_dwordx4 v[210:211], off
	v_lshl_add_u64 v[210:211], s[42:43], 0, v[132:133]
	s_mov_b32 m0, s25
	s_nop 0
	global_load_lds_dwordx4 v[210:211], off
	v_lshl_add_u64 v[210:211], s[42:43], 0, v[128:129]
	s_add_i32 m0, s25, 0x2000
	s_nop 0
	global_load_lds_dwordx4 v[210:211], off
	v_lshl_add_u64 v[210:211], s[40:41], 0, v[134:135]
	s_mov_b32 m0, s55
	s_nop 0
	global_load_lds_dwordx4 v[210:211], off
	v_lshl_add_u64 v[210:211], s[40:41], 0, v[130:131]
	s_mov_b32 m0, s57
	s_nop 0
	global_load_lds_dwordx4 v[210:211], off
	s_waitcnt vmcnt(8)
	s_waitcnt lgkmcnt(0)
	s_setprio 1
	s_barrier
	v_mfma_f32_16x16x32_bf16 v[60:63], v[140:143], v[178:181], v[60:63]
	v_mfma_f32_16x16x32_bf16 v[56:59], v[154:157], v[178:181], v[56:59]
	v_mfma_f32_16x16x32_bf16 v[52:55], v[140:143], v[186:189], v[52:55]
	v_mfma_f32_16x16x32_bf16 v[48:51], v[154:157], v[186:189], v[48:51]
	v_mfma_f32_16x16x32_bf16 v[44:47], v[140:143], v[194:197], v[44:47]
	v_mfma_f32_16x16x32_bf16 v[40:43], v[154:157], v[194:197], v[40:43]
	v_mfma_f32_16x16x32_bf16 v[36:39], v[140:143], v[202:205], v[36:39]
	v_mfma_f32_16x16x32_bf16 v[32:35], v[154:157], v[202:205], v[32:35]
	v_mfma_f32_16x16x32_bf16 v[60:63], v[150:153], v[182:185], v[60:63]
	v_mfma_f32_16x16x32_bf16 v[56:59], v[158:161], v[182:185], v[56:59]
	v_mfma_f32_16x16x32_bf16 v[52:55], v[150:153], v[190:193], v[52:55]
	v_mfma_f32_16x16x32_bf16 v[48:51], v[158:161], v[190:193], v[48:51]
	v_mfma_f32_16x16x32_bf16 v[44:47], v[150:153], v[198:201], v[44:47]
	v_mfma_f32_16x16x32_bf16 v[40:43], v[158:161], v[198:201], v[40:43]
	v_mfma_f32_16x16x32_bf16 v[36:39], v[150:153], v[206:209], v[36:39]
	v_mfma_f32_16x16x32_bf16 v[32:35], v[158:161], v[206:209], v[32:35]
	v_mfma_f32_16x16x32_bf16 v[28:31], v[162:165], v[178:181], v[28:31]
	v_mfma_f32_16x16x32_bf16 v[24:27], v[170:173], v[178:181], v[24:27]
	v_mfma_f32_16x16x32_bf16 v[20:23], v[162:165], v[186:189], v[20:23]
	v_mfma_f32_16x16x32_bf16 v[16:19], v[170:173], v[186:189], v[16:19]
	v_mfma_f32_16x16x32_bf16 v[12:15], v[162:165], v[194:197], v[12:15]
	v_mfma_f32_16x16x32_bf16 v[8:11], v[170:173], v[194:197], v[8:11]
	v_mfma_f32_16x16x32_bf16 v[4:7], v[162:165], v[202:205], v[4:7]
	v_mfma_f32_16x16x32_bf16 v[0:3], v[170:173], v[202:205], v[0:3]
	v_mfma_f32_16x16x32_bf16 v[28:31], v[166:169], v[182:185], v[28:31]
	v_mfma_f32_16x16x32_bf16 v[24:27], v[174:177], v[182:185], v[24:27]
	v_mfma_f32_16x16x32_bf16 v[20:23], v[166:169], v[190:193], v[20:23]
	v_mfma_f32_16x16x32_bf16 v[16:19], v[174:177], v[190:193], v[16:19]
	v_mfma_f32_16x16x32_bf16 v[12:15], v[166:169], v[198:201], v[12:15]
	v_mfma_f32_16x16x32_bf16 v[8:11], v[174:177], v[198:201], v[8:11]
	v_mfma_f32_16x16x32_bf16 v[4:7], v[166:169], v[206:209], v[4:7]
	v_mfma_f32_16x16x32_bf16 v[0:3], v[174:177], v[206:209], v[0:3]
	s_barrier
	s_setprio 0
	s_add_i32 s23, s23, 2
	s_add_u32 s38, s38, 0x100
	s_addc_u32 s39, s39, 0
	s_cmp_gt_u32 s23, 61
	s_cbranch_scc0 .LBB0_1240
	s_and_b64 vcc, exec, s[18:19]
	s_cbranch_vccz .LBB0_1243
	s_barrier

; #define PG8_STAGE(bufoff, gbase, voff) do { _Pragma("unroll") for (int _i = 0; _i < 2; ++_i) \
;         __builtin_amdgcn_global_load_lds((const unsigned*)((const char*)(gbase) + (voff)[_i]), (PG8_LAS unsigned*)(lds + (bufoff) + ldsw + _i * 8192), 16, 0, 0); } while (0)
; #define PG8_LDA(dst, b, h) do { _Pragma("unroll") for (int m = 0; m < 4; ++m) _Pragma("unroll") for (int k = 0; k < 2; ++k) dst[m][k] = *(const PG8_LAS bf16x8*)(lds + PG8_SA(b, h) + aoff + m * 2048 + k * 1024); } while (0)
; #define PG8_LDB(dst, b, h) do { _Pragma("unroll") for (int n = 0; n < 2; ++n) _Pragma("unroll") for (int k = 0; k < 2; ++k) dst[n][k] = *(const PG8_LAS bf16x8*)(lds + PG8_SB(b, h) + boff + n * 2048 + k * 1024); } while (0)
; #define PG8_WAIT_V(n) asm volatile("s_waitcnt vmcnt(" #n ")" ::: "memory")
; #define PG8_WAIT_L(n) asm volatile("s_waitcnt lgkmcnt(" #n ")" ::: "memory")
; #define PG8_BAR __builtin_amdgcn_s_barrier()
; #define PG8_SCHED __builtin_amdgcn_sched_barrier(0)
; template <class Epi, class Sched, bool ALIGN_EPI = false, bool SP2 = false, bool F8 = false>
; __device__ __forceinline__ void gemm_phase(PG8_LAS unsigned char* lds, const int K, const Sched& S, const Epi& E, const int wave) {
;     ...
;             const bool last = (t == nt - 2);
;             const char* a1 = cA + (size_t)(t + 1) * kstep;
;             const char* a2 = last ? nA : cA + (size_t)(t + 2) * kstep; const char* b2 = last ? nB : cB + (size_t)(t + 2) * kstep;
;             const char* a3 = a2 + kstep; const char* b3 = b2 + kstep;
;             asm volatile("" : "+s"(a1), "+s"(a2), "+s"(b2), "+s"(a3), "+s"(b3));
;             if (last && has_next) S.a_ready(nxt);
;             if constexpr (Epi::KHOOK) { if (cur.prob == 2 ? (t == 16) : (t == 32 || t == 48)) { if (wr == 0) PG8_BAR;
;                 E.khook(acc, cur, (cur.prob == 2 || t == 48) ? 1 : 0, wr, wc, fr, fq); if (wr == 1) PG8_BAR; } }
;             if constexpr (SP2) {
;             PG8_LDB(B0, 0, 0); PG8_LDB(B1, 0, 1); PG8_SCHED; PG8_LDA(At, 0, 0); PG8_STAGE(PG8_SA(1, 1), a1 + hstep, voffA);
;             PG8_WAIT_V(8); PG8_WAIT_L(0); PG8_BAR; PG8_MMA(0, 0, At, B0); PG8_MMA(0, 1, At, B1); PG8_BAR; PG8_SCHED;
;             PG8_LDA(At, 0, 1); PG8_STAGE(PG8_SB(0, 0), b2, voffB); PG8_STAGE(PG8_SB(0, 1), b2 + hstep, voffB); PG8_STAGE(PG8_SA(0, 0), a2, voffA);
.LBB0_1348:
	s_add_i32 s87, s8, 2
	s_cmp_eq_u32 s82, s8
	s_cselect_b32 s40, s79, s83
	s_cselect_b32 s41, s78, s84
	s_cselect_b32 s43, s80, s86
	s_cselect_b32 s42, s81, s85
	s_add_u32 s8, s40, 0x80
	s_addc_u32 s9, s41, 0
	s_add_u32 s38, s42, 0x80
	s_addc_u32 s39, s43, 0
	s_mov_b64 s[88:89], s[6:7]
	v_add_u32_e32 v1, s67, v166
	ds_read_b128 v[132:135], v1
	ds_read_b128 v[136:139], v1 offset:1024
	ds_read_b128 v[156:159], v1 offset:2048
	ds_read_b128 v[160:163], v1 offset:3072
	v_add_u32_e32 v1, s72, v166
	ds_read_b128 v[170:173], v1
	ds_read_b128 v[174:177], v1 offset:1024
	ds_read_b128 v[178:181], v1 offset:2048
	ds_read_b128 v[182:185], v1 offset:3072
	s_add_u32 s88, s88, 0x2b0000
	s_addc_u32 s89, s89, 0
	v_lshl_add_u64 v[2:3], s[88:89], 0, v[140:141]
	s_add_i32 m0, s58, 0xc000
	ds_read_b128 v[186:189], v168
	ds_read_b128 v[190:193], v168 offset:1024
	ds_read_b128 v[194:197], v168 offset:2048
	ds_read_b128 v[198:201], v168 offset:3072
	ds_read_b128 v[202:205], v168 offset:4096
	ds_read_b128 v[206:209], v168 offset:5120
	ds_read_b128 v[210:213], v168 offset:6144
	ds_read_b128 v[214:217], v168 offset:7168
	global_load_lds_dwordx4 v[2:3], off
	v_lshl_add_u64 v[2:3], s[88:89], 0, v[144:145]
	s_add_i32 m0, s58, 0xe000
	s_nop 0
	global_load_lds_dwordx4 v[2:3], off
	s_waitcnt vmcnt(8)
	s_waitcnt lgkmcnt(0)
	s_setprio 1
	s_barrier
	v_mfma_f32_16x16x32_bf16 v[128:131], v[132:135], v[186:189], v[128:131]
	v_mfma_f32_16x16x32_bf16 v[124:127], v[156:159], v[186:189], v[124:127]
	v_mfma_f32_16x16x32_bf16 v[120:123], v[132:135], v[194:197], v[120:123]
	v_mfma_f32_16x16x32_bf16 v[116:119], v[156:159], v[194:197], v[116:119]
	v_mfma_f32_16x16x32_bf16 v[112:115], v[132:135], v[202:205], v[112:115]
	v_mfma_f32_16x16x32_bf16 v[108:111], v[156:159], v[202:205], v[108:111]
	v_mfma_f32_16x16x32_bf16 v[104:107], v[132:135], v[210:213], v[104:107]
	v_mfma_f32_16x16x32_bf16 v[100:103], v[156:159], v[210:213], v[100:103]
	v_mfma_f32_16x16x32_bf16 v[128:131], v[136:139], v[190:193], v[128:131]
	v_mfma_f32_16x16x32_bf16 v[124:127], v[160:163], v[190:193], v[124:127]
	v_mfma_f32_16x16x32_bf16 v[120:123], v[136:139], v[198:201], v[120:123]
	v_mfma_f32_16x16x32_bf16 v[116:119], v[160:163], v[198:201], v[116:119]
	v_mfma_f32_16x16x32_bf16 v[112:115], v[136:139], v[206:209], v[112:115]
	v_mfma_f32_16x16x32_bf16 v[108:111], v[160:163], v[206:209], v[108:111]
	v_mfma_f32_16x16x32_bf16 v[104:107], v[136:139], v[214:217], v[104:107]
	v_mfma_f32_16x16x32_bf16 v[100:103], v[160:163], v[214:217], v[100:103]
	v_mfma_f32_16x16x32_bf16 v[96:99], v[170:173], v[186:189], v[96:99]
	v_mfma_f32_16x16x32_bf16 v[92:95], v[178:181], v[186:189], v[92:95]
	v_mfma_f32_16x16x32_bf16 v[88:91], v[170:173], v[194:197], v[88:91]
	v_mfma_f32_16x16x32_bf16 v[84:87], v[178:181], v[194:197], v[84:87]
	v_mfma_f32_16x16x32_bf16 v[80:83], v[170:173], v[202:205], v[80:83]
	v_mfma_f32_16x16x32_bf16 v[76:79], v[178:181], v[202:205], v[76:79]
	v_mfma_f32_16x16x32_bf16 v[72:75], v[170:173], v[210:213], v[72:75]
	v_mfma_f32_16x16x32_bf16 v[68:71], v[178:181], v[210:213], v[68:71]
	v_mfma_f32_16x16x32_bf16 v[96:99], v[174:177], v[190:193], v[96:99]
	v_mfma_f32_16x16x32_bf16 v[92:95], v[182:185], v[190:193], v[92:95]
	v_mfma_f32_16x16x32_bf16 v[88:91], v[174:177], v[198:201], v[88:91]
	v_mfma_f32_16x16x32_bf16 v[84:87], v[182:185], v[198:201], v[84:87]
	v_mfma_f32_16x16x32_bf16 v[80:83], v[174:177], v[206:209], v[80:83]
	v_mfma_f32_16x16x32_bf16 v[76:79], v[182:185], v[206:209], v[76:79]
	v_mfma_f32_16x16x32_bf16 v[72:75], v[174:177], v[214:217], v[72:75]
	v_mfma_f32_16x16x32_bf16 v[68:71], v[182:185], v[214:217], v[68:71]
	s_barrier
	s_setprio 0
	s_add_i32 s88, s67, s57
	v_lshl_add_u64 v[2:3], s[42:43], 0, v[142:143]
	s_mov_b32 m0, s88
	ds_read_b128 v[186:189], v168 offset:16384
	ds_read_b128 v[190:193], v168 offset:17408
	ds_read_b128 v[194:197], v168 offset:18432
	ds_read_b128 v[198:201], v168 offset:19456
	ds_read_b128 v[202:205], v168 offset:20480
	ds_read_b128 v[206:209], v168 offset:21504
	ds_read_b128 v[210:213], v168 offset:22528
	ds_read_b128 v[214:217], v168 offset:23552
	global_load_lds_dwordx4 v[2:3], off
	s_add_i32 m0, s88, 0x2000
	v_lshl_add_u64 v[2:3], s[42:43], 0, v[146:147]
	s_add_u32 s42, s42, 0x2b0000
	s_addc_u32 s43, s43, 0
	s_add_i32 s88, s72, s57
	global_load_lds_dwordx4 v[2:3], off
	v_lshl_add_u64 v[2:3], s[42:43], 0, v[142:143]
	s_mov_b32 m0, s88
	s_nop 0
	global_load_lds_dwordx4 v[2:3], off
	v_lshl_add_u64 v[2:3], s[42:43], 0, v[146:147]
	s_add_i32 m0, s88, 0x2000
	s_nop 0
	global_load_lds_dwordx4 v[2:3], off
	v_lshl_add_u64 v[2:3], s[40:41], 0, v[140:141]
	s_mov_b32 m0, s58
	s_nop 0
	global_load_lds_dwordx4 v[2:3], off
	v_lshl_add_u64 v[2:3], s[40:41], 0, v[144:145]
	s_mov_b32 m0, s59
	s_nop 0
	global_load_lds_dwordx4 v[2:3], off
	s_waitcnt vmcnt(8)
	s_waitcnt lgkmcnt(0)
	s_setprio 1
	s_barrier
; #define PG8_STAGE(bufoff, gbase, voff) do { _Pragma("unroll") for (int _i = 0; _i < 2; ++_i) \
;         __builtin_amdgcn_global_load_lds((const unsigned*)((const char*)(gbase) + (voff)[_i]), (PG8_LAS unsigned*)(lds + (bufoff) + ldsw + _i * 8192), 16, 0, 0); } while (0)
; #define PG8_LDA(dst, b, h) do { _Pragma("unroll") for (int m = 0; m < 4; ++m) _Pragma("unroll") for (int k = 0; k < 2; ++k) dst[m][k] = *(const PG8_LAS bf16x8*)(lds + PG8_SA(b, h) + aoff + m * 2048 + k * 1024); } while (0)
; #define PG8_LDB(dst, b, h) do { _Pragma("unroll") for (int n = 0; n < 2; ++n) _Pragma("unroll") for (int k = 0; k < 2; ++k) dst[n][k] = *(const PG8_LAS bf16x8*)(lds + PG8_SB(b, h) + boff + n * 2048 + k * 1024); } while (0)
; #define PG8_WAIT_V(n) asm volatile("s_waitcnt vmcnt(" #n ")" ::: "memory")
; #define PG8_WAIT_L(n) asm volatile("s_waitcnt lgkmcnt(" #n ")" ::: "memory")
; #define PG8_BAR __builtin_amdgcn_s_barrier()
; #define PG8_SCHED __builtin_amdgcn_sched_barrier(0)
; template <class Epi, class Sched, bool ALIGN_EPI = false, bool SP2 = false, bool F8 = false>
; __device__ __forceinline__ void gemm_phase(PG8_LAS unsigned char* lds, const int K, const Sched& S, const Epi& E, const int wave) {
;     ...
;             PG8_WAIT_V(8); PG8_WAIT_L(0); PG8_BAR; PG8_MMA(1, 0, At, B0); PG8_MMA(1, 1, At, B1); PG8_BAR; PG8_SCHED;
;             PG8_LDB(B0, 1, 0); PG8_LDB(B1, 1, 1); PG8_SCHED; PG8_LDA(At, 1, 0); PG8_STAGE(PG8_SA(0, 1), a2 + hstep, voffA);
;             PG8_WAIT_V(8); PG8_WAIT_L(0); PG8_BAR; PG8_MMA(0, 0, At, B0); PG8_MMA(0, 1, At, B1); PG8_BAR; PG8_SCHED;
	v_mfma_f32_16x16x32_bf16 v[64:67], v[132:135], v[186:189], v[64:67]
	v_mfma_f32_16x16x32_bf16 v[60:63], v[156:159], v[186:189], v[60:63]
	v_mfma_f32_16x16x32_bf16 v[56:59], v[132:135], v[194:197], v[56:59]
	v_mfma_f32_16x16x32_bf16 v[52:55], v[156:159], v[194:197], v[52:55]
	v_mfma_f32_16x16x32_bf16 v[48:51], v[132:135], v[202:205], v[48:51]
	v_mfma_f32_16x16x32_bf16 v[44:47], v[156:159], v[202:205], v[44:47]
	v_mfma_f32_16x16x32_bf16 v[40:43], v[132:135], v[210:213], v[40:43]
	v_mfma_f32_16x16x32_bf16 v[36:39], v[156:159], v[210:213], v[36:39]
	v_mfma_f32_16x16x32_bf16 v[64:67], v[136:139], v[190:193], v[64:67]
	v_mfma_f32_16x16x32_bf16 v[60:63], v[160:163], v[190:193], v[60:63]
	v_mfma_f32_16x16x32_bf16 v[56:59], v[136:139], v[198:201], v[56:59]
	v_mfma_f32_16x16x32_bf16 v[52:55], v[160:163], v[198:201], v[52:55]
	v_mfma_f32_16x16x32_bf16 v[48:51], v[136:139], v[206:209], v[48:51]
	v_mfma_f32_16x16x32_bf16 v[44:47], v[160:163], v[206:209], v[44:47]
	v_mfma_f32_16x16x32_bf16 v[40:43], v[136:139], v[214:217], v[40:43]
	v_mfma_f32_16x16x32_bf16 v[36:39], v[160:163], v[214:217], v[36:39]
	v_mfma_f32_16x16x32_bf16 v[32:35], v[170:173], v[186:189], v[32:35]
	v_mfma_f32_16x16x32_bf16 v[28:31], v[178:181], v[186:189], v[28:31]
	v_mfma_f32_16x16x32_bf16 v[24:27], v[170:173], v[194:197], v[24:27]
	v_mfma_f32_16x16x32_bf16 v[20:23], v[178:181], v[194:197], v[20:23]
	v_mfma_f32_16x16x32_bf16 v[16:19], v[170:173], v[202:205], v[16:19]
	v_mfma_f32_16x16x32_bf16 v[12:15], v[178:181], v[202:205], v[12:15]
	v_mfma_f32_16x16x32_bf16 v[8:11], v[170:173], v[210:213], v[8:11]
	v_mfma_f32_16x16x32_bf16 v[2:5], v[178:181], v[210:213], v[4:7]
	v_mfma_f32_16x16x32_bf16 v[32:35], v[174:177], v[190:193], v[32:35]
	v_mfma_f32_16x16x32_bf16 v[28:31], v[182:185], v[190:193], v[28:31]
	v_mfma_f32_16x16x32_bf16 v[24:27], v[174:177], v[198:201], v[24:27]
	v_mfma_f32_16x16x32_bf16 v[20:23], v[182:185], v[198:201], v[20:23]
	v_mfma_f32_16x16x32_bf16 v[16:19], v[174:177], v[206:209], v[16:19]
	v_mfma_f32_16x16x32_bf16 v[12:15], v[182:185], v[206:209], v[12:15]
	v_mfma_f32_16x16x32_bf16 v[8:11], v[174:177], v[214:217], v[8:11]
	v_mfma_f32_16x16x32_bf16 v[2:5], v[182:185], v[214:217], v[2:5]
	s_barrier
	s_setprio 0
	s_add_i32 s42, 0, 0x18000
	v_add_u32_e32 v1, s42, v166
	s_add_i32 s43, 0, 0x1c000
	ds_read_b128 v[132:135], v1
	ds_read_b128 v[136:139], v1 offset:1024
	ds_read_b128 v[156:159], v1 offset:2048
	ds_read_b128 v[160:163], v1 offset:3072
	v_add_u32_e32 v1, s43, v166
	ds_read_b128 v[170:173], v1
	ds_read_b128 v[174:177], v1 offset:1024
	ds_read_b128 v[178:181], v1 offset:2048
	ds_read_b128 v[182:185], v1 offset:3072
	s_add_u32 s40, s40, 0x2b0000
	s_addc_u32 s41, s41, 0
	s_mov_b32 m0, s60
	v_lshl_add_u64 v[6:7], s[40:41], 0, v[140:141]
	ds_read_b128 v[186:189], v168 offset:32768
	ds_read_b128 v[190:193], v168 offset:33792
	ds_read_b128 v[194:197], v168 offset:34816
	ds_read_b128 v[198:201], v168 offset:35840
	ds_read_b128 v[202:205], v168 offset:36864
	ds_read_b128 v[206:209], v168 offset:37888
	ds_read_b128 v[210:213], v168 offset:38912
	ds_read_b128 v[214:217], v168 offset:39936
	global_load_lds_dwordx4 v[6:7], off
	v_lshl_add_u64 v[6:7], s[40:41], 0, v[144:145]
	s_mov_b32 m0, s61
	s_nop 0
	global_load_lds_dwordx4 v[6:7], off
	s_waitcnt vmcnt(8)
	s_waitcnt lgkmcnt(0)
	s_setprio 1
	s_barrier
	v_mfma_f32_16x16x32_bf16 v[128:131], v[132:135], v[186:189], v[128:131]
	v_mfma_f32_16x16x32_bf16 v[124:127], v[156:159], v[186:189], v[124:127]
	v_mfma_f32_16x16x32_bf16 v[120:123], v[132:135], v[194:197], v[120:123]
	v_mfma_f32_16x16x32_bf16 v[116:119], v[156:159], v[194:197], v[116:119]
	v_mfma_f32_16x16x32_bf16 v[112:115], v[132:135], v[202:205], v[112:115]
	v_mfma_f32_16x16x32_bf16 v[108:111], v[156:159], v[202:205], v[108:111]
	v_mfma_f32_16x16x32_bf16 v[104:107], v[132:135], v[210:213], v[104:107]
	v_mfma_f32_16x16x32_bf16 v[100:103], v[156:159], v[210:213], v[100:103]
	v_mfma_f32_16x16x32_bf16 v[128:131], v[136:139], v[190:193], v[128:131]
	v_mfma_f32_16x16x32_bf16 v[124:127], v[160:163], v[190:193], v[124:127]
	v_mfma_f32_16x16x32_bf16 v[120:123], v[136:139], v[198:201], v[120:123]
	v_mfma_f32_16x16x32_bf16 v[116:119], v[160:163], v[198:201], v[116:119]
	v_mfma_f32_16x16x32_bf16 v[112:115], v[136:139], v[206:209], v[112:115]
	v_mfma_f32_16x16x32_bf16 v[108:111], v[160:163], v[206:209], v[108:111]
	v_mfma_f32_16x16x32_bf16 v[104:107], v[136:139], v[214:217], v[104:107]
	v_mfma_f32_16x16x32_bf16 v[100:103], v[160:163], v[214:217], v[100:103]
	v_mfma_f32_16x16x32_bf16 v[96:99], v[170:173], v[186:189], v[96:99]
	v_mfma_f32_16x16x32_bf16 v[92:95], v[178:181], v[186:189], v[92:95]
	v_mfma_f32_16x16x32_bf16 v[88:91], v[170:173], v[194:197], v[88:91]
	v_mfma_f32_16x16x32_bf16 v[84:87], v[178:181], v[194:197], v[84:87]
	v_mfma_f32_16x16x32_bf16 v[80:83], v[170:173], v[202:205], v[80:83]
	v_mfma_f32_16x16x32_bf16 v[76:79], v[178:181], v[202:205], v[76:79]
	v_mfma_f32_16x16x32_bf16 v[72:75], v[170:173], v[210:213], v[72:75]
	v_mfma_f32_16x16x32_bf16 v[68:71], v[178:181], v[210:213], v[68:71]
	v_mfma_f32_16x16x32_bf16 v[96:99], v[174:177], v[190:193], v[96:99]
	v_mfma_f32_16x16x32_bf16 v[92:95], v[182:185], v[190:193], v[92:95]
	v_mfma_f32_16x16x32_bf16 v[88:91], v[174:177], v[198:201], v[88:91]
	v_mfma_f32_16x16x32_bf16 v[84:87], v[182:185], v[198:201], v[84:87]
	v_mfma_f32_16x16x32_bf16 v[80:83], v[174:177], v[206:209], v[80:83]
	v_mfma_f32_16x16x32_bf16 v[76:79], v[182:185], v[206:209], v[76:79]
	v_mfma_f32_16x16x32_bf16 v[72:75], v[174:177], v[214:217], v[72:75]
	v_mfma_f32_16x16x32_bf16 v[68:71], v[182:185], v[214:217], v[68:71]
	s_barrier
; #define PG8_STAGE(bufoff, gbase, voff) do { _Pragma("unroll") for (int _i = 0; _i < 2; ++_i) \
;         __builtin_amdgcn_global_load_lds((const unsigned*)((const char*)(gbase) + (voff)[_i]), (PG8_LAS unsigned*)(lds + (bufoff) + ldsw + _i * 8192), 16, 0, 0); } while (0)
; #define PG8_LDA(dst, b, h) do { _Pragma("unroll") for (int m = 0; m < 4; ++m) _Pragma("unroll") for (int k = 0; k < 2; ++k) dst[m][k] = *(const PG8_LAS bf16x8*)(lds + PG8_SA(b, h) + aoff + m * 2048 + k * 1024); } while (0)
; #define PG8_WAIT_V(n) asm volatile("s_waitcnt vmcnt(" #n ")" ::: "memory")
; #define PG8_WAIT_L(n) asm volatile("s_waitcnt lgkmcnt(" #n ")" ::: "memory")
; #define PG8_BAR __builtin_amdgcn_s_barrier()
; #define PG8_SCHED __builtin_amdgcn_sched_barrier(0)
; template <class Epi, class Sched, bool ALIGN_EPI = false, bool SP2 = false, bool F8 = false>
; __device__ __forceinline__ void gemm_phase(PG8_LAS unsigned char* lds, const int K, const Sched& S, const Epi& E, const int wave) {
;     ...
;             PG8_LDA(At, 1, 1); PG8_STAGE(PG8_SB(1, 0), b3, voffB); PG8_STAGE(PG8_SB(1, 1), b3 + hstep, voffB); PG8_STAGE(PG8_SA(1, 0), a3, voffA);
;             PG8_WAIT_V(8); PG8_WAIT_L(0); PG8_BAR; PG8_MMA(1, 0, At, B0); PG8_MMA(1, 1, At, B1); PG8_BAR; PG8_SCHED;
	s_setprio 0
	s_add_i32 s40, s42, s57
	v_lshl_add_u64 v[6:7], s[38:39], 0, v[142:143]
	s_mov_b32 m0, s40
	ds_read_b128 v[186:189], v168 offset:49152
	ds_read_b128 v[190:193], v168 offset:50176
	ds_read_b128 v[194:197], v168 offset:51200
	ds_read_b128 v[198:201], v168 offset:52224
	ds_read_b128 v[202:205], v168 offset:53248
	ds_read_b128 v[206:209], v168 offset:54272
	ds_read_b128 v[210:213], v168 offset:55296
	ds_read_b128 v[214:217], v168 offset:56320
	global_load_lds_dwordx4 v[6:7], off
	s_add_i32 m0, s40, 0x2000
	v_lshl_add_u64 v[6:7], s[38:39], 0, v[146:147]
	s_add_u32 s38, s38, 0x2b0000
	s_addc_u32 s39, s39, 0
	s_add_i32 s40, s43, s57
	global_load_lds_dwordx4 v[6:7], off
	v_lshl_add_u64 v[6:7], s[38:39], 0, v[142:143]
	s_mov_b32 m0, s40
	s_nop 0
	global_load_lds_dwordx4 v[6:7], off
	v_lshl_add_u64 v[6:7], s[38:39], 0, v[146:147]
	s_add_i32 m0, s40, 0x2000
	s_nop 0
	global_load_lds_dwordx4 v[6:7], off
	v_lshl_add_u64 v[6:7], s[8:9], 0, v[140:141]
	s_mov_b32 m0, s65
	s_nop 0
	global_load_lds_dwordx4 v[6:7], off
	v_lshl_add_u64 v[6:7], s[8:9], 0, v[144:145]
	s_mov_b32 m0, s66
	s_nop 0
	global_load_lds_dwordx4 v[6:7], off
	s_waitcnt vmcnt(8)
	s_waitcnt lgkmcnt(0)
	s_setprio 1
	s_barrier
	v_mfma_f32_16x16x32_bf16 v[64:67], v[132:135], v[186:189], v[64:67]
	v_mfma_f32_16x16x32_bf16 v[60:63], v[156:159], v[186:189], v[60:63]
	v_mfma_f32_16x16x32_bf16 v[56:59], v[132:135], v[194:197], v[56:59]
	v_mfma_f32_16x16x32_bf16 v[52:55], v[156:159], v[194:197], v[52:55]
	v_mfma_f32_16x16x32_bf16 v[48:51], v[132:135], v[202:205], v[48:51]
	v_mfma_f32_16x16x32_bf16 v[44:47], v[156:159], v[202:205], v[44:47]
	v_mfma_f32_16x16x32_bf16 v[40:43], v[132:135], v[210:213], v[40:43]
	v_mfma_f32_16x16x32_bf16 v[36:39], v[156:159], v[210:213], v[36:39]
	v_mfma_f32_16x16x32_bf16 v[64:67], v[136:139], v[190:193], v[64:67]
	v_mfma_f32_16x16x32_bf16 v[60:63], v[160:163], v[190:193], v[60:63]
	v_mfma_f32_16x16x32_bf16 v[56:59], v[136:139], v[198:201], v[56:59]
	v_mfma_f32_16x16x32_bf16 v[52:55], v[160:163], v[198:201], v[52:55]
	v_mfma_f32_16x16x32_bf16 v[48:51], v[136:139], v[206:209], v[48:51]
	v_mfma_f32_16x16x32_bf16 v[44:47], v[160:163], v[206:209], v[44:47]
	v_mfma_f32_16x16x32_bf16 v[40:43], v[136:139], v[214:217], v[40:43]
	v_mfma_f32_16x16x32_bf16 v[36:39], v[160:163], v[214:217], v[36:39]
	v_mfma_f32_16x16x32_bf16 v[32:35], v[170:173], v[186:189], v[32:35]
	v_mfma_f32_16x16x32_bf16 v[28:31], v[178:181], v[186:189], v[28:31]
	v_mfma_f32_16x16x32_bf16 v[24:27], v[170:173], v[194:197], v[24:27]
	v_mfma_f32_16x16x32_bf16 v[20:23], v[178:181], v[194:197], v[20:23]
	v_mfma_f32_16x16x32_bf16 v[16:19], v[170:173], v[202:205], v[16:19]
	v_mfma_f32_16x16x32_bf16 v[12:15], v[178:181], v[202:205], v[12:15]
	v_mfma_f32_16x16x32_bf16 v[6:9], v[170:173], v[210:213], v[8:11]
	v_mfma_f32_16x16x32_bf16 v[2:5], v[178:181], v[210:213], v[2:5]
	v_mfma_f32_16x16x32_bf16 v[32:35], v[174:177], v[190:193], v[32:35]
	v_mfma_f32_16x16x32_bf16 v[28:31], v[182:185], v[190:193], v[28:31]
	v_mfma_f32_16x16x32_bf16 v[24:27], v[174:177], v[198:201], v[24:27]
	v_mfma_f32_16x16x32_bf16 v[20:23], v[182:185], v[198:201], v[20:23]
	v_mfma_f32_16x16x32_bf16 v[16:19], v[174:177], v[206:209], v[16:19]
	v_mfma_f32_16x16x32_bf16 v[12:15], v[182:185], v[206:209], v[12:15]
	v_mfma_f32_16x16x32_bf16 v[8:11], v[174:177], v[214:217], v[6:9]
	v_mfma_f32_16x16x32_bf16 v[4:7], v[182:185], v[214:217], v[2:5]
	s_barrier
	s_setprio 0
	s_add_u32 s83, s83, 0x100
	s_addc_u32 s84, s84, 0
	s_add_u32 s85, s85, 0x100
	s_addc_u32 s86, s86, 0
	s_add_u32 s6, s6, 0x100
	s_addc_u32 s7, s7, 0
	s_cmp_ge_i32 s87, s56
	s_mov_b32 s8, s87
	s_cbranch_scc0 .LBB0_1348
